# v33 + GEMM K-loops: one static s_setprio 1 for waves 4-7 in front of each K-loop, dropped at loop exit
# speedup vs baseline: 1.0019x; 1.0019x over previous
; #define PG8_STAGE(bufoff, gbase, voff) do { _Pragma("unroll") for (int _i = 0; _i < 2; ++_i) \
;         __builtin_amdgcn_global_load_lds((const unsigned*)((const char*)(gbase) + (voff)[_i]), (PG8_LAS unsigned*)(lds + (bufoff) + ldsw + _i * 8192), 16, 0, 0); } while (0)
; #define PG8_LDA(dst, b, h) do { _Pragma("unroll") for (int m = 0; m < 4; ++m) _Pragma("unroll") for (int k = 0; k < 2; ++k) dst[m][k] = *(const PG8_LAS bf16x8*)(lds + PG8_SA(b, h) + aoff + m * 2048 + k * 1024); } while (0)
; #define PG8_LDB(dst, b, h) do { _Pragma("unroll") for (int n = 0; n < 2; ++n) _Pragma("unroll") for (int k = 0; k < 2; ++k) dst[n][k] = *(const PG8_LAS bf16x8*)(lds + PG8_SB(b, h) + boff + n * 2048 + k * 1024); } while (0)
; #define PG8_MMA(ai, bj, At, Bt) do { __builtin_amdgcn_s_setprio(1); _Pragma("unroll") for (int m = 0; m < 4; ++m) _Pragma("unroll") for (int n = 0; n < 2; ++n) _Pragma("unroll") for (int k = 0; k < 2; ++k) \
;         acc[ai][bj][m][n] = __builtin_amdgcn_mfma_f32_16x16x32_bf16(Bt[n][k], At[m][k], acc[ai][bj][m][n], 0, 0, 0); __builtin_amdgcn_s_setprio(0); } while (0)
; #define PG8_WAIT_V(n) asm volatile("s_waitcnt vmcnt(" #n ")" ::: "memory")
; #define PG8_WAIT_L(n) asm volatile("s_waitcnt lgkmcnt(" #n ")" ::: "memory")
; #define PG8_BAR __builtin_amdgcn_s_barrier()
; #define PG8_SCHED __builtin_amdgcn_sched_barrier(0)
; template <class Epi, class Sched, bool ALIGN_EPI = false, bool SP2 = false>
; __device__ __forceinline__ void gemm_phase(PG8_LAS unsigned char* lds, const Gemm g, const Sched& S, const Epi& E, int tid_in) {
;     ...
;             PG8_LDB(B0, 0, 0); PG8_LDB(B1, 0, 1); PG8_SCHED; PG8_LDA(At, 0, 0); PG8_STAGE(PG8_SA(1, 1), a1 + hstep, voffA);
;             PG8_WAIT_V(8); PG8_WAIT_L(0); PG8_BAR; PG8_MMA(0, 0, At, B0); PG8_MMA(0, 1, At, B1); PG8_BAR; PG8_SCHED;
;             PG8_LDA(At, 0, 1); PG8_STAGE(PG8_SB(0, 0), b2, voffB); PG8_STAGE(PG8_SB(0, 1), b2 + hstep, voffB); PG8_STAGE(PG8_SA(0, 0), a2, voffA);
;             PG8_WAIT_V(8); PG8_WAIT_L(0); PG8_BAR; PG8_MMA(1, 0, At, B0); PG8_MMA(1, 1, At, B1); PG8_BAR; PG8_SCHED;
.LBB0_375:
	s_ashr_i32 s17, s16, 31
	s_lshl_b64 s[18:19], s[16:17], 19
	s_add_u32 s18, s0, s18
	s_addc_u32 s19, s1, s19
	s_and_b64 s[20:21], s[2:3], exec
	s_cselect_b32 s17, s19, s25
	s_cselect_b32 s52, s18, s24
	s_ashr_i32 s15, s14, 31
	s_lshl_b64 s[20:21], s[14:15], 19
	s_add_u32 s20, s30, s20
	s_addc_u32 s21, s31, s21
	s_and_b64 s[28:29], s[2:3], exec
	s_cselect_b32 s15, s21, s27
	s_cselect_b32 s53, s20, s26
	s_add_u32 s24, s24, 0x40080
	s_addc_u32 s25, s25, 0
	s_add_u32 s54, s26, 0x100
	s_addc_u32 s55, s27, 0
	s_mov_b32 s56, -2
	s_add_u32 s26, s24, 0xfffc0080
	s_addc_u32 s27, s25, -1
	s_cmp_eq_u32 s56, 12
	s_cselect_b32 s29, s17, s27
	s_cselect_b32 s28, s52, s26
	s_cselect_b32 s27, s15, s55
	s_cselect_b32 s26, s53, s54
	s_add_i32 m0, s23, 0xc000
	ds_read_b128 v[150:153], v147
	global_load_lds_dwordx4 v136, s[24:25]
	s_add_i32 m0, s23, 0xe000
	ds_read_b128 v[154:157], v147 offset:1024
	global_load_lds_dwordx4 v138, s[24:25]
	ds_read_b128 v[158:161], v147 offset:2048
	ds_read_b128 v[162:165], v147 offset:3072
	ds_read_b128 v[166:169], v148
	ds_read_b128 v[170:173], v148 offset:1024
	ds_read_b128 v[174:177], v148 offset:2048
	ds_read_b128 v[178:181], v148 offset:3072
	ds_read_b128 v[182:185], v149
	ds_read_b128 v[186:189], v149 offset:1024
	ds_read_b128 v[190:193], v149 offset:2048
	ds_read_b128 v[194:197], v149 offset:3072
	ds_read_b128 v[198:201], v149 offset:4096
	ds_read_b128 v[202:205], v149 offset:5120
	ds_read_b128 v[206:209], v149 offset:6144
	ds_read_b128 v[210:213], v149 offset:7168
	s_waitcnt vmcnt(8)
	s_waitcnt lgkmcnt(0)
	s_barrier
	v_mfma_f32_16x16x32_bf16 v[124:127], v[150:153], v[182:185], 0
	v_mfma_f32_16x16x32_bf16 v[120:123], v[158:161], v[182:185], 0
	v_mfma_f32_16x16x32_bf16 v[108:111], v[150:153], v[190:193], 0
	v_mfma_f32_16x16x32_bf16 v[104:107], v[158:161], v[190:193], 0
	v_mfma_f32_16x16x32_bf16 v[92:95], v[150:153], v[198:201], 0
	v_mfma_f32_16x16x32_bf16 v[88:91], v[158:161], v[198:201], 0
	v_mfma_f32_16x16x32_bf16 v[76:79], v[150:153], v[206:209], 0
	v_mfma_f32_16x16x32_bf16 v[72:75], v[158:161], v[206:209], 0
	v_mfma_f32_16x16x32_bf16 v[124:127], v[154:157], v[186:189], v[124:127]
	v_mfma_f32_16x16x32_bf16 v[120:123], v[162:165], v[186:189], v[120:123]
	v_mfma_f32_16x16x32_bf16 v[108:111], v[154:157], v[194:197], v[108:111]
	v_mfma_f32_16x16x32_bf16 v[104:107], v[162:165], v[194:197], v[104:107]
	v_mfma_f32_16x16x32_bf16 v[92:95], v[154:157], v[202:205], v[92:95]
	v_mfma_f32_16x16x32_bf16 v[88:91], v[162:165], v[202:205], v[88:91]
	v_mfma_f32_16x16x32_bf16 v[76:79], v[154:157], v[210:213], v[76:79]
	v_mfma_f32_16x16x32_bf16 v[72:75], v[162:165], v[210:213], v[72:75]
	v_mfma_f32_16x16x32_bf16 v[116:119], v[166:169], v[182:185], 0
	v_mfma_f32_16x16x32_bf16 v[112:115], v[174:177], v[182:185], 0
	v_mfma_f32_16x16x32_bf16 v[100:103], v[166:169], v[190:193], 0
	v_mfma_f32_16x16x32_bf16 v[96:99], v[174:177], v[190:193], 0
	v_mfma_f32_16x16x32_bf16 v[84:87], v[166:169], v[198:201], 0
	v_mfma_f32_16x16x32_bf16 v[80:83], v[174:177], v[198:201], 0
	v_mfma_f32_16x16x32_bf16 v[68:71], v[166:169], v[206:209], 0
	v_mfma_f32_16x16x32_bf16 v[64:67], v[174:177], v[206:209], 0
	v_mfma_f32_16x16x32_bf16 v[116:119], v[170:173], v[186:189], v[116:119]
	v_mfma_f32_16x16x32_bf16 v[112:115], v[178:181], v[186:189], v[112:115]
	v_mfma_f32_16x16x32_bf16 v[100:103], v[170:173], v[194:197], v[100:103]
	v_mfma_f32_16x16x32_bf16 v[96:99], v[178:181], v[194:197], v[96:99]
	v_mfma_f32_16x16x32_bf16 v[84:87], v[170:173], v[202:205], v[84:87]
	v_mfma_f32_16x16x32_bf16 v[80:83], v[178:181], v[202:205], v[80:83]
	v_mfma_f32_16x16x32_bf16 v[68:71], v[170:173], v[210:213], v[68:71]
	v_mfma_f32_16x16x32_bf16 v[64:67], v[178:181], v[210:213], v[64:67]
	s_barrier
	s_add_u32 s98, s26, s10
	s_addc_u32 s99, s27, s11
	s_add_u32 s100, s28, s10
	s_addc_u32 s101, s29, s11
	s_add_i32 s57, s48, s34
	s_mov_b32 m0, s57
	ds_read_b128 v[182:185], v149 offset:16384
	global_load_lds_dwordx4 v132, s[26:27]
	s_add_i32 m0, s57, 0x2000
	s_add_u32 s60, s26, 0x40000
	s_addc_u32 s61, s27, 0
	s_add_i32 s57, s49, s34
	global_load_lds_dwordx4 v128, s[26:27]
	s_mov_b32 m0, s57
	ds_read_b128 v[186:189], v149 offset:17408
	global_load_lds_dwordx4 v132, s[60:61]
	s_add_i32 m0, s57, 0x2000
	ds_read_b128 v[190:193], v149 offset:18432
	global_load_lds_dwordx4 v128, s[60:61]
	s_mov_b32 m0, s23
	ds_read_b128 v[194:197], v149 offset:19456
	global_load_lds_dwordx4 v134, s[28:29]
	s_mov_b32 m0, s37
	ds_read_b128 v[198:201], v149 offset:20480
	global_load_lds_dwordx4 v130, s[28:29]
	ds_read_b128 v[202:205], v149 offset:21504
	ds_read_b128 v[206:209], v149 offset:22528
	ds_read_b128 v[210:213], v149 offset:23552
	s_waitcnt vmcnt(8)
	s_waitcnt lgkmcnt(0)
	s_barrier
; #define PG8_STAGE(bufoff, gbase, voff) do { _Pragma("unroll") for (int _i = 0; _i < 2; ++_i) \
;         __builtin_amdgcn_global_load_lds((const unsigned*)((const char*)(gbase) + (voff)[_i]), (PG8_LAS unsigned*)(lds + (bufoff) + ldsw + _i * 8192), 16, 0, 0); } while (0)
; #define PG8_LDA(dst, b, h) do { _Pragma("unroll") for (int m = 0; m < 4; ++m) _Pragma("unroll") for (int k = 0; k < 2; ++k) dst[m][k] = *(const PG8_LAS bf16x8*)(lds + PG8_SA(b, h) + aoff + m * 2048 + k * 1024); } while (0)
; #define PG8_LDB(dst, b, h) do { _Pragma("unroll") for (int n = 0; n < 2; ++n) _Pragma("unroll") for (int k = 0; k < 2; ++k) dst[n][k] = *(const PG8_LAS bf16x8*)(lds + PG8_SB(b, h) + boff + n * 2048 + k * 1024); } while (0)
; #define PG8_MMA(ai, bj, At, Bt) do { __builtin_amdgcn_s_setprio(1); _Pragma("unroll") for (int m = 0; m < 4; ++m) _Pragma("unroll") for (int n = 0; n < 2; ++n) _Pragma("unroll") for (int k = 0; k < 2; ++k) \
;         acc[ai][bj][m][n] = __builtin_amdgcn_mfma_f32_16x16x32_bf16(Bt[n][k], At[m][k], acc[ai][bj][m][n], 0, 0, 0); __builtin_amdgcn_s_setprio(0); } while (0)
; #define PG8_WAIT_V(n) asm volatile("s_waitcnt vmcnt(" #n ")" ::: "memory")
; #define PG8_WAIT_L(n) asm volatile("s_waitcnt lgkmcnt(" #n ")" ::: "memory")
; #define PG8_BAR __builtin_amdgcn_s_barrier()
; #define PG8_SCHED __builtin_amdgcn_sched_barrier(0)
; template <class Epi, class Sched, bool ALIGN_EPI = false, bool SP2 = false>
; __device__ __forceinline__ void gemm_phase(PG8_LAS unsigned char* lds, const Gemm g, const Sched& S, const Epi& E, int tid_in) {
;     ...
;             PG8_WAIT_V(8); PG8_WAIT_L(0); PG8_BAR; PG8_MMA(1, 0, At, B0); PG8_MMA(1, 1, At, B1); PG8_BAR; PG8_SCHED;
;             PG8_LDB(B0, 1, 0); PG8_LDB(B1, 1, 1); PG8_SCHED; PG8_LDA(At, 1, 0); PG8_STAGE(PG8_SA(0, 1), a2 + hstep, voffA);
;             PG8_WAIT_V(8); PG8_WAIT_L(0); PG8_BAR; PG8_MMA(0, 0, At, B0); PG8_MMA(0, 1, At, B1); PG8_BAR; PG8_SCHED;
	v_mfma_f32_16x16x32_bf16 v[60:63], v[150:153], v[182:185], 0
	v_mfma_f32_16x16x32_bf16 v[56:59], v[158:161], v[182:185], 0
	v_mfma_f32_16x16x32_bf16 v[44:47], v[150:153], v[190:193], 0
	v_mfma_f32_16x16x32_bf16 v[40:43], v[158:161], v[190:193], 0
	v_mfma_f32_16x16x32_bf16 v[28:31], v[150:153], v[198:201], 0
	v_mfma_f32_16x16x32_bf16 v[24:27], v[158:161], v[198:201], 0
	v_mfma_f32_16x16x32_bf16 v[12:15], v[150:153], v[206:209], 0
	v_mfma_f32_16x16x32_bf16 v[8:11], v[158:161], v[206:209], 0
	v_mfma_f32_16x16x32_bf16 v[60:63], v[154:157], v[186:189], v[60:63]
	v_mfma_f32_16x16x32_bf16 v[56:59], v[162:165], v[186:189], v[56:59]
	v_mfma_f32_16x16x32_bf16 v[44:47], v[154:157], v[194:197], v[44:47]
	v_mfma_f32_16x16x32_bf16 v[40:43], v[162:165], v[194:197], v[40:43]
	v_mfma_f32_16x16x32_bf16 v[28:31], v[154:157], v[202:205], v[28:31]
	v_mfma_f32_16x16x32_bf16 v[24:27], v[162:165], v[202:205], v[24:27]
	v_mfma_f32_16x16x32_bf16 v[12:15], v[154:157], v[210:213], v[12:15]
	v_mfma_f32_16x16x32_bf16 v[8:11], v[162:165], v[210:213], v[8:11]
	v_mfma_f32_16x16x32_bf16 v[52:55], v[166:169], v[182:185], 0
	v_mfma_f32_16x16x32_bf16 v[48:51], v[174:177], v[182:185], 0
	v_mfma_f32_16x16x32_bf16 v[36:39], v[166:169], v[190:193], 0
	v_mfma_f32_16x16x32_bf16 v[32:35], v[174:177], v[190:193], 0
	v_mfma_f32_16x16x32_bf16 v[20:23], v[166:169], v[198:201], 0
	v_mfma_f32_16x16x32_bf16 v[16:19], v[174:177], v[198:201], 0
	v_mfma_f32_16x16x32_bf16 v[4:7], v[166:169], v[206:209], 0
	v_mfma_f32_16x16x32_bf16 v[0:3], v[174:177], v[206:209], 0
	v_mfma_f32_16x16x32_bf16 v[52:55], v[170:173], v[186:189], v[52:55]
	v_mfma_f32_16x16x32_bf16 v[48:51], v[178:181], v[186:189], v[48:51]
	v_mfma_f32_16x16x32_bf16 v[36:39], v[170:173], v[194:197], v[36:39]
	v_mfma_f32_16x16x32_bf16 v[32:35], v[178:181], v[194:197], v[32:35]
	v_mfma_f32_16x16x32_bf16 v[20:23], v[170:173], v[202:205], v[20:23]
	v_mfma_f32_16x16x32_bf16 v[16:19], v[178:181], v[202:205], v[16:19]
	v_mfma_f32_16x16x32_bf16 v[4:7], v[170:173], v[210:213], v[4:7]
	v_mfma_f32_16x16x32_bf16 v[0:3], v[178:181], v[210:213], v[0:3]
	s_barrier
	s_add_i32 s57, 0, 0x18000
	s_add_i32 s59, 0, 0x1c000
	s_add_u32 s28, s28, 0x40000
	s_addc_u32 s29, s29, 0
	s_mov_b32 m0, s38
	s_nop 0
	global_load_lds_dwordx4 v134, s[28:29]
	s_mov_b32 m0, s39
	s_nop 0
	global_load_lds_dwordx4 v130, s[28:29]
	v_add_u32_e32 v162, s57, v145
	v_add_u32_e32 v178, s59, v145
	ds_read_b128 v[150:153], v162
	ds_read_b128 v[154:157], v162 offset:1024
	ds_read_b128 v[158:161], v162 offset:2048
	ds_read_b128 v[162:165], v162 offset:3072
	ds_read_b128 v[166:169], v178
	ds_read_b128 v[170:173], v178 offset:1024
	ds_read_b128 v[174:177], v178 offset:2048
	ds_read_b128 v[178:181], v178 offset:3072
	ds_read_b128 v[182:185], v149 offset:32768
	ds_read_b128 v[186:189], v149 offset:33792
	ds_read_b128 v[190:193], v149 offset:34816
	ds_read_b128 v[194:197], v149 offset:35840
	ds_read_b128 v[198:201], v149 offset:36864
	ds_read_b128 v[202:205], v149 offset:37888
	ds_read_b128 v[206:209], v149 offset:38912
	ds_read_b128 v[210:213], v149 offset:39936
	s_waitcnt vmcnt(8)
	s_waitcnt lgkmcnt(0)
	s_barrier
	v_mfma_f32_16x16x32_bf16 v[124:127], v[150:153], v[182:185], v[124:127]
	v_mfma_f32_16x16x32_bf16 v[120:123], v[158:161], v[182:185], v[120:123]
	v_mfma_f32_16x16x32_bf16 v[108:111], v[150:153], v[190:193], v[108:111]
	v_mfma_f32_16x16x32_bf16 v[104:107], v[158:161], v[190:193], v[104:107]
	v_mfma_f32_16x16x32_bf16 v[92:95], v[150:153], v[198:201], v[92:95]
	v_mfma_f32_16x16x32_bf16 v[88:91], v[158:161], v[198:201], v[88:91]
	v_mfma_f32_16x16x32_bf16 v[76:79], v[150:153], v[206:209], v[76:79]
	v_mfma_f32_16x16x32_bf16 v[72:75], v[158:161], v[206:209], v[72:75]
	v_mfma_f32_16x16x32_bf16 v[124:127], v[154:157], v[186:189], v[124:127]
	v_mfma_f32_16x16x32_bf16 v[120:123], v[162:165], v[186:189], v[120:123]
	v_mfma_f32_16x16x32_bf16 v[108:111], v[154:157], v[194:197], v[108:111]
	v_mfma_f32_16x16x32_bf16 v[104:107], v[162:165], v[194:197], v[104:107]
	v_mfma_f32_16x16x32_bf16 v[92:95], v[154:157], v[202:205], v[92:95]
	v_mfma_f32_16x16x32_bf16 v[88:91], v[162:165], v[202:205], v[88:91]
	v_mfma_f32_16x16x32_bf16 v[76:79], v[154:157], v[210:213], v[76:79]
	v_mfma_f32_16x16x32_bf16 v[72:75], v[162:165], v[210:213], v[72:75]
	v_mfma_f32_16x16x32_bf16 v[116:119], v[166:169], v[182:185], v[116:119]
	v_mfma_f32_16x16x32_bf16 v[112:115], v[174:177], v[182:185], v[112:115]
	v_mfma_f32_16x16x32_bf16 v[100:103], v[166:169], v[190:193], v[100:103]
	v_mfma_f32_16x16x32_bf16 v[96:99], v[174:177], v[190:193], v[96:99]
	v_mfma_f32_16x16x32_bf16 v[84:87], v[166:169], v[198:201], v[84:87]
	v_mfma_f32_16x16x32_bf16 v[80:83], v[174:177], v[198:201], v[80:83]
	v_mfma_f32_16x16x32_bf16 v[68:71], v[166:169], v[206:209], v[68:71]
	v_mfma_f32_16x16x32_bf16 v[64:67], v[174:177], v[206:209], v[64:67]
	v_mfma_f32_16x16x32_bf16 v[116:119], v[170:173], v[186:189], v[116:119]
	v_mfma_f32_16x16x32_bf16 v[112:115], v[178:181], v[186:189], v[112:115]
	v_mfma_f32_16x16x32_bf16 v[100:103], v[170:173], v[194:197], v[100:103]
	v_mfma_f32_16x16x32_bf16 v[96:99], v[178:181], v[194:197], v[96:99]
	v_mfma_f32_16x16x32_bf16 v[84:87], v[170:173], v[202:205], v[84:87]
	v_mfma_f32_16x16x32_bf16 v[80:83], v[178:181], v[202:205], v[80:83]
	v_mfma_f32_16x16x32_bf16 v[68:71], v[170:173], v[210:213], v[68:71]
	v_mfma_f32_16x16x32_bf16 v[64:67], v[178:181], v[210:213], v[64:67]
	s_barrier
; #define PG8_STAGE(bufoff, gbase, voff) do { _Pragma("unroll") for (int _i = 0; _i < 2; ++_i) \
;         __builtin_amdgcn_global_load_lds((const unsigned*)((const char*)(gbase) + (voff)[_i]), (PG8_LAS unsigned*)(lds + (bufoff) + ldsw + _i * 8192), 16, 0, 0); } while (0)
; #define PG8_LDA(dst, b, h) do { _Pragma("unroll") for (int m = 0; m < 4; ++m) _Pragma("unroll") for (int k = 0; k < 2; ++k) dst[m][k] = *(const PG8_LAS bf16x8*)(lds + PG8_SA(b, h) + aoff + m * 2048 + k * 1024); } while (0)
; #define PG8_LDB(dst, b, h) do { _Pragma("unroll") for (int n = 0; n < 2; ++n) _Pragma("unroll") for (int k = 0; k < 2; ++k) dst[n][k] = *(const PG8_LAS bf16x8*)(lds + PG8_SB(b, h) + boff + n * 2048 + k * 1024); } while (0)
; #define PG8_WAIT_V(n) asm volatile("s_waitcnt vmcnt(" #n ")" ::: "memory")
; #define PG8_WAIT_L(n) asm volatile("s_waitcnt lgkmcnt(" #n ")" ::: "memory")
; #define PG8_BAR __builtin_amdgcn_s_barrier()
; #define PG8_SCHED __builtin_amdgcn_sched_barrier(0)
; template <class Epi, class Sched, bool ALIGN_EPI = false, bool SP2 = false>
; __device__ __forceinline__ void gemm_phase(PG8_LAS unsigned char* lds, const Gemm g, const Sched& S, const Epi& E, int tid_in) {
;     ...
;         for (int t = 0; t < nt; t += 2) {
;             if constexpr (Epi::MIDK) { if (t == Epi::MIDK_T) { if (wr == 0) PG8_BAR; E.mid(acc, cur, wr, wc, fr, fq); if (wr == 1) PG8_BAR; } }
;             const bool last = (t == nt - 2);
;             const char* a1 = cA + (size_t)(t + 1) * kstep;
;             const char* a2 = last ? nA : cA + (size_t)(t + 2) * kstep; const char* b2 = last ? nB : cB + (size_t)(t + 2) * kstep;
;             const char* a3 = a2 + kstep; const char* b3 = b2 + kstep;
;             if (last && has_next) S.a_ready(nxt);
;             if constexpr (SP2) {
;             PG8_LDB(B0, 0, 0); PG8_LDB(B1, 0, 1); PG8_SCHED; PG8_LDA(At, 0, 0); PG8_STAGE(PG8_SA(1, 1), a1 + hstep, voffA);
;     ...
;             PG8_WAIT_V(8); PG8_WAIT_L(0); PG8_BAR; PG8_MMA(0, 0, At, B0); PG8_MMA(0, 1, At, B1); PG8_BAR; PG8_SCHED;
;             PG8_LDA(At, 1, 1); PG8_STAGE(PG8_SB(1, 0), b3, voffB); PG8_STAGE(PG8_SB(1, 1), b3 + hstep, voffB); PG8_STAGE(PG8_SA(1, 0), a3, voffA);
;             PG8_WAIT_V(8); PG8_WAIT_L(0); PG8_BAR; PG8_MMA(1, 0, At, B0); PG8_MMA(1, 1, At, B1); PG8_BAR; PG8_SCHED;
	s_add_i32 s28, s57, s34
	s_mov_b32 m0, s28
	ds_read_b128 v[182:185], v149 offset:49152
	global_load_lds_dwordx4 v132, s[98:99]
	s_add_i32 m0, s28, 0x2000
	s_add_u32 s26, s26, 0x40080
	s_addc_u32 s27, s27, 0
	s_add_i32 s28, s59, s34
	global_load_lds_dwordx4 v128, s[98:99]
	s_mov_b32 m0, s28
	ds_read_b128 v[186:189], v149 offset:50176
	global_load_lds_dwordx4 v132, s[26:27]
	s_add_i32 m0, s28, 0x2000
	ds_read_b128 v[190:193], v149 offset:51200
	global_load_lds_dwordx4 v128, s[26:27]
	s_mov_b32 m0, s44
	ds_read_b128 v[194:197], v149 offset:52224
	global_load_lds_dwordx4 v134, s[100:101]
	s_mov_b32 m0, s45
	ds_read_b128 v[198:201], v149 offset:53248
	global_load_lds_dwordx4 v130, s[100:101]
	ds_read_b128 v[202:205], v149 offset:54272
	ds_read_b128 v[206:209], v149 offset:55296
	ds_read_b128 v[210:213], v149 offset:56320
	s_waitcnt vmcnt(8)
	s_waitcnt lgkmcnt(0)
	s_barrier
	v_mfma_f32_16x16x32_bf16 v[60:63], v[150:153], v[182:185], v[60:63]
	v_mfma_f32_16x16x32_bf16 v[56:59], v[158:161], v[182:185], v[56:59]
	v_mfma_f32_16x16x32_bf16 v[44:47], v[150:153], v[190:193], v[44:47]
	v_mfma_f32_16x16x32_bf16 v[40:43], v[158:161], v[190:193], v[40:43]
	v_mfma_f32_16x16x32_bf16 v[28:31], v[150:153], v[198:201], v[28:31]
	v_mfma_f32_16x16x32_bf16 v[24:27], v[158:161], v[198:201], v[24:27]
	v_mfma_f32_16x16x32_bf16 v[12:15], v[150:153], v[206:209], v[12:15]
	v_mfma_f32_16x16x32_bf16 v[8:11], v[158:161], v[206:209], v[8:11]
	v_mfma_f32_16x16x32_bf16 v[60:63], v[154:157], v[186:189], v[60:63]
	v_mfma_f32_16x16x32_bf16 v[56:59], v[162:165], v[186:189], v[56:59]
	v_mfma_f32_16x16x32_bf16 v[44:47], v[154:157], v[194:197], v[44:47]
	v_mfma_f32_16x16x32_bf16 v[40:43], v[162:165], v[194:197], v[40:43]
	v_mfma_f32_16x16x32_bf16 v[28:31], v[154:157], v[202:205], v[28:31]
	v_mfma_f32_16x16x32_bf16 v[24:27], v[162:165], v[202:205], v[24:27]
	v_mfma_f32_16x16x32_bf16 v[12:15], v[154:157], v[210:213], v[12:15]
	v_mfma_f32_16x16x32_bf16 v[8:11], v[162:165], v[210:213], v[8:11]
	v_mfma_f32_16x16x32_bf16 v[52:55], v[166:169], v[182:185], v[52:55]
	v_mfma_f32_16x16x32_bf16 v[48:51], v[174:177], v[182:185], v[48:51]
	v_mfma_f32_16x16x32_bf16 v[36:39], v[166:169], v[190:193], v[36:39]
	v_mfma_f32_16x16x32_bf16 v[32:35], v[174:177], v[190:193], v[32:35]
	v_mfma_f32_16x16x32_bf16 v[20:23], v[166:169], v[198:201], v[20:23]
	v_mfma_f32_16x16x32_bf16 v[16:19], v[174:177], v[198:201], v[16:19]
	v_mfma_f32_16x16x32_bf16 v[4:7], v[166:169], v[206:209], v[4:7]
	v_mfma_f32_16x16x32_bf16 v[0:3], v[174:177], v[206:209], v[0:3]
	v_mfma_f32_16x16x32_bf16 v[52:55], v[170:173], v[186:189], v[52:55]
	v_mfma_f32_16x16x32_bf16 v[48:51], v[178:181], v[186:189], v[48:51]
	v_mfma_f32_16x16x32_bf16 v[36:39], v[170:173], v[194:197], v[36:39]
	v_mfma_f32_16x16x32_bf16 v[32:35], v[178:181], v[194:197], v[32:35]
	v_mfma_f32_16x16x32_bf16 v[20:23], v[170:173], v[202:205], v[20:23]
	v_mfma_f32_16x16x32_bf16 v[16:19], v[178:181], v[202:205], v[16:19]
	v_mfma_f32_16x16x32_bf16 v[4:7], v[170:173], v[210:213], v[4:7]
	v_mfma_f32_16x16x32_bf16 v[0:3], v[178:181], v[210:213], v[0:3]
	s_barrier
	s_add_i32 s56, s56, 2
	s_add_u32 s24, s24, 0x100
	s_addc_u32 s25, s25, 0
	s_add_u32 s54, s54, 0x100
	s_addc_u32 s55, s55, 0
	v_readlane_b32 s98, v248, 0
	s_nop 3
	s_cmp_ge_u32 s98, 0x100
	s_cbranch_scc0 .Lgprio_skip_0
	s_setprio 1
.Lgprio_skip_0:
.LBB0_376:
	s_add_u32 s26, s24, 0xfffc0080
	s_addc_u32 s27, s25, -1
	s_cmp_eq_u32 s56, 12
	s_cselect_b32 s29, s17, s27
	s_cselect_b32 s28, s52, s26
	s_cselect_b32 s27, s15, s55
	s_cselect_b32 s26, s53, s54
	s_add_i32 m0, s23, 0xc000
	ds_read_b128 v[150:153], v147
	global_load_lds_dwordx4 v136, s[24:25]
	s_add_i32 m0, s23, 0xe000
	ds_read_b128 v[154:157], v147 offset:1024
	global_load_lds_dwordx4 v138, s[24:25]
	ds_read_b128 v[158:161], v147 offset:2048
	ds_read_b128 v[162:165], v147 offset:3072
	ds_read_b128 v[166:169], v148
	ds_read_b128 v[170:173], v148 offset:1024
	ds_read_b128 v[174:177], v148 offset:2048
	ds_read_b128 v[178:181], v148 offset:3072
	ds_read_b128 v[182:185], v149
	ds_read_b128 v[186:189], v149 offset:1024
	ds_read_b128 v[190:193], v149 offset:2048
	ds_read_b128 v[194:197], v149 offset:3072
	ds_read_b128 v[198:201], v149 offset:4096
	ds_read_b128 v[202:205], v149 offset:5120
	ds_read_b128 v[206:209], v149 offset:6144
	ds_read_b128 v[210:213], v149 offset:7168
	s_waitcnt vmcnt(8)
	s_waitcnt lgkmcnt(0)
	s_barrier
	v_mfma_f32_16x16x32_bf16 v[124:127], v[150:153], v[182:185], v[124:127]
	v_mfma_f32_16x16x32_bf16 v[120:123], v[158:161], v[182:185], v[120:123]
	v_mfma_f32_16x16x32_bf16 v[108:111], v[150:153], v[190:193], v[108:111]
	v_mfma_f32_16x16x32_bf16 v[104:107], v[158:161], v[190:193], v[104:107]
	v_mfma_f32_16x16x32_bf16 v[92:95], v[150:153], v[198:201], v[92:95]
	v_mfma_f32_16x16x32_bf16 v[88:91], v[158:161], v[198:201], v[88:91]
	v_mfma_f32_16x16x32_bf16 v[76:79], v[150:153], v[206:209], v[76:79]
	v_mfma_f32_16x16x32_bf16 v[72:75], v[158:161], v[206:209], v[72:75]
	v_mfma_f32_16x16x32_bf16 v[124:127], v[154:157], v[186:189], v[124:127]
	v_mfma_f32_16x16x32_bf16 v[120:123], v[162:165], v[186:189], v[120:123]
	v_mfma_f32_16x16x32_bf16 v[108:111], v[154:157], v[194:197], v[108:111]
	v_mfma_f32_16x16x32_bf16 v[104:107], v[162:165], v[194:197], v[104:107]
	v_mfma_f32_16x16x32_bf16 v[92:95], v[154:157], v[202:205], v[92:95]
	v_mfma_f32_16x16x32_bf16 v[88:91], v[162:165], v[202:205], v[88:91]
	v_mfma_f32_16x16x32_bf16 v[76:79], v[154:157], v[210:213], v[76:79]
	v_mfma_f32_16x16x32_bf16 v[72:75], v[162:165], v[210:213], v[72:75]
	v_mfma_f32_16x16x32_bf16 v[116:119], v[166:169], v[182:185], v[116:119]
	v_mfma_f32_16x16x32_bf16 v[112:115], v[174:177], v[182:185], v[112:115]
	v_mfma_f32_16x16x32_bf16 v[100:103], v[166:169], v[190:193], v[100:103]
	v_mfma_f32_16x16x32_bf16 v[96:99], v[174:177], v[190:193], v[96:99]
	v_mfma_f32_16x16x32_bf16 v[84:87], v[166:169], v[198:201], v[84:87]
	v_mfma_f32_16x16x32_bf16 v[80:83], v[174:177], v[198:201], v[80:83]
	v_mfma_f32_16x16x32_bf16 v[68:71], v[166:169], v[206:209], v[68:71]
	v_mfma_f32_16x16x32_bf16 v[64:67], v[174:177], v[206:209], v[64:67]
	v_mfma_f32_16x16x32_bf16 v[116:119], v[170:173], v[186:189], v[116:119]
	v_mfma_f32_16x16x32_bf16 v[112:115], v[178:181], v[186:189], v[112:115]
	v_mfma_f32_16x16x32_bf16 v[100:103], v[170:173], v[194:197], v[100:103]
	v_mfma_f32_16x16x32_bf16 v[96:99], v[178:181], v[194:197], v[96:99]
	v_mfma_f32_16x16x32_bf16 v[84:87], v[170:173], v[202:205], v[84:87]
	v_mfma_f32_16x16x32_bf16 v[80:83], v[178:181], v[202:205], v[80:83]
	v_mfma_f32_16x16x32_bf16 v[68:71], v[170:173], v[210:213], v[68:71]
	v_mfma_f32_16x16x32_bf16 v[64:67], v[178:181], v[210:213], v[64:67]
	s_barrier
; #define PG8_STAGE(bufoff, gbase, voff) do { _Pragma("unroll") for (int _i = 0; _i < 2; ++_i) \
;         __builtin_amdgcn_global_load_lds((const unsigned*)((const char*)(gbase) + (voff)[_i]), (PG8_LAS unsigned*)(lds + (bufoff) + ldsw + _i * 8192), 16, 0, 0); } while (0)
; #define PG8_LDA(dst, b, h) do { _Pragma("unroll") for (int m = 0; m < 4; ++m) _Pragma("unroll") for (int k = 0; k < 2; ++k) dst[m][k] = *(const PG8_LAS bf16x8*)(lds + PG8_SA(b, h) + aoff + m * 2048 + k * 1024); } while (0)
; #define PG8_LDB(dst, b, h) do { _Pragma("unroll") for (int n = 0; n < 2; ++n) _Pragma("unroll") for (int k = 0; k < 2; ++k) dst[n][k] = *(const PG8_LAS bf16x8*)(lds + PG8_SB(b, h) + boff + n * 2048 + k * 1024); } while (0)
; #define PG8_MMA(ai, bj, At, Bt) do { __builtin_amdgcn_s_setprio(1); _Pragma("unroll") for (int m = 0; m < 4; ++m) _Pragma("unroll") for (int n = 0; n < 2; ++n) _Pragma("unroll") for (int k = 0; k < 2; ++k) \
;         acc[ai][bj][m][n] = __builtin_amdgcn_mfma_f32_16x16x32_bf16(Bt[n][k], At[m][k], acc[ai][bj][m][n], 0, 0, 0); __builtin_amdgcn_s_setprio(0); } while (0)
; #define PG8_WAIT_V(n) asm volatile("s_waitcnt vmcnt(" #n ")" ::: "memory")
; #define PG8_WAIT_L(n) asm volatile("s_waitcnt lgkmcnt(" #n ")" ::: "memory")
; #define PG8_BAR __builtin_amdgcn_s_barrier()
; #define PG8_SCHED __builtin_amdgcn_sched_barrier(0)
; template <class Epi, class Sched, bool ALIGN_EPI = false, bool SP2 = false>
; __device__ __forceinline__ void gemm_phase(PG8_LAS unsigned char* lds, const Gemm g, const Sched& S, const Epi& E, int tid_in) {
;     ...
;             PG8_LDB(B0, 0, 0); PG8_LDB(B1, 0, 1); PG8_SCHED; PG8_LDA(At, 0, 0); PG8_STAGE(PG8_SA(1, 1), a1 + hstep, voffA);
;             PG8_WAIT_V(8); PG8_WAIT_L(0); PG8_BAR; PG8_MMA(0, 0, At, B0); PG8_MMA(0, 1, At, B1); PG8_BAR; PG8_SCHED;
;             PG8_LDA(At, 0, 1); PG8_STAGE(PG8_SB(0, 0), b2, voffB); PG8_STAGE(PG8_SB(0, 1), b2 + hstep, voffB); PG8_STAGE(PG8_SA(0, 0), a2, voffA);
;             PG8_WAIT_V(8); PG8_WAIT_L(0); PG8_BAR; PG8_MMA(1, 0, At, B0); PG8_MMA(1, 1, At, B1); PG8_BAR; PG8_SCHED;
;             PG8_LDB(B0, 1, 0); PG8_LDB(B1, 1, 1); PG8_SCHED; PG8_LDA(At, 1, 0); PG8_STAGE(PG8_SA(0, 1), a2 + hstep, voffA);
	s_add_u32 s98, s26, s10
	s_addc_u32 s99, s27, s11
	s_add_u32 s100, s28, s10
	s_addc_u32 s101, s29, s11
	s_add_i32 s57, s48, s34
	s_mov_b32 m0, s57
	ds_read_b128 v[182:185], v149 offset:16384
	global_load_lds_dwordx4 v132, s[26:27]
	s_add_i32 m0, s57, 0x2000
	s_add_u32 s60, s26, 0x40000
	s_addc_u32 s61, s27, 0
	s_add_i32 s57, s49, s34
	global_load_lds_dwordx4 v128, s[26:27]
	s_mov_b32 m0, s57
	ds_read_b128 v[186:189], v149 offset:17408
	global_load_lds_dwordx4 v132, s[60:61]
	s_add_i32 m0, s57, 0x2000
	ds_read_b128 v[190:193], v149 offset:18432
	global_load_lds_dwordx4 v128, s[60:61]
	s_mov_b32 m0, s23
	ds_read_b128 v[194:197], v149 offset:19456
	global_load_lds_dwordx4 v134, s[28:29]
	s_mov_b32 m0, s37
	ds_read_b128 v[198:201], v149 offset:20480
	global_load_lds_dwordx4 v130, s[28:29]
	ds_read_b128 v[202:205], v149 offset:21504
	ds_read_b128 v[206:209], v149 offset:22528
	ds_read_b128 v[210:213], v149 offset:23552
	s_waitcnt vmcnt(8)
	s_waitcnt lgkmcnt(0)
	s_barrier
	v_mfma_f32_16x16x32_bf16 v[60:63], v[150:153], v[182:185], v[60:63]
	v_mfma_f32_16x16x32_bf16 v[56:59], v[158:161], v[182:185], v[56:59]
	v_mfma_f32_16x16x32_bf16 v[44:47], v[150:153], v[190:193], v[44:47]
	v_mfma_f32_16x16x32_bf16 v[40:43], v[158:161], v[190:193], v[40:43]
	v_mfma_f32_16x16x32_bf16 v[28:31], v[150:153], v[198:201], v[28:31]
	v_mfma_f32_16x16x32_bf16 v[24:27], v[158:161], v[198:201], v[24:27]
	v_mfma_f32_16x16x32_bf16 v[12:15], v[150:153], v[206:209], v[12:15]
	v_mfma_f32_16x16x32_bf16 v[8:11], v[158:161], v[206:209], v[8:11]
	v_mfma_f32_16x16x32_bf16 v[60:63], v[154:157], v[186:189], v[60:63]
	v_mfma_f32_16x16x32_bf16 v[56:59], v[162:165], v[186:189], v[56:59]
	v_mfma_f32_16x16x32_bf16 v[44:47], v[154:157], v[194:197], v[44:47]
	v_mfma_f32_16x16x32_bf16 v[40:43], v[162:165], v[194:197], v[40:43]
	v_mfma_f32_16x16x32_bf16 v[28:31], v[154:157], v[202:205], v[28:31]
	v_mfma_f32_16x16x32_bf16 v[24:27], v[162:165], v[202:205], v[24:27]
	v_mfma_f32_16x16x32_bf16 v[12:15], v[154:157], v[210:213], v[12:15]
	v_mfma_f32_16x16x32_bf16 v[8:11], v[162:165], v[210:213], v[8:11]
	v_mfma_f32_16x16x32_bf16 v[52:55], v[166:169], v[182:185], v[52:55]
	v_mfma_f32_16x16x32_bf16 v[48:51], v[174:177], v[182:185], v[48:51]
	v_mfma_f32_16x16x32_bf16 v[36:39], v[166:169], v[190:193], v[36:39]
	v_mfma_f32_16x16x32_bf16 v[32:35], v[174:177], v[190:193], v[32:35]
	v_mfma_f32_16x16x32_bf16 v[20:23], v[166:169], v[198:201], v[20:23]
	v_mfma_f32_16x16x32_bf16 v[16:19], v[174:177], v[198:201], v[16:19]
	v_mfma_f32_16x16x32_bf16 v[4:7], v[166:169], v[206:209], v[4:7]
	v_mfma_f32_16x16x32_bf16 v[0:3], v[174:177], v[206:209], v[0:3]
	v_mfma_f32_16x16x32_bf16 v[52:55], v[170:173], v[186:189], v[52:55]
	v_mfma_f32_16x16x32_bf16 v[48:51], v[178:181], v[186:189], v[48:51]
	v_mfma_f32_16x16x32_bf16 v[36:39], v[170:173], v[194:197], v[36:39]
	v_mfma_f32_16x16x32_bf16 v[32:35], v[178:181], v[194:197], v[32:35]
	v_mfma_f32_16x16x32_bf16 v[20:23], v[170:173], v[202:205], v[20:23]
	v_mfma_f32_16x16x32_bf16 v[16:19], v[178:181], v[202:205], v[16:19]
	v_mfma_f32_16x16x32_bf16 v[4:7], v[170:173], v[210:213], v[4:7]
	v_mfma_f32_16x16x32_bf16 v[0:3], v[178:181], v[210:213], v[0:3]
	s_barrier
	s_add_i32 s57, 0, 0x18000
	s_add_i32 s59, 0, 0x1c000
	s_add_u32 s28, s28, 0x40000
	s_addc_u32 s29, s29, 0
	s_mov_b32 m0, s38
	s_nop 0
	global_load_lds_dwordx4 v134, s[28:29]
	s_mov_b32 m0, s39
	s_nop 0
	global_load_lds_dwordx4 v130, s[28:29]
	v_add_u32_e32 v162, s57, v145
	v_add_u32_e32 v178, s59, v145
	ds_read_b128 v[150:153], v162
	ds_read_b128 v[154:157], v162 offset:1024
	ds_read_b128 v[158:161], v162 offset:2048
	ds_read_b128 v[162:165], v162 offset:3072
	ds_read_b128 v[166:169], v178
	ds_read_b128 v[170:173], v178 offset:1024
	ds_read_b128 v[174:177], v178 offset:2048
	ds_read_b128 v[178:181], v178 offset:3072
	ds_read_b128 v[182:185], v149 offset:32768
	ds_read_b128 v[186:189], v149 offset:33792
	ds_read_b128 v[190:193], v149 offset:34816
	ds_read_b128 v[194:197], v149 offset:35840
	ds_read_b128 v[198:201], v149 offset:36864
	ds_read_b128 v[202:205], v149 offset:37888
	ds_read_b128 v[206:209], v149 offset:38912
	ds_read_b128 v[210:213], v149 offset:39936
	s_waitcnt vmcnt(8)
	s_waitcnt lgkmcnt(0)
	s_barrier
; #define PG8_STAGE(bufoff, gbase, voff) do { _Pragma("unroll") for (int _i = 0; _i < 2; ++_i) \
;         __builtin_amdgcn_global_load_lds((const unsigned*)((const char*)(gbase) + (voff)[_i]), (PG8_LAS unsigned*)(lds + (bufoff) + ldsw + _i * 8192), 16, 0, 0); } while (0)
; #define PG8_LDA(dst, b, h) do { _Pragma("unroll") for (int m = 0; m < 4; ++m) _Pragma("unroll") for (int k = 0; k < 2; ++k) dst[m][k] = *(const PG8_LAS bf16x8*)(lds + PG8_SA(b, h) + aoff + m * 2048 + k * 1024); } while (0)
; #define PG8_MMA(ai, bj, At, Bt) do { __builtin_amdgcn_s_setprio(1); _Pragma("unroll") for (int m = 0; m < 4; ++m) _Pragma("unroll") for (int n = 0; n < 2; ++n) _Pragma("unroll") for (int k = 0; k < 2; ++k) \
;         acc[ai][bj][m][n] = __builtin_amdgcn_mfma_f32_16x16x32_bf16(Bt[n][k], At[m][k], acc[ai][bj][m][n], 0, 0, 0); __builtin_amdgcn_s_setprio(0); } while (0)
; #define PG8_WAIT_V(n) asm volatile("s_waitcnt vmcnt(" #n ")" ::: "memory")
; #define PG8_WAIT_L(n) asm volatile("s_waitcnt lgkmcnt(" #n ")" ::: "memory")
; #define PG8_BAR __builtin_amdgcn_s_barrier()
; #define PG8_SCHED __builtin_amdgcn_sched_barrier(0)
; template <class Epi, class Sched, bool ALIGN_EPI = false, bool SP2 = false>
; __device__ __forceinline__ void gemm_phase(PG8_LAS unsigned char* lds, const Gemm g, const Sched& S, const Epi& E, int tid_in) {
;     ...
;             PG8_WAIT_V(8); PG8_WAIT_L(0); PG8_BAR; PG8_MMA(0, 0, At, B0); PG8_MMA(0, 1, At, B1); PG8_BAR; PG8_SCHED;
;             PG8_LDA(At, 1, 1); PG8_STAGE(PG8_SB(1, 0), b3, voffB); PG8_STAGE(PG8_SB(1, 1), b3 + hstep, voffB); PG8_STAGE(PG8_SA(1, 0), a3, voffA);
;             PG8_WAIT_V(8); PG8_WAIT_L(0); PG8_BAR; PG8_MMA(1, 0, At, B0); PG8_MMA(1, 1, At, B1); PG8_BAR; PG8_SCHED;
;     ...
;         if constexpr (ALIGN_EPI) { if (wr == 0) PG8_BAR; }
	v_mfma_f32_16x16x32_bf16 v[124:127], v[150:153], v[182:185], v[124:127]
	v_mfma_f32_16x16x32_bf16 v[120:123], v[158:161], v[182:185], v[120:123]
	v_mfma_f32_16x16x32_bf16 v[108:111], v[150:153], v[190:193], v[108:111]
	v_mfma_f32_16x16x32_bf16 v[104:107], v[158:161], v[190:193], v[104:107]
	v_mfma_f32_16x16x32_bf16 v[92:95], v[150:153], v[198:201], v[92:95]
	v_mfma_f32_16x16x32_bf16 v[88:91], v[158:161], v[198:201], v[88:91]
	v_mfma_f32_16x16x32_bf16 v[76:79], v[150:153], v[206:209], v[76:79]
	v_mfma_f32_16x16x32_bf16 v[72:75], v[158:161], v[206:209], v[72:75]
	v_mfma_f32_16x16x32_bf16 v[124:127], v[154:157], v[186:189], v[124:127]
	v_mfma_f32_16x16x32_bf16 v[120:123], v[162:165], v[186:189], v[120:123]
	v_mfma_f32_16x16x32_bf16 v[108:111], v[154:157], v[194:197], v[108:111]
	v_mfma_f32_16x16x32_bf16 v[104:107], v[162:165], v[194:197], v[104:107]
	v_mfma_f32_16x16x32_bf16 v[92:95], v[154:157], v[202:205], v[92:95]
	v_mfma_f32_16x16x32_bf16 v[88:91], v[162:165], v[202:205], v[88:91]
	v_mfma_f32_16x16x32_bf16 v[76:79], v[154:157], v[210:213], v[76:79]
	v_mfma_f32_16x16x32_bf16 v[72:75], v[162:165], v[210:213], v[72:75]
	v_mfma_f32_16x16x32_bf16 v[116:119], v[166:169], v[182:185], v[116:119]
	v_mfma_f32_16x16x32_bf16 v[112:115], v[174:177], v[182:185], v[112:115]
	v_mfma_f32_16x16x32_bf16 v[100:103], v[166:169], v[190:193], v[100:103]
	v_mfma_f32_16x16x32_bf16 v[96:99], v[174:177], v[190:193], v[96:99]
	v_mfma_f32_16x16x32_bf16 v[84:87], v[166:169], v[198:201], v[84:87]
	v_mfma_f32_16x16x32_bf16 v[80:83], v[174:177], v[198:201], v[80:83]
	v_mfma_f32_16x16x32_bf16 v[68:71], v[166:169], v[206:209], v[68:71]
	v_mfma_f32_16x16x32_bf16 v[64:67], v[174:177], v[206:209], v[64:67]
	v_mfma_f32_16x16x32_bf16 v[116:119], v[170:173], v[186:189], v[116:119]
	v_mfma_f32_16x16x32_bf16 v[112:115], v[178:181], v[186:189], v[112:115]
	v_mfma_f32_16x16x32_bf16 v[100:103], v[170:173], v[194:197], v[100:103]
	v_mfma_f32_16x16x32_bf16 v[96:99], v[178:181], v[194:197], v[96:99]
	v_mfma_f32_16x16x32_bf16 v[84:87], v[170:173], v[202:205], v[84:87]
	v_mfma_f32_16x16x32_bf16 v[80:83], v[178:181], v[202:205], v[80:83]
	v_mfma_f32_16x16x32_bf16 v[68:71], v[170:173], v[210:213], v[68:71]
	v_mfma_f32_16x16x32_bf16 v[64:67], v[178:181], v[210:213], v[64:67]
	s_barrier
	s_add_i32 s28, s57, s34
	s_mov_b32 m0, s28
	ds_read_b128 v[182:185], v149 offset:49152
	global_load_lds_dwordx4 v132, s[98:99]
	s_add_i32 m0, s28, 0x2000
	s_add_u32 s26, s26, 0x40080
	s_addc_u32 s27, s27, 0
	s_add_i32 s28, s59, s34
	global_load_lds_dwordx4 v128, s[98:99]
	s_mov_b32 m0, s28
	ds_read_b128 v[186:189], v149 offset:50176
	global_load_lds_dwordx4 v132, s[26:27]
	s_add_i32 m0, s28, 0x2000
	ds_read_b128 v[190:193], v149 offset:51200
	global_load_lds_dwordx4 v128, s[26:27]
	s_mov_b32 m0, s44
	ds_read_b128 v[194:197], v149 offset:52224
	global_load_lds_dwordx4 v134, s[100:101]
	s_mov_b32 m0, s45
	ds_read_b128 v[198:201], v149 offset:53248
	global_load_lds_dwordx4 v130, s[100:101]
	ds_read_b128 v[202:205], v149 offset:54272
	ds_read_b128 v[206:209], v149 offset:55296
	ds_read_b128 v[210:213], v149 offset:56320
	s_waitcnt vmcnt(8)
	s_waitcnt lgkmcnt(0)
	s_barrier
	v_mfma_f32_16x16x32_bf16 v[60:63], v[150:153], v[182:185], v[60:63]
	v_mfma_f32_16x16x32_bf16 v[56:59], v[158:161], v[182:185], v[56:59]
	v_mfma_f32_16x16x32_bf16 v[44:47], v[150:153], v[190:193], v[44:47]
	v_mfma_f32_16x16x32_bf16 v[40:43], v[158:161], v[190:193], v[40:43]
	v_mfma_f32_16x16x32_bf16 v[28:31], v[150:153], v[198:201], v[28:31]
	v_mfma_f32_16x16x32_bf16 v[24:27], v[158:161], v[198:201], v[24:27]
	v_mfma_f32_16x16x32_bf16 v[12:15], v[150:153], v[206:209], v[12:15]
	v_mfma_f32_16x16x32_bf16 v[8:11], v[158:161], v[206:209], v[8:11]
	v_mfma_f32_16x16x32_bf16 v[60:63], v[154:157], v[186:189], v[60:63]
	v_mfma_f32_16x16x32_bf16 v[56:59], v[162:165], v[186:189], v[56:59]
	v_mfma_f32_16x16x32_bf16 v[44:47], v[154:157], v[194:197], v[44:47]
	v_mfma_f32_16x16x32_bf16 v[40:43], v[162:165], v[194:197], v[40:43]
	v_mfma_f32_16x16x32_bf16 v[28:31], v[154:157], v[202:205], v[28:31]
	v_mfma_f32_16x16x32_bf16 v[24:27], v[162:165], v[202:205], v[24:27]
	v_mfma_f32_16x16x32_bf16 v[12:15], v[154:157], v[210:213], v[12:15]
	v_mfma_f32_16x16x32_bf16 v[8:11], v[162:165], v[210:213], v[8:11]
	v_mfma_f32_16x16x32_bf16 v[52:55], v[166:169], v[182:185], v[52:55]
	v_mfma_f32_16x16x32_bf16 v[48:51], v[174:177], v[182:185], v[48:51]
	v_mfma_f32_16x16x32_bf16 v[36:39], v[166:169], v[190:193], v[36:39]
	v_mfma_f32_16x16x32_bf16 v[32:35], v[174:177], v[190:193], v[32:35]
	v_mfma_f32_16x16x32_bf16 v[20:23], v[166:169], v[198:201], v[20:23]
	v_mfma_f32_16x16x32_bf16 v[16:19], v[174:177], v[198:201], v[16:19]
	v_mfma_f32_16x16x32_bf16 v[4:7], v[166:169], v[206:209], v[4:7]
	v_mfma_f32_16x16x32_bf16 v[0:3], v[174:177], v[206:209], v[0:3]
	v_mfma_f32_16x16x32_bf16 v[52:55], v[170:173], v[186:189], v[52:55]
	v_mfma_f32_16x16x32_bf16 v[48:51], v[178:181], v[186:189], v[48:51]
	v_mfma_f32_16x16x32_bf16 v[36:39], v[170:173], v[194:197], v[36:39]
	v_mfma_f32_16x16x32_bf16 v[32:35], v[178:181], v[194:197], v[32:35]
	v_mfma_f32_16x16x32_bf16 v[20:23], v[170:173], v[202:205], v[20:23]
	v_mfma_f32_16x16x32_bf16 v[16:19], v[178:181], v[202:205], v[16:19]
	v_mfma_f32_16x16x32_bf16 v[4:7], v[170:173], v[210:213], v[4:7]
	v_mfma_f32_16x16x32_bf16 v[0:3], v[178:181], v[210:213], v[0:3]
	s_barrier
	s_add_i32 s56, s56, 2
	s_add_u32 s24, s24, 0x100
	s_addc_u32 s25, s25, 0
	s_add_u32 s54, s54, 0x100
	s_addc_u32 s55, s55, 0
	s_cmp_gt_u32 s56, 13
	s_cbranch_scc0 .LBB0_376
	s_setprio 0
	s_and_b64 vcc, exec, s[12:13]
	s_cbranch_vccz .LBB0_379
	s_barrier

; #define PG8_STAGE(bufoff, gbase, voff) do { _Pragma("unroll") for (int _i = 0; _i < 2; ++_i) \
;         __builtin_amdgcn_global_load_lds((const unsigned*)((const char*)(gbase) + (voff)[_i]), (PG8_LAS unsigned*)(lds + (bufoff) + ldsw + _i * 8192), 16, 0, 0); } while (0)
; #define PG8_LDA(dst, b, h) do { _Pragma("unroll") for (int m = 0; m < 4; ++m) _Pragma("unroll") for (int k = 0; k < 2; ++k) dst[m][k] = *(const PG8_LAS bf16x8*)(lds + PG8_SA(b, h) + aoff + m * 2048 + k * 1024); } while (0)
; #define PG8_LDB(dst, b, h) do { _Pragma("unroll") for (int n = 0; n < 2; ++n) _Pragma("unroll") for (int k = 0; k < 2; ++k) dst[n][k] = *(const PG8_LAS bf16x8*)(lds + PG8_SB(b, h) + boff + n * 2048 + k * 1024); } while (0)
; #define PG8_MMA(ai, bj, At, Bt) do { __builtin_amdgcn_s_setprio(1); _Pragma("unroll") for (int m = 0; m < 4; ++m) _Pragma("unroll") for (int n = 0; n < 2; ++n) _Pragma("unroll") for (int k = 0; k < 2; ++k) \
;         acc[ai][bj][m][n] = __builtin_amdgcn_mfma_f32_16x16x32_bf16(Bt[n][k], At[m][k], acc[ai][bj][m][n], 0, 0, 0); __builtin_amdgcn_s_setprio(0); } while (0)
; #define PG8_WAIT_V(n) asm volatile("s_waitcnt vmcnt(" #n ")" ::: "memory")
; #define PG8_WAIT_L(n) asm volatile("s_waitcnt lgkmcnt(" #n ")" ::: "memory")
; #define PG8_BAR __builtin_amdgcn_s_barrier()
; #define PG8_SCHED __builtin_amdgcn_sched_barrier(0)
; template <class Epi, class Sched, bool ALIGN_EPI = false, bool SP2 = false>
; __device__ __forceinline__ void gemm_phase(PG8_LAS unsigned char* lds, const Gemm g, const Sched& S, const Epi& E, int tid_in) {
;     ...
;             PG8_LDB(B0, 0, 0); PG8_LDB(B1, 0, 1); PG8_SCHED; PG8_LDA(At, 0, 0); PG8_STAGE(PG8_SA(1, 1), a1 + hstep, voffA);
;             PG8_WAIT_V(8); PG8_WAIT_L(0); PG8_BAR; PG8_MMA(0, 0, At, B0); PG8_MMA(0, 1, At, B1); PG8_BAR; PG8_SCHED;
;             PG8_LDA(At, 0, 1); PG8_STAGE(PG8_SB(0, 0), b2, voffB); PG8_STAGE(PG8_SB(0, 1), b2 + hstep, voffB); PG8_STAGE(PG8_SA(0, 0), a2, voffA);
;             PG8_WAIT_V(8); PG8_WAIT_L(0); PG8_BAR; PG8_MMA(1, 0, At, B0); PG8_MMA(1, 1, At, B1); PG8_BAR; PG8_SCHED;
.LBB0_460:
	s_add_u32 s12, s50, 0x100
	s_addc_u32 s75, s51, 0
	s_mov_b32 s76, -2
	s_waitcnt lgkmcnt(0)
	s_add_u32 s6, s48, 0x100
	s_addc_u32 s7, s49, 0
	s_cmp_eq_u32 s76, 40
	s_cselect_b32 s53, s45, s7
	s_cselect_b32 s52, s44, s6
	s_cselect_b32 s51, s47, s75
	s_cselect_b32 s50, s46, s12
	s_add_i32 m0, s60, 0xc000
	ds_read_b128 v[128:131], v236
	global_load_lds_dwordx4 v200, s[48:49]
	s_add_i32 m0, s60, 0xe000
	ds_read_b128 v[132:135], v236 offset:1024
	global_load_lds_dwordx4 v202, s[48:49]
	ds_read_b128 v[136:139], v236 offset:2048
	ds_read_b128 v[140:143], v236 offset:3072
	ds_read_b128 v[144:147], v237
	ds_read_b128 v[148:151], v237 offset:1024
	ds_read_b128 v[152:155], v237 offset:2048
	ds_read_b128 v[156:159], v237 offset:3072
	ds_read_b128 v[160:163], v238
	ds_read_b128 v[164:167], v238 offset:1024
	ds_read_b128 v[168:171], v238 offset:2048
	ds_read_b128 v[172:175], v238 offset:3072
	ds_read_b128 v[176:179], v238 offset:4096
	ds_read_b128 v[180:183], v238 offset:5120
	ds_read_b128 v[184:187], v238 offset:6144
	ds_read_b128 v[188:191], v238 offset:7168
	s_waitcnt vmcnt(8)
	s_waitcnt lgkmcnt(0)
	s_barrier
	v_mfma_f32_16x16x32_bf16 v[124:127], v[128:131], v[160:163], 0
	v_mfma_f32_16x16x32_bf16 v[120:123], v[136:139], v[160:163], 0
	v_mfma_f32_16x16x32_bf16 v[108:111], v[128:131], v[168:171], 0
	v_mfma_f32_16x16x32_bf16 v[104:107], v[136:139], v[168:171], 0
	v_mfma_f32_16x16x32_bf16 v[92:95], v[128:131], v[176:179], 0
	v_mfma_f32_16x16x32_bf16 v[88:91], v[136:139], v[176:179], 0
	v_mfma_f32_16x16x32_bf16 v[76:79], v[128:131], v[184:187], 0
	v_mfma_f32_16x16x32_bf16 v[72:75], v[136:139], v[184:187], 0
	v_mfma_f32_16x16x32_bf16 v[124:127], v[132:135], v[164:167], v[124:127]
	v_mfma_f32_16x16x32_bf16 v[120:123], v[140:143], v[164:167], v[120:123]
	v_mfma_f32_16x16x32_bf16 v[108:111], v[132:135], v[172:175], v[108:111]
	v_mfma_f32_16x16x32_bf16 v[104:107], v[140:143], v[172:175], v[104:107]
	v_mfma_f32_16x16x32_bf16 v[92:95], v[132:135], v[180:183], v[92:95]
	v_mfma_f32_16x16x32_bf16 v[88:91], v[140:143], v[180:183], v[88:91]
	v_mfma_f32_16x16x32_bf16 v[76:79], v[132:135], v[188:191], v[76:79]
	v_mfma_f32_16x16x32_bf16 v[72:75], v[140:143], v[188:191], v[72:75]
	v_mfma_f32_16x16x32_bf16 v[116:119], v[144:147], v[160:163], 0
	v_mfma_f32_16x16x32_bf16 v[112:115], v[152:155], v[160:163], 0
	v_mfma_f32_16x16x32_bf16 v[100:103], v[144:147], v[168:171], 0
	v_mfma_f32_16x16x32_bf16 v[96:99], v[152:155], v[168:171], 0
	v_mfma_f32_16x16x32_bf16 v[84:87], v[144:147], v[176:179], 0
	v_mfma_f32_16x16x32_bf16 v[80:83], v[152:155], v[176:179], 0
	v_mfma_f32_16x16x32_bf16 v[68:71], v[144:147], v[184:187], 0
	v_mfma_f32_16x16x32_bf16 v[64:67], v[152:155], v[184:187], 0
	v_mfma_f32_16x16x32_bf16 v[116:119], v[148:151], v[164:167], v[116:119]
	v_mfma_f32_16x16x32_bf16 v[112:115], v[156:159], v[164:167], v[112:115]
	v_mfma_f32_16x16x32_bf16 v[100:103], v[148:151], v[172:175], v[100:103]
	v_mfma_f32_16x16x32_bf16 v[96:99], v[156:159], v[172:175], v[96:99]
	v_mfma_f32_16x16x32_bf16 v[84:87], v[148:151], v[180:183], v[84:87]
	v_mfma_f32_16x16x32_bf16 v[80:83], v[156:159], v[180:183], v[80:83]
	v_mfma_f32_16x16x32_bf16 v[68:71], v[148:151], v[188:191], v[68:71]
	v_mfma_f32_16x16x32_bf16 v[64:67], v[156:159], v[188:191], v[64:67]
	s_barrier
	s_add_u32 s98, s50, s22
	s_addc_u32 s99, s51, s23
	s_add_u32 s100, s52, s22
	s_addc_u32 s101, s53, s23
	s_add_i32 s48, s70, s59
	s_mov_b32 m0, s48
	ds_read_b128 v[160:163], v238 offset:16384
	global_load_lds_dwordx4 v194, s[50:51]
	s_add_i32 m0, s48, 0x2000
	s_add_u32 s48, s50, 0xb0000
	s_addc_u32 s49, s51, 0
	s_add_i32 s77, s71, s59
	global_load_lds_dwordx4 v198, s[50:51]
	s_mov_b32 m0, s77
	ds_read_b128 v[164:167], v238 offset:17408
	global_load_lds_dwordx4 v194, s[48:49]
	s_add_i32 m0, s77, 0x2000
	ds_read_b128 v[168:171], v238 offset:18432
	global_load_lds_dwordx4 v198, s[48:49]
	s_mov_b32 m0, s60
	ds_read_b128 v[172:175], v238 offset:19456
	global_load_lds_dwordx4 v192, s[52:53]
	s_mov_b32 m0, s61
	ds_read_b128 v[176:179], v238 offset:20480
	global_load_lds_dwordx4 v196, s[52:53]
	ds_read_b128 v[180:183], v238 offset:21504
	ds_read_b128 v[184:187], v238 offset:22528
	ds_read_b128 v[188:191], v238 offset:23552
	s_waitcnt vmcnt(8)
	s_waitcnt lgkmcnt(0)
	s_barrier
	v_mfma_f32_16x16x32_bf16 v[60:63], v[128:131], v[160:163], 0
	v_mfma_f32_16x16x32_bf16 v[56:59], v[136:139], v[160:163], 0
	v_mfma_f32_16x16x32_bf16 v[44:47], v[128:131], v[168:171], 0
	v_mfma_f32_16x16x32_bf16 v[40:43], v[136:139], v[168:171], 0
	v_mfma_f32_16x16x32_bf16 v[28:31], v[128:131], v[176:179], 0
	v_mfma_f32_16x16x32_bf16 v[24:27], v[136:139], v[176:179], 0
	v_mfma_f32_16x16x32_bf16 v[12:15], v[128:131], v[184:187], 0
	v_mfma_f32_16x16x32_bf16 v[8:11], v[136:139], v[184:187], 0
	v_mfma_f32_16x16x32_bf16 v[60:63], v[132:135], v[164:167], v[60:63]
	v_mfma_f32_16x16x32_bf16 v[56:59], v[140:143], v[164:167], v[56:59]
	v_mfma_f32_16x16x32_bf16 v[44:47], v[132:135], v[172:175], v[44:47]
	v_mfma_f32_16x16x32_bf16 v[40:43], v[140:143], v[172:175], v[40:43]
	v_mfma_f32_16x16x32_bf16 v[28:31], v[132:135], v[180:183], v[28:31]
	v_mfma_f32_16x16x32_bf16 v[24:27], v[140:143], v[180:183], v[24:27]
	v_mfma_f32_16x16x32_bf16 v[12:15], v[132:135], v[188:191], v[12:15]
	v_mfma_f32_16x16x32_bf16 v[8:11], v[140:143], v[188:191], v[8:11]
	v_mfma_f32_16x16x32_bf16 v[52:55], v[144:147], v[160:163], 0
	v_mfma_f32_16x16x32_bf16 v[48:51], v[152:155], v[160:163], 0
	v_mfma_f32_16x16x32_bf16 v[36:39], v[144:147], v[168:171], 0
	v_mfma_f32_16x16x32_bf16 v[32:35], v[152:155], v[168:171], 0
	v_mfma_f32_16x16x32_bf16 v[20:23], v[144:147], v[176:179], 0
	v_mfma_f32_16x16x32_bf16 v[16:19], v[152:155], v[176:179], 0
	v_mfma_f32_16x16x32_bf16 v[4:7], v[144:147], v[184:187], 0
	v_mfma_f32_16x16x32_bf16 v[0:3], v[152:155], v[184:187], 0
	v_mfma_f32_16x16x32_bf16 v[52:55], v[148:151], v[164:167], v[52:55]
	v_mfma_f32_16x16x32_bf16 v[48:51], v[156:159], v[164:167], v[48:51]
	v_mfma_f32_16x16x32_bf16 v[36:39], v[148:151], v[172:175], v[36:39]
	v_mfma_f32_16x16x32_bf16 v[32:35], v[156:159], v[172:175], v[32:35]
	v_mfma_f32_16x16x32_bf16 v[20:23], v[148:151], v[180:183], v[20:23]
	v_mfma_f32_16x16x32_bf16 v[16:19], v[156:159], v[180:183], v[16:19]
	v_mfma_f32_16x16x32_bf16 v[4:7], v[148:151], v[188:191], v[4:7]
	v_mfma_f32_16x16x32_bf16 v[0:3], v[156:159], v[188:191], v[0:3]
	s_barrier
; #define PG8_STAGE(bufoff, gbase, voff) do { _Pragma("unroll") for (int _i = 0; _i < 2; ++_i) \
;         __builtin_amdgcn_global_load_lds((const unsigned*)((const char*)(gbase) + (voff)[_i]), (PG8_LAS unsigned*)(lds + (bufoff) + ldsw + _i * 8192), 16, 0, 0); } while (0)
; #define PG8_LDA(dst, b, h) do { _Pragma("unroll") for (int m = 0; m < 4; ++m) _Pragma("unroll") for (int k = 0; k < 2; ++k) dst[m][k] = *(const PG8_LAS bf16x8*)(lds + PG8_SA(b, h) + aoff + m * 2048 + k * 1024); } while (0)
; #define PG8_LDB(dst, b, h) do { _Pragma("unroll") for (int n = 0; n < 2; ++n) _Pragma("unroll") for (int k = 0; k < 2; ++k) dst[n][k] = *(const PG8_LAS bf16x8*)(lds + PG8_SB(b, h) + boff + n * 2048 + k * 1024); } while (0)
; #define PG8_MMA(ai, bj, At, Bt) do { __builtin_amdgcn_s_setprio(1); _Pragma("unroll") for (int m = 0; m < 4; ++m) _Pragma("unroll") for (int n = 0; n < 2; ++n) _Pragma("unroll") for (int k = 0; k < 2; ++k) \
;         acc[ai][bj][m][n] = __builtin_amdgcn_mfma_f32_16x16x32_bf16(Bt[n][k], At[m][k], acc[ai][bj][m][n], 0, 0, 0); __builtin_amdgcn_s_setprio(0); } while (0)
; #define PG8_WAIT_V(n) asm volatile("s_waitcnt vmcnt(" #n ")" ::: "memory")
; #define PG8_WAIT_L(n) asm volatile("s_waitcnt lgkmcnt(" #n ")" ::: "memory")
; #define PG8_BAR __builtin_amdgcn_s_barrier()
; #define PG8_SCHED __builtin_amdgcn_sched_barrier(0)
; template <class Epi, class Sched, bool ALIGN_EPI = false, bool SP2 = false>
; __device__ __forceinline__ void gemm_phase(PG8_LAS unsigned char* lds, const Gemm g, const Sched& S, const Epi& E, int tid_in) {
;     ...
;             PG8_LDB(B0, 1, 0); PG8_LDB(B1, 1, 1); PG8_SCHED; PG8_LDA(At, 1, 0); PG8_STAGE(PG8_SA(0, 1), a2 + hstep, voffA);
;             PG8_WAIT_V(8); PG8_WAIT_L(0); PG8_BAR; PG8_MMA(0, 0, At, B0); PG8_MMA(0, 1, At, B1); PG8_BAR; PG8_SCHED;
;             PG8_LDA(At, 1, 1); PG8_STAGE(PG8_SB(1, 0), b3, voffB); PG8_STAGE(PG8_SB(1, 1), b3 + hstep, voffB); PG8_STAGE(PG8_SA(1, 0), a3, voffA);
;             PG8_WAIT_V(8); PG8_WAIT_L(0); PG8_BAR; PG8_MMA(1, 0, At, B0); PG8_MMA(1, 1, At, B1); PG8_BAR; PG8_SCHED;
	s_add_i32 s77, 0, 0x18000
	s_add_i32 s78, 0, 0x1c000
	s_add_u32 s48, s52, 0xb0000
	s_addc_u32 s49, s53, 0
	s_mov_b32 m0, s62
	s_nop 0
	global_load_lds_dwordx4 v192, s[48:49]
	s_mov_b32 m0, s63
	s_nop 0
	global_load_lds_dwordx4 v196, s[48:49]
	v_add_u32_e32 v140, s77, v232
	v_add_u32_e32 v156, s78, v232
	ds_read_b128 v[128:131], v140
	ds_read_b128 v[132:135], v140 offset:1024
	ds_read_b128 v[136:139], v140 offset:2048
	ds_read_b128 v[140:143], v140 offset:3072
	ds_read_b128 v[144:147], v156
	ds_read_b128 v[148:151], v156 offset:1024
	ds_read_b128 v[152:155], v156 offset:2048
	ds_read_b128 v[156:159], v156 offset:3072
	ds_read_b128 v[160:163], v238 offset:32768
	ds_read_b128 v[164:167], v238 offset:33792
	ds_read_b128 v[168:171], v238 offset:34816
	ds_read_b128 v[172:175], v238 offset:35840
	ds_read_b128 v[176:179], v238 offset:36864
	ds_read_b128 v[180:183], v238 offset:37888
	ds_read_b128 v[184:187], v238 offset:38912
	ds_read_b128 v[188:191], v238 offset:39936
	s_waitcnt vmcnt(8)
	s_waitcnt lgkmcnt(0)
	s_barrier
	v_mfma_f32_16x16x32_bf16 v[124:127], v[128:131], v[160:163], v[124:127]
	v_mfma_f32_16x16x32_bf16 v[120:123], v[136:139], v[160:163], v[120:123]
	v_mfma_f32_16x16x32_bf16 v[108:111], v[128:131], v[168:171], v[108:111]
	v_mfma_f32_16x16x32_bf16 v[104:107], v[136:139], v[168:171], v[104:107]
	v_mfma_f32_16x16x32_bf16 v[92:95], v[128:131], v[176:179], v[92:95]
	v_mfma_f32_16x16x32_bf16 v[88:91], v[136:139], v[176:179], v[88:91]
	v_mfma_f32_16x16x32_bf16 v[76:79], v[128:131], v[184:187], v[76:79]
	v_mfma_f32_16x16x32_bf16 v[72:75], v[136:139], v[184:187], v[72:75]
	v_mfma_f32_16x16x32_bf16 v[124:127], v[132:135], v[164:167], v[124:127]
	v_mfma_f32_16x16x32_bf16 v[120:123], v[140:143], v[164:167], v[120:123]
	v_mfma_f32_16x16x32_bf16 v[108:111], v[132:135], v[172:175], v[108:111]
	v_mfma_f32_16x16x32_bf16 v[104:107], v[140:143], v[172:175], v[104:107]
	v_mfma_f32_16x16x32_bf16 v[92:95], v[132:135], v[180:183], v[92:95]
	v_mfma_f32_16x16x32_bf16 v[88:91], v[140:143], v[180:183], v[88:91]
	v_mfma_f32_16x16x32_bf16 v[76:79], v[132:135], v[188:191], v[76:79]
	v_mfma_f32_16x16x32_bf16 v[72:75], v[140:143], v[188:191], v[72:75]
	v_mfma_f32_16x16x32_bf16 v[116:119], v[144:147], v[160:163], v[116:119]
	v_mfma_f32_16x16x32_bf16 v[112:115], v[152:155], v[160:163], v[112:115]
	v_mfma_f32_16x16x32_bf16 v[100:103], v[144:147], v[168:171], v[100:103]
	v_mfma_f32_16x16x32_bf16 v[96:99], v[152:155], v[168:171], v[96:99]
	v_mfma_f32_16x16x32_bf16 v[84:87], v[144:147], v[176:179], v[84:87]
	v_mfma_f32_16x16x32_bf16 v[80:83], v[152:155], v[176:179], v[80:83]
	v_mfma_f32_16x16x32_bf16 v[68:71], v[144:147], v[184:187], v[68:71]
	v_mfma_f32_16x16x32_bf16 v[64:67], v[152:155], v[184:187], v[64:67]
	v_mfma_f32_16x16x32_bf16 v[116:119], v[148:151], v[164:167], v[116:119]
	v_mfma_f32_16x16x32_bf16 v[112:115], v[156:159], v[164:167], v[112:115]
	v_mfma_f32_16x16x32_bf16 v[100:103], v[148:151], v[172:175], v[100:103]
	v_mfma_f32_16x16x32_bf16 v[96:99], v[156:159], v[172:175], v[96:99]
	v_mfma_f32_16x16x32_bf16 v[84:87], v[148:151], v[180:183], v[84:87]
	v_mfma_f32_16x16x32_bf16 v[80:83], v[156:159], v[180:183], v[80:83]
	v_mfma_f32_16x16x32_bf16 v[68:71], v[148:151], v[188:191], v[68:71]
	v_mfma_f32_16x16x32_bf16 v[64:67], v[156:159], v[188:191], v[64:67]
	s_barrier
	s_add_i32 s48, s77, s59
	s_mov_b32 m0, s48
	ds_read_b128 v[160:163], v238 offset:49152
	global_load_lds_dwordx4 v194, s[98:99]
	s_add_i32 m0, s48, 0x2000
	s_add_u32 s48, s50, 0xb0080
	s_addc_u32 s49, s51, 0
	s_add_i32 s50, s78, s59
	global_load_lds_dwordx4 v198, s[98:99]
	s_mov_b32 m0, s50
	ds_read_b128 v[164:167], v238 offset:50176
	global_load_lds_dwordx4 v194, s[48:49]
	s_add_i32 m0, s50, 0x2000
	ds_read_b128 v[168:171], v238 offset:51200
	global_load_lds_dwordx4 v198, s[48:49]
	s_mov_b32 m0, s65
	ds_read_b128 v[172:175], v238 offset:52224
	global_load_lds_dwordx4 v192, s[100:101]
	s_mov_b32 m0, s67
	ds_read_b128 v[176:179], v238 offset:53248
	global_load_lds_dwordx4 v196, s[100:101]
	ds_read_b128 v[180:183], v238 offset:54272
	ds_read_b128 v[184:187], v238 offset:55296
	ds_read_b128 v[188:191], v238 offset:56320
	s_waitcnt vmcnt(8)
	s_waitcnt lgkmcnt(0)
	s_barrier
	v_mfma_f32_16x16x32_bf16 v[60:63], v[128:131], v[160:163], v[60:63]
	v_mfma_f32_16x16x32_bf16 v[56:59], v[136:139], v[160:163], v[56:59]
	v_mfma_f32_16x16x32_bf16 v[44:47], v[128:131], v[168:171], v[44:47]
	v_mfma_f32_16x16x32_bf16 v[40:43], v[136:139], v[168:171], v[40:43]
	v_mfma_f32_16x16x32_bf16 v[28:31], v[128:131], v[176:179], v[28:31]
	v_mfma_f32_16x16x32_bf16 v[24:27], v[136:139], v[176:179], v[24:27]
	v_mfma_f32_16x16x32_bf16 v[12:15], v[128:131], v[184:187], v[12:15]
	v_mfma_f32_16x16x32_bf16 v[8:11], v[136:139], v[184:187], v[8:11]
	v_mfma_f32_16x16x32_bf16 v[60:63], v[132:135], v[164:167], v[60:63]
	v_mfma_f32_16x16x32_bf16 v[56:59], v[140:143], v[164:167], v[56:59]
	v_mfma_f32_16x16x32_bf16 v[44:47], v[132:135], v[172:175], v[44:47]
	v_mfma_f32_16x16x32_bf16 v[40:43], v[140:143], v[172:175], v[40:43]
	v_mfma_f32_16x16x32_bf16 v[28:31], v[132:135], v[180:183], v[28:31]
	v_mfma_f32_16x16x32_bf16 v[24:27], v[140:143], v[180:183], v[24:27]
	v_mfma_f32_16x16x32_bf16 v[12:15], v[132:135], v[188:191], v[12:15]
	v_mfma_f32_16x16x32_bf16 v[8:11], v[140:143], v[188:191], v[8:11]
	v_mfma_f32_16x16x32_bf16 v[52:55], v[144:147], v[160:163], v[52:55]
	v_mfma_f32_16x16x32_bf16 v[48:51], v[152:155], v[160:163], v[48:51]
	v_mfma_f32_16x16x32_bf16 v[36:39], v[144:147], v[168:171], v[36:39]
	v_mfma_f32_16x16x32_bf16 v[32:35], v[152:155], v[168:171], v[32:35]
	v_mfma_f32_16x16x32_bf16 v[20:23], v[144:147], v[176:179], v[20:23]
	v_mfma_f32_16x16x32_bf16 v[16:19], v[152:155], v[176:179], v[16:19]
	v_mfma_f32_16x16x32_bf16 v[4:7], v[144:147], v[184:187], v[4:7]
	v_mfma_f32_16x16x32_bf16 v[0:3], v[152:155], v[184:187], v[0:3]
	v_mfma_f32_16x16x32_bf16 v[52:55], v[148:151], v[164:167], v[52:55]
	v_mfma_f32_16x16x32_bf16 v[48:51], v[156:159], v[164:167], v[48:51]
	v_mfma_f32_16x16x32_bf16 v[36:39], v[148:151], v[172:175], v[36:39]
	v_mfma_f32_16x16x32_bf16 v[32:35], v[156:159], v[172:175], v[32:35]
	v_mfma_f32_16x16x32_bf16 v[20:23], v[148:151], v[180:183], v[20:23]
	v_mfma_f32_16x16x32_bf16 v[16:19], v[156:159], v[180:183], v[16:19]
	v_mfma_f32_16x16x32_bf16 v[4:7], v[148:151], v[188:191], v[4:7]
	v_mfma_f32_16x16x32_bf16 v[0:3], v[156:159], v[188:191], v[0:3]
	s_barrier
	s_add_i32 s76, s76, 2
	s_add_u32 s12, s12, 0x100
	s_addc_u32 s75, s75, 0
	s_mov_b64 s[48:49], s[6:7]
	v_readlane_b32 s98, v248, 0
	s_nop 3
	s_cmp_ge_u32 s98, 0x100
	s_cbranch_scc0 .Lgprio_skip_1
	s_setprio 1
; #define PG8_STAGE(bufoff, gbase, voff) do { _Pragma("unroll") for (int _i = 0; _i < 2; ++_i) \
;         __builtin_amdgcn_global_load_lds((const unsigned*)((const char*)(gbase) + (voff)[_i]), (PG8_LAS unsigned*)(lds + (bufoff) + ldsw + _i * 8192), 16, 0, 0); } while (0)
; #define PG8_LDA(dst, b, h) do { _Pragma("unroll") for (int m = 0; m < 4; ++m) _Pragma("unroll") for (int k = 0; k < 2; ++k) dst[m][k] = *(const PG8_LAS bf16x8*)(lds + PG8_SA(b, h) + aoff + m * 2048 + k * 1024); } while (0)
; #define PG8_LDB(dst, b, h) do { _Pragma("unroll") for (int n = 0; n < 2; ++n) _Pragma("unroll") for (int k = 0; k < 2; ++k) dst[n][k] = *(const PG8_LAS bf16x8*)(lds + PG8_SB(b, h) + boff + n * 2048 + k * 1024); } while (0)
; #define PG8_MMA(ai, bj, At, Bt) do { __builtin_amdgcn_s_setprio(1); _Pragma("unroll") for (int m = 0; m < 4; ++m) _Pragma("unroll") for (int n = 0; n < 2; ++n) _Pragma("unroll") for (int k = 0; k < 2; ++k) \
;         acc[ai][bj][m][n] = __builtin_amdgcn_mfma_f32_16x16x32_bf16(Bt[n][k], At[m][k], acc[ai][bj][m][n], 0, 0, 0); __builtin_amdgcn_s_setprio(0); } while (0)
; #define PG8_WAIT_V(n) asm volatile("s_waitcnt vmcnt(" #n ")" ::: "memory")
; #define PG8_WAIT_L(n) asm volatile("s_waitcnt lgkmcnt(" #n ")" ::: "memory")
; #define PG8_BAR __builtin_amdgcn_s_barrier()
; template <class Epi, class Sched, bool ALIGN_EPI = false, bool SP2 = false>
; __device__ __forceinline__ void gemm_phase(PG8_LAS unsigned char* lds, const Gemm g, const Sched& S, const Epi& E, int tid_in) {
;     ...
;             const char* a1 = cA + (size_t)(t + 1) * kstep;
;             const char* a2 = last ? nA : cA + (size_t)(t + 2) * kstep; const char* b2 = last ? nB : cB + (size_t)(t + 2) * kstep;
;             const char* a3 = a2 + kstep; const char* b3 = b2 + kstep;
;             if (last && has_next) S.a_ready(nxt);
;             if constexpr (SP2) {
;             PG8_LDB(B0, 0, 0); PG8_LDB(B1, 0, 1); PG8_SCHED; PG8_LDA(At, 0, 0); PG8_STAGE(PG8_SA(1, 1), a1 + hstep, voffA);
;             PG8_WAIT_V(8); PG8_WAIT_L(0); PG8_BAR; PG8_MMA(0, 0, At, B0); PG8_MMA(0, 1, At, B1); PG8_BAR; PG8_SCHED;
;             PG8_LDA(At, 0, 1); PG8_STAGE(PG8_SB(0, 0), b2, voffB); PG8_STAGE(PG8_SB(0, 1), b2 + hstep, voffB); PG8_STAGE(PG8_SA(0, 0), a2, voffA);
;             PG8_WAIT_V(8); PG8_WAIT_L(0); PG8_BAR; PG8_MMA(1, 0, At, B0); PG8_MMA(1, 1, At, B1); PG8_BAR; PG8_SCHED;
.Lgprio_skip_1:
.LBB0_461:
	s_add_u32 s6, s48, 0x100
	s_addc_u32 s7, s49, 0
	s_cmp_eq_u32 s76, 40
	s_cselect_b32 s53, s45, s7
	s_cselect_b32 s52, s44, s6
	s_cselect_b32 s51, s47, s75
	s_cselect_b32 s50, s46, s12
	s_add_i32 m0, s60, 0xc000
	ds_read_b128 v[128:131], v236
	global_load_lds_dwordx4 v200, s[48:49]
	s_add_i32 m0, s60, 0xe000
	ds_read_b128 v[132:135], v236 offset:1024
	global_load_lds_dwordx4 v202, s[48:49]
	ds_read_b128 v[136:139], v236 offset:2048
	ds_read_b128 v[140:143], v236 offset:3072
	ds_read_b128 v[144:147], v237
	ds_read_b128 v[148:151], v237 offset:1024
	ds_read_b128 v[152:155], v237 offset:2048
	ds_read_b128 v[156:159], v237 offset:3072
	ds_read_b128 v[160:163], v238
	ds_read_b128 v[164:167], v238 offset:1024
	ds_read_b128 v[168:171], v238 offset:2048
	ds_read_b128 v[172:175], v238 offset:3072
	ds_read_b128 v[176:179], v238 offset:4096
	ds_read_b128 v[180:183], v238 offset:5120
	ds_read_b128 v[184:187], v238 offset:6144
	ds_read_b128 v[188:191], v238 offset:7168
	s_waitcnt vmcnt(8)
	s_waitcnt lgkmcnt(0)
	s_barrier
	v_mfma_f32_16x16x32_bf16 v[124:127], v[128:131], v[160:163], v[124:127]
	v_mfma_f32_16x16x32_bf16 v[120:123], v[136:139], v[160:163], v[120:123]
	v_mfma_f32_16x16x32_bf16 v[108:111], v[128:131], v[168:171], v[108:111]
	v_mfma_f32_16x16x32_bf16 v[104:107], v[136:139], v[168:171], v[104:107]
	v_mfma_f32_16x16x32_bf16 v[92:95], v[128:131], v[176:179], v[92:95]
	v_mfma_f32_16x16x32_bf16 v[88:91], v[136:139], v[176:179], v[88:91]
	v_mfma_f32_16x16x32_bf16 v[76:79], v[128:131], v[184:187], v[76:79]
	v_mfma_f32_16x16x32_bf16 v[72:75], v[136:139], v[184:187], v[72:75]
	v_mfma_f32_16x16x32_bf16 v[124:127], v[132:135], v[164:167], v[124:127]
	v_mfma_f32_16x16x32_bf16 v[120:123], v[140:143], v[164:167], v[120:123]
	v_mfma_f32_16x16x32_bf16 v[108:111], v[132:135], v[172:175], v[108:111]
	v_mfma_f32_16x16x32_bf16 v[104:107], v[140:143], v[172:175], v[104:107]
	v_mfma_f32_16x16x32_bf16 v[92:95], v[132:135], v[180:183], v[92:95]
	v_mfma_f32_16x16x32_bf16 v[88:91], v[140:143], v[180:183], v[88:91]
	v_mfma_f32_16x16x32_bf16 v[76:79], v[132:135], v[188:191], v[76:79]
	v_mfma_f32_16x16x32_bf16 v[72:75], v[140:143], v[188:191], v[72:75]
	v_mfma_f32_16x16x32_bf16 v[116:119], v[144:147], v[160:163], v[116:119]
	v_mfma_f32_16x16x32_bf16 v[112:115], v[152:155], v[160:163], v[112:115]
	v_mfma_f32_16x16x32_bf16 v[100:103], v[144:147], v[168:171], v[100:103]
	v_mfma_f32_16x16x32_bf16 v[96:99], v[152:155], v[168:171], v[96:99]
	v_mfma_f32_16x16x32_bf16 v[84:87], v[144:147], v[176:179], v[84:87]
	v_mfma_f32_16x16x32_bf16 v[80:83], v[152:155], v[176:179], v[80:83]
	v_mfma_f32_16x16x32_bf16 v[68:71], v[144:147], v[184:187], v[68:71]
	v_mfma_f32_16x16x32_bf16 v[64:67], v[152:155], v[184:187], v[64:67]
	v_mfma_f32_16x16x32_bf16 v[116:119], v[148:151], v[164:167], v[116:119]
	v_mfma_f32_16x16x32_bf16 v[112:115], v[156:159], v[164:167], v[112:115]
	v_mfma_f32_16x16x32_bf16 v[100:103], v[148:151], v[172:175], v[100:103]
	v_mfma_f32_16x16x32_bf16 v[96:99], v[156:159], v[172:175], v[96:99]
	v_mfma_f32_16x16x32_bf16 v[84:87], v[148:151], v[180:183], v[84:87]
	v_mfma_f32_16x16x32_bf16 v[80:83], v[156:159], v[180:183], v[80:83]
	v_mfma_f32_16x16x32_bf16 v[68:71], v[148:151], v[188:191], v[68:71]
	v_mfma_f32_16x16x32_bf16 v[64:67], v[156:159], v[188:191], v[64:67]
	s_barrier
	s_add_u32 s98, s50, s22
	s_addc_u32 s99, s51, s23
	s_add_u32 s100, s52, s22
	s_addc_u32 s101, s53, s23
	s_add_i32 s48, s70, s59
	s_mov_b32 m0, s48
	ds_read_b128 v[160:163], v238 offset:16384
	global_load_lds_dwordx4 v194, s[50:51]
	s_add_i32 m0, s48, 0x2000
	s_add_u32 s48, s50, 0xb0000
	s_addc_u32 s49, s51, 0
	s_add_i32 s77, s71, s59
	global_load_lds_dwordx4 v198, s[50:51]
	s_mov_b32 m0, s77
	ds_read_b128 v[164:167], v238 offset:17408
	global_load_lds_dwordx4 v194, s[48:49]
	s_add_i32 m0, s77, 0x2000
	ds_read_b128 v[168:171], v238 offset:18432
	global_load_lds_dwordx4 v198, s[48:49]
	s_mov_b32 m0, s60
	ds_read_b128 v[172:175], v238 offset:19456
	global_load_lds_dwordx4 v192, s[52:53]
	s_mov_b32 m0, s61
	ds_read_b128 v[176:179], v238 offset:20480
	global_load_lds_dwordx4 v196, s[52:53]
	ds_read_b128 v[180:183], v238 offset:21504
	ds_read_b128 v[184:187], v238 offset:22528
	ds_read_b128 v[188:191], v238 offset:23552
	s_waitcnt vmcnt(8)
	s_waitcnt lgkmcnt(0)
	s_barrier
	v_mfma_f32_16x16x32_bf16 v[60:63], v[128:131], v[160:163], v[60:63]
	v_mfma_f32_16x16x32_bf16 v[56:59], v[136:139], v[160:163], v[56:59]
	v_mfma_f32_16x16x32_bf16 v[44:47], v[128:131], v[168:171], v[44:47]
	v_mfma_f32_16x16x32_bf16 v[40:43], v[136:139], v[168:171], v[40:43]
	v_mfma_f32_16x16x32_bf16 v[28:31], v[128:131], v[176:179], v[28:31]
	v_mfma_f32_16x16x32_bf16 v[24:27], v[136:139], v[176:179], v[24:27]
	v_mfma_f32_16x16x32_bf16 v[12:15], v[128:131], v[184:187], v[12:15]
	v_mfma_f32_16x16x32_bf16 v[8:11], v[136:139], v[184:187], v[8:11]
	v_mfma_f32_16x16x32_bf16 v[60:63], v[132:135], v[164:167], v[60:63]
	v_mfma_f32_16x16x32_bf16 v[56:59], v[140:143], v[164:167], v[56:59]
	v_mfma_f32_16x16x32_bf16 v[44:47], v[132:135], v[172:175], v[44:47]
	v_mfma_f32_16x16x32_bf16 v[40:43], v[140:143], v[172:175], v[40:43]
	v_mfma_f32_16x16x32_bf16 v[28:31], v[132:135], v[180:183], v[28:31]
	v_mfma_f32_16x16x32_bf16 v[24:27], v[140:143], v[180:183], v[24:27]
	v_mfma_f32_16x16x32_bf16 v[12:15], v[132:135], v[188:191], v[12:15]
	v_mfma_f32_16x16x32_bf16 v[8:11], v[140:143], v[188:191], v[8:11]
	v_mfma_f32_16x16x32_bf16 v[52:55], v[144:147], v[160:163], v[52:55]
	v_mfma_f32_16x16x32_bf16 v[48:51], v[152:155], v[160:163], v[48:51]
	v_mfma_f32_16x16x32_bf16 v[36:39], v[144:147], v[168:171], v[36:39]
	v_mfma_f32_16x16x32_bf16 v[32:35], v[152:155], v[168:171], v[32:35]
	v_mfma_f32_16x16x32_bf16 v[20:23], v[144:147], v[176:179], v[20:23]
	v_mfma_f32_16x16x32_bf16 v[16:19], v[152:155], v[176:179], v[16:19]
	v_mfma_f32_16x16x32_bf16 v[4:7], v[144:147], v[184:187], v[4:7]
	v_mfma_f32_16x16x32_bf16 v[0:3], v[152:155], v[184:187], v[0:3]
	v_mfma_f32_16x16x32_bf16 v[52:55], v[148:151], v[164:167], v[52:55]
	v_mfma_f32_16x16x32_bf16 v[48:51], v[156:159], v[164:167], v[48:51]
	v_mfma_f32_16x16x32_bf16 v[36:39], v[148:151], v[172:175], v[36:39]
	v_mfma_f32_16x16x32_bf16 v[32:35], v[156:159], v[172:175], v[32:35]
	v_mfma_f32_16x16x32_bf16 v[20:23], v[148:151], v[180:183], v[20:23]
	v_mfma_f32_16x16x32_bf16 v[16:19], v[156:159], v[180:183], v[16:19]
	v_mfma_f32_16x16x32_bf16 v[4:7], v[148:151], v[188:191], v[4:7]
	v_mfma_f32_16x16x32_bf16 v[0:3], v[156:159], v[188:191], v[0:3]
	s_barrier
; #define PG8_STAGE(bufoff, gbase, voff) do { _Pragma("unroll") for (int _i = 0; _i < 2; ++_i) \
;         __builtin_amdgcn_global_load_lds((const unsigned*)((const char*)(gbase) + (voff)[_i]), (PG8_LAS unsigned*)(lds + (bufoff) + ldsw + _i * 8192), 16, 0, 0); } while (0)
; #define PG8_LDA(dst, b, h) do { _Pragma("unroll") for (int m = 0; m < 4; ++m) _Pragma("unroll") for (int k = 0; k < 2; ++k) dst[m][k] = *(const PG8_LAS bf16x8*)(lds + PG8_SA(b, h) + aoff + m * 2048 + k * 1024); } while (0)
; #define PG8_LDB(dst, b, h) do { _Pragma("unroll") for (int n = 0; n < 2; ++n) _Pragma("unroll") for (int k = 0; k < 2; ++k) dst[n][k] = *(const PG8_LAS bf16x8*)(lds + PG8_SB(b, h) + boff + n * 2048 + k * 1024); } while (0)
; #define PG8_MMA(ai, bj, At, Bt) do { __builtin_amdgcn_s_setprio(1); _Pragma("unroll") for (int m = 0; m < 4; ++m) _Pragma("unroll") for (int n = 0; n < 2; ++n) _Pragma("unroll") for (int k = 0; k < 2; ++k) \
;         acc[ai][bj][m][n] = __builtin_amdgcn_mfma_f32_16x16x32_bf16(Bt[n][k], At[m][k], acc[ai][bj][m][n], 0, 0, 0); __builtin_amdgcn_s_setprio(0); } while (0)
; #define PG8_WAIT_V(n) asm volatile("s_waitcnt vmcnt(" #n ")" ::: "memory")
; #define PG8_WAIT_L(n) asm volatile("s_waitcnt lgkmcnt(" #n ")" ::: "memory")
; #define PG8_BAR __builtin_amdgcn_s_barrier()
; #define PG8_SCHED __builtin_amdgcn_sched_barrier(0)
; template <class Epi, class Sched, bool ALIGN_EPI = false, bool SP2 = false>
; __device__ __forceinline__ void gemm_phase(PG8_LAS unsigned char* lds, const Gemm g, const Sched& S, const Epi& E, int tid_in) {
;     ...
;             PG8_LDB(B0, 1, 0); PG8_LDB(B1, 1, 1); PG8_SCHED; PG8_LDA(At, 1, 0); PG8_STAGE(PG8_SA(0, 1), a2 + hstep, voffA);
;             PG8_WAIT_V(8); PG8_WAIT_L(0); PG8_BAR; PG8_MMA(0, 0, At, B0); PG8_MMA(0, 1, At, B1); PG8_BAR; PG8_SCHED;
;             PG8_LDA(At, 1, 1); PG8_STAGE(PG8_SB(1, 0), b3, voffB); PG8_STAGE(PG8_SB(1, 1), b3 + hstep, voffB); PG8_STAGE(PG8_SA(1, 0), a3, voffA);
;             PG8_WAIT_V(8); PG8_WAIT_L(0); PG8_BAR; PG8_MMA(1, 0, At, B0); PG8_MMA(1, 1, At, B1); PG8_BAR; PG8_SCHED;
;     ...
;         if constexpr (ALIGN_EPI) { if (wr == 0) PG8_BAR; }
	s_add_i32 s77, 0, 0x18000
	s_add_i32 s78, 0, 0x1c000
	s_add_u32 s48, s52, 0xb0000
	s_addc_u32 s49, s53, 0
	s_mov_b32 m0, s62
	s_nop 0
	global_load_lds_dwordx4 v192, s[48:49]
	s_mov_b32 m0, s63
	s_nop 0
	global_load_lds_dwordx4 v196, s[48:49]
	v_add_u32_e32 v140, s77, v232
	v_add_u32_e32 v156, s78, v232
	ds_read_b128 v[128:131], v140
	ds_read_b128 v[132:135], v140 offset:1024
	ds_read_b128 v[136:139], v140 offset:2048
	ds_read_b128 v[140:143], v140 offset:3072
	ds_read_b128 v[144:147], v156
	ds_read_b128 v[148:151], v156 offset:1024
	ds_read_b128 v[152:155], v156 offset:2048
	ds_read_b128 v[156:159], v156 offset:3072
	ds_read_b128 v[160:163], v238 offset:32768
	ds_read_b128 v[164:167], v238 offset:33792
	ds_read_b128 v[168:171], v238 offset:34816
	ds_read_b128 v[172:175], v238 offset:35840
	ds_read_b128 v[176:179], v238 offset:36864
	ds_read_b128 v[180:183], v238 offset:37888
	ds_read_b128 v[184:187], v238 offset:38912
	ds_read_b128 v[188:191], v238 offset:39936
	s_waitcnt vmcnt(8)
	s_waitcnt lgkmcnt(0)
	s_barrier
	v_mfma_f32_16x16x32_bf16 v[124:127], v[128:131], v[160:163], v[124:127]
	v_mfma_f32_16x16x32_bf16 v[120:123], v[136:139], v[160:163], v[120:123]
	v_mfma_f32_16x16x32_bf16 v[108:111], v[128:131], v[168:171], v[108:111]
	v_mfma_f32_16x16x32_bf16 v[104:107], v[136:139], v[168:171], v[104:107]
	v_mfma_f32_16x16x32_bf16 v[92:95], v[128:131], v[176:179], v[92:95]
	v_mfma_f32_16x16x32_bf16 v[88:91], v[136:139], v[176:179], v[88:91]
	v_mfma_f32_16x16x32_bf16 v[76:79], v[128:131], v[184:187], v[76:79]
	v_mfma_f32_16x16x32_bf16 v[72:75], v[136:139], v[184:187], v[72:75]
	v_mfma_f32_16x16x32_bf16 v[124:127], v[132:135], v[164:167], v[124:127]
	v_mfma_f32_16x16x32_bf16 v[120:123], v[140:143], v[164:167], v[120:123]
	v_mfma_f32_16x16x32_bf16 v[108:111], v[132:135], v[172:175], v[108:111]
	v_mfma_f32_16x16x32_bf16 v[104:107], v[140:143], v[172:175], v[104:107]
	v_mfma_f32_16x16x32_bf16 v[92:95], v[132:135], v[180:183], v[92:95]
	v_mfma_f32_16x16x32_bf16 v[88:91], v[140:143], v[180:183], v[88:91]
	v_mfma_f32_16x16x32_bf16 v[76:79], v[132:135], v[188:191], v[76:79]
	v_mfma_f32_16x16x32_bf16 v[72:75], v[140:143], v[188:191], v[72:75]
	v_mfma_f32_16x16x32_bf16 v[116:119], v[144:147], v[160:163], v[116:119]
	v_mfma_f32_16x16x32_bf16 v[112:115], v[152:155], v[160:163], v[112:115]
	v_mfma_f32_16x16x32_bf16 v[100:103], v[144:147], v[168:171], v[100:103]
	v_mfma_f32_16x16x32_bf16 v[96:99], v[152:155], v[168:171], v[96:99]
	v_mfma_f32_16x16x32_bf16 v[84:87], v[144:147], v[176:179], v[84:87]
	v_mfma_f32_16x16x32_bf16 v[80:83], v[152:155], v[176:179], v[80:83]
	v_mfma_f32_16x16x32_bf16 v[68:71], v[144:147], v[184:187], v[68:71]
	v_mfma_f32_16x16x32_bf16 v[64:67], v[152:155], v[184:187], v[64:67]
	v_mfma_f32_16x16x32_bf16 v[116:119], v[148:151], v[164:167], v[116:119]
	v_mfma_f32_16x16x32_bf16 v[112:115], v[156:159], v[164:167], v[112:115]
	v_mfma_f32_16x16x32_bf16 v[100:103], v[148:151], v[172:175], v[100:103]
	v_mfma_f32_16x16x32_bf16 v[96:99], v[156:159], v[172:175], v[96:99]
	v_mfma_f32_16x16x32_bf16 v[84:87], v[148:151], v[180:183], v[84:87]
	v_mfma_f32_16x16x32_bf16 v[80:83], v[156:159], v[180:183], v[80:83]
	v_mfma_f32_16x16x32_bf16 v[68:71], v[148:151], v[188:191], v[68:71]
	v_mfma_f32_16x16x32_bf16 v[64:67], v[156:159], v[188:191], v[64:67]
	s_barrier
	s_add_i32 s48, s77, s59
	s_mov_b32 m0, s48
	ds_read_b128 v[160:163], v238 offset:49152
	global_load_lds_dwordx4 v194, s[98:99]
	s_add_i32 m0, s48, 0x2000
	s_add_u32 s48, s50, 0xb0080
	s_addc_u32 s49, s51, 0
	s_add_i32 s50, s78, s59
	global_load_lds_dwordx4 v198, s[98:99]
	s_mov_b32 m0, s50
	ds_read_b128 v[164:167], v238 offset:50176
	global_load_lds_dwordx4 v194, s[48:49]
	s_add_i32 m0, s50, 0x2000
	ds_read_b128 v[168:171], v238 offset:51200
	global_load_lds_dwordx4 v198, s[48:49]
	s_mov_b32 m0, s65
	ds_read_b128 v[172:175], v238 offset:52224
	global_load_lds_dwordx4 v192, s[100:101]
	s_mov_b32 m0, s67
	ds_read_b128 v[176:179], v238 offset:53248
	global_load_lds_dwordx4 v196, s[100:101]
	ds_read_b128 v[180:183], v238 offset:54272
	ds_read_b128 v[184:187], v238 offset:55296
	ds_read_b128 v[188:191], v238 offset:56320
	s_waitcnt vmcnt(8)
	s_waitcnt lgkmcnt(0)
	s_barrier
	v_mfma_f32_16x16x32_bf16 v[60:63], v[128:131], v[160:163], v[60:63]
	v_mfma_f32_16x16x32_bf16 v[56:59], v[136:139], v[160:163], v[56:59]
	v_mfma_f32_16x16x32_bf16 v[44:47], v[128:131], v[168:171], v[44:47]
	v_mfma_f32_16x16x32_bf16 v[40:43], v[136:139], v[168:171], v[40:43]
	v_mfma_f32_16x16x32_bf16 v[28:31], v[128:131], v[176:179], v[28:31]
	v_mfma_f32_16x16x32_bf16 v[24:27], v[136:139], v[176:179], v[24:27]
	v_mfma_f32_16x16x32_bf16 v[12:15], v[128:131], v[184:187], v[12:15]
	v_mfma_f32_16x16x32_bf16 v[8:11], v[136:139], v[184:187], v[8:11]
	v_mfma_f32_16x16x32_bf16 v[60:63], v[132:135], v[164:167], v[60:63]
	v_mfma_f32_16x16x32_bf16 v[56:59], v[140:143], v[164:167], v[56:59]
	v_mfma_f32_16x16x32_bf16 v[44:47], v[132:135], v[172:175], v[44:47]
	v_mfma_f32_16x16x32_bf16 v[40:43], v[140:143], v[172:175], v[40:43]
	v_mfma_f32_16x16x32_bf16 v[28:31], v[132:135], v[180:183], v[28:31]
	v_mfma_f32_16x16x32_bf16 v[24:27], v[140:143], v[180:183], v[24:27]
	v_mfma_f32_16x16x32_bf16 v[12:15], v[132:135], v[188:191], v[12:15]
	v_mfma_f32_16x16x32_bf16 v[8:11], v[140:143], v[188:191], v[8:11]
	v_mfma_f32_16x16x32_bf16 v[52:55], v[144:147], v[160:163], v[52:55]
	v_mfma_f32_16x16x32_bf16 v[48:51], v[152:155], v[160:163], v[48:51]
	v_mfma_f32_16x16x32_bf16 v[36:39], v[144:147], v[168:171], v[36:39]
	v_mfma_f32_16x16x32_bf16 v[32:35], v[152:155], v[168:171], v[32:35]
	v_mfma_f32_16x16x32_bf16 v[20:23], v[144:147], v[176:179], v[20:23]
	v_mfma_f32_16x16x32_bf16 v[16:19], v[152:155], v[176:179], v[16:19]
	v_mfma_f32_16x16x32_bf16 v[4:7], v[144:147], v[184:187], v[4:7]
	v_mfma_f32_16x16x32_bf16 v[0:3], v[152:155], v[184:187], v[0:3]
	v_mfma_f32_16x16x32_bf16 v[52:55], v[148:151], v[164:167], v[52:55]
	v_mfma_f32_16x16x32_bf16 v[48:51], v[156:159], v[164:167], v[48:51]
	v_mfma_f32_16x16x32_bf16 v[36:39], v[148:151], v[172:175], v[36:39]
	v_mfma_f32_16x16x32_bf16 v[32:35], v[156:159], v[172:175], v[32:35]
	v_mfma_f32_16x16x32_bf16 v[20:23], v[148:151], v[180:183], v[20:23]
	v_mfma_f32_16x16x32_bf16 v[16:19], v[156:159], v[180:183], v[16:19]
	v_mfma_f32_16x16x32_bf16 v[4:7], v[148:151], v[188:191], v[4:7]
	v_mfma_f32_16x16x32_bf16 v[0:3], v[156:159], v[188:191], v[0:3]
	s_barrier
	s_add_i32 s76, s76, 2
	s_add_u32 s12, s12, 0x100
	s_addc_u32 s75, s75, 0
	s_cmp_gt_u32 s76, 41
	s_mov_b64 s[48:49], s[6:7]
	s_cbranch_scc0 .LBB0_461
	s_setprio 0
	s_and_b64 vcc, exec, s[24:25]
	s_cbranch_vccz .LBB0_464
	s_barrier

; #define PG8_STAGE(bufoff, gbase, voff) do { _Pragma("unroll") for (int _i = 0; _i < 2; ++_i) \
;         __builtin_amdgcn_global_load_lds((const unsigned*)((const char*)(gbase) + (voff)[_i]), (PG8_LAS unsigned*)(lds + (bufoff) + ldsw + _i * 8192), 16, 0, 0); } while (0)
; #define PG8_LDA(dst, b, h) do { _Pragma("unroll") for (int m = 0; m < 4; ++m) _Pragma("unroll") for (int k = 0; k < 2; ++k) dst[m][k] = *(const PG8_LAS bf16x8*)(lds + PG8_SA(b, h) + aoff + m * 2048 + k * 1024); } while (0)
; #define PG8_LDB(dst, b, h) do { _Pragma("unroll") for (int n = 0; n < 2; ++n) _Pragma("unroll") for (int k = 0; k < 2; ++k) dst[n][k] = *(const PG8_LAS bf16x8*)(lds + PG8_SB(b, h) + boff + n * 2048 + k * 1024); } while (0)
; #define PG8_WAIT_V(n) asm volatile("s_waitcnt vmcnt(" #n ")" ::: "memory")
; #define PG8_WAIT_L(n) asm volatile("s_waitcnt lgkmcnt(" #n ")" ::: "memory")
; #define PG8_BAR __builtin_amdgcn_s_barrier()
; #define PG8_SCHED __builtin_amdgcn_sched_barrier(0)
; template <class Epi, class Sched, bool ALIGN_EPI = false, bool SP2 = false>
; __device__ __forceinline__ void gemm_phase(PG8_LAS unsigned char* lds, const Gemm g, const Sched& S, const Epi& E, int tid_in) {
;     ...
;         const bool has_next = S.next(ui + 1, nxt);
;         const char* nA = has_next ? (const char*)g.A + (size_t)nxt.pm * tstep : cA; const char* nB = has_next ? (const char*)g.Bt + (size_t)nxt.pn * tstep : cB;
;         for (int t = 0; t < nt; t += 2) {
;             if constexpr (Epi::MIDK) { if (t == Epi::MIDK_T) { if (wr == 0) PG8_BAR; E.mid(acc, cur, wr, wc, fr, fq); if (wr == 1) PG8_BAR; } }
;             const bool last = (t == nt - 2);
;             const char* a1 = cA + (size_t)(t + 1) * kstep;
;             const char* a2 = last ? nA : cA + (size_t)(t + 2) * kstep; const char* b2 = last ? nB : cB + (size_t)(t + 2) * kstep;
;             const char* a3 = a2 + kstep; const char* b3 = b2 + kstep;
;             if (last && has_next) S.a_ready(nxt);
;             if constexpr (SP2) {
;             PG8_LDB(B0, 0, 0); PG8_LDB(B1, 0, 1); PG8_SCHED; PG8_LDA(At, 0, 0); PG8_STAGE(PG8_SA(1, 1), a1 + hstep, voffA);
;             PG8_WAIT_V(8); PG8_WAIT_L(0); PG8_BAR; PG8_MMA(0, 0, At, B0); PG8_MMA(0, 1, At, B1); PG8_BAR; PG8_SCHED;
;             PG8_LDA(At, 0, 1); PG8_STAGE(PG8_SB(0, 0), b2, voffB); PG8_STAGE(PG8_SB(0, 1), b2 + hstep, voffB); PG8_STAGE(PG8_SA(0, 0), a2, voffA);
.LBB0_563:
	s_ashr_i32 s35, s34, 31
	s_lshl_b64 s[0:1], s[34:35], 19
	s_add_u32 s36, s54, s0
	s_addc_u32 s37, s55, s1
	s_and_b64 s[0:1], s[4:5], exec
	s_cselect_b32 s0, s37, s47
	s_cselect_b32 s1, s36, s46
	s_ashr_i32 s31, s30, 31
	s_lshl_b64 s[38:39], s[30:31], 19
	s_add_u32 s38, s56, s38
	s_addc_u32 s39, s57, s39
	s_and_b64 s[50:51], s[4:5], exec
	s_cselect_b32 s7, s39, s49
	s_cselect_b32 s31, s38, s48
	s_add_u32 s46, s46, 0x40080
	s_addc_u32 s47, s47, 0
	s_add_u32 s35, s48, 0x100
	s_addc_u32 s45, s49, 0
	s_mov_b32 s52, -2
	s_add_u32 s48, s46, 0xfffc0080
	s_addc_u32 s49, s47, -1
	s_cmp_eq_u32 s52, 12
	s_cselect_b32 s51, s0, s49
	s_cselect_b32 s50, s1, s48
	s_cselect_b32 s49, s7, s45
	s_cselect_b32 s48, s31, s35
	s_add_i32 m0, s59, 0xc000
	ds_read_b128 v[128:131], v180
	global_load_lds_dwordx4 v158, s[46:47]
	s_add_i32 m0, s59, 0xe000
	ds_read_b128 v[132:135], v180 offset:1024
	global_load_lds_dwordx4 v160, s[46:47]
	ds_read_b128 v[136:139], v180 offset:2048
	ds_read_b128 v[140:143], v180 offset:3072
	ds_read_b128 v[166:169], v181
	ds_read_b128 v[170:173], v181 offset:1024
	ds_read_b128 v[174:177], v181 offset:2048
	ds_read_b128 v[184:187], v181 offset:3072
	ds_read_b128 v[188:191], v182
	ds_read_b128 v[192:195], v182 offset:1024
	ds_read_b128 v[196:199], v182 offset:2048
	ds_read_b128 v[200:203], v182 offset:3072
	ds_read_b128 v[204:207], v182 offset:4096
	ds_read_b128 v[208:211], v182 offset:5120
	ds_read_b128 v[212:215], v182 offset:6144
	ds_read_b128 v[216:219], v182 offset:7168
	s_waitcnt vmcnt(8)
	s_waitcnt lgkmcnt(0)
	s_barrier
	v_mfma_f32_16x16x32_bf16 v[68:71], v[128:131], v[188:191], 0
	v_mfma_f32_16x16x32_bf16 v[56:59], v[136:139], v[188:191], 0
	v_mfma_f32_16x16x32_bf16 v[52:55], v[128:131], v[196:199], 0
	v_mfma_f32_16x16x32_bf16 v[48:51], v[136:139], v[196:199], 0
	v_mfma_f32_16x16x32_bf16 v[44:47], v[128:131], v[204:207], 0
	v_mfma_f32_16x16x32_bf16 v[40:43], v[136:139], v[204:207], 0
	v_mfma_f32_16x16x32_bf16 v[36:39], v[128:131], v[212:215], 0
	v_mfma_f32_16x16x32_bf16 v[32:35], v[136:139], v[212:215], 0
	v_mfma_f32_16x16x32_bf16 v[68:71], v[132:135], v[192:195], v[68:71]
	v_mfma_f32_16x16x32_bf16 v[56:59], v[140:143], v[192:195], v[56:59]
	v_mfma_f32_16x16x32_bf16 v[52:55], v[132:135], v[200:203], v[52:55]
	v_mfma_f32_16x16x32_bf16 v[48:51], v[140:143], v[200:203], v[48:51]
	v_mfma_f32_16x16x32_bf16 v[44:47], v[132:135], v[208:211], v[44:47]
	v_mfma_f32_16x16x32_bf16 v[40:43], v[140:143], v[208:211], v[40:43]
	v_mfma_f32_16x16x32_bf16 v[36:39], v[132:135], v[216:219], v[36:39]
	v_mfma_f32_16x16x32_bf16 v[32:35], v[140:143], v[216:219], v[32:35]
	v_mfma_f32_16x16x32_bf16 v[124:127], v[166:169], v[188:191], 0
	v_mfma_f32_16x16x32_bf16 v[120:123], v[174:177], v[188:191], 0
	v_mfma_f32_16x16x32_bf16 v[116:119], v[166:169], v[196:199], 0
	v_mfma_f32_16x16x32_bf16 v[112:115], v[174:177], v[196:199], 0
	v_mfma_f32_16x16x32_bf16 v[108:111], v[166:169], v[204:207], 0
	v_mfma_f32_16x16x32_bf16 v[104:107], v[174:177], v[204:207], 0
	v_mfma_f32_16x16x32_bf16 v[100:103], v[166:169], v[212:215], 0
	v_mfma_f32_16x16x32_bf16 v[96:99], v[174:177], v[212:215], 0
	v_mfma_f32_16x16x32_bf16 v[124:127], v[170:173], v[192:195], v[124:127]
	v_mfma_f32_16x16x32_bf16 v[120:123], v[184:187], v[192:195], v[120:123]
	v_mfma_f32_16x16x32_bf16 v[116:119], v[170:173], v[200:203], v[116:119]
	v_mfma_f32_16x16x32_bf16 v[112:115], v[184:187], v[200:203], v[112:115]
	v_mfma_f32_16x16x32_bf16 v[108:111], v[170:173], v[208:211], v[108:111]
	v_mfma_f32_16x16x32_bf16 v[104:107], v[184:187], v[208:211], v[104:107]
	v_mfma_f32_16x16x32_bf16 v[100:103], v[170:173], v[216:219], v[100:103]
	v_mfma_f32_16x16x32_bf16 v[96:99], v[184:187], v[216:219], v[96:99]
	s_barrier
	s_add_u32 s98, s48, s14
	s_addc_u32 s99, s49, s15
	s_add_u32 s100, s50, s14
	s_addc_u32 s101, s51, s15
	s_add_i32 s53, s77, s29
	s_mov_b32 m0, s53
	ds_read_b128 v[188:191], v182 offset:16384
	global_load_lds_dwordx4 v146, s[48:49]
	s_add_i32 m0, s53, 0x2000
	s_add_u32 s88, s48, 0x40000
	s_addc_u32 s89, s49, 0
	s_add_i32 s53, s78, s29
	global_load_lds_dwordx4 v150, s[48:49]
	s_mov_b32 m0, s53
	ds_read_b128 v[192:195], v182 offset:17408
	global_load_lds_dwordx4 v146, s[88:89]
	s_add_i32 m0, s53, 0x2000
	ds_read_b128 v[196:199], v182 offset:18432
	global_load_lds_dwordx4 v150, s[88:89]
	s_mov_b32 m0, s59
	ds_read_b128 v[200:203], v182 offset:19456
	global_load_lds_dwordx4 v144, s[50:51]
	s_mov_b32 m0, s60
	ds_read_b128 v[204:207], v182 offset:20480
	global_load_lds_dwordx4 v148, s[50:51]
	ds_read_b128 v[208:211], v182 offset:21504
	ds_read_b128 v[212:215], v182 offset:22528
	ds_read_b128 v[216:219], v182 offset:23552
	s_waitcnt vmcnt(8)
	s_waitcnt lgkmcnt(0)
	s_barrier
; #define PG8_STAGE(bufoff, gbase, voff) do { _Pragma("unroll") for (int _i = 0; _i < 2; ++_i) \
;         __builtin_amdgcn_global_load_lds((const unsigned*)((const char*)(gbase) + (voff)[_i]), (PG8_LAS unsigned*)(lds + (bufoff) + ldsw + _i * 8192), 16, 0, 0); } while (0)
; #define PG8_LDA(dst, b, h) do { _Pragma("unroll") for (int m = 0; m < 4; ++m) _Pragma("unroll") for (int k = 0; k < 2; ++k) dst[m][k] = *(const PG8_LAS bf16x8*)(lds + PG8_SA(b, h) + aoff + m * 2048 + k * 1024); } while (0)
; #define PG8_LDB(dst, b, h) do { _Pragma("unroll") for (int n = 0; n < 2; ++n) _Pragma("unroll") for (int k = 0; k < 2; ++k) dst[n][k] = *(const PG8_LAS bf16x8*)(lds + PG8_SB(b, h) + boff + n * 2048 + k * 1024); } while (0)
; #define PG8_MMA(ai, bj, At, Bt) do { __builtin_amdgcn_s_setprio(1); _Pragma("unroll") for (int m = 0; m < 4; ++m) _Pragma("unroll") for (int n = 0; n < 2; ++n) _Pragma("unroll") for (int k = 0; k < 2; ++k) \
;         acc[ai][bj][m][n] = __builtin_amdgcn_mfma_f32_16x16x32_bf16(Bt[n][k], At[m][k], acc[ai][bj][m][n], 0, 0, 0); __builtin_amdgcn_s_setprio(0); } while (0)
; #define PG8_WAIT_V(n) asm volatile("s_waitcnt vmcnt(" #n ")" ::: "memory")
; #define PG8_WAIT_L(n) asm volatile("s_waitcnt lgkmcnt(" #n ")" ::: "memory")
; #define PG8_BAR __builtin_amdgcn_s_barrier()
; #define PG8_SCHED __builtin_amdgcn_sched_barrier(0)
; template <class Epi, class Sched, bool ALIGN_EPI = false, bool SP2 = false>
; __device__ __forceinline__ void gemm_phase(PG8_LAS unsigned char* lds, const Gemm g, const Sched& S, const Epi& E, int tid_in) {
;     ...
;             PG8_WAIT_V(8); PG8_WAIT_L(0); PG8_BAR; PG8_MMA(1, 0, At, B0); PG8_MMA(1, 1, At, B1); PG8_BAR; PG8_SCHED;
;             PG8_LDB(B0, 1, 0); PG8_LDB(B1, 1, 1); PG8_SCHED; PG8_LDA(At, 1, 0); PG8_STAGE(PG8_SA(0, 1), a2 + hstep, voffA);
;             PG8_WAIT_V(8); PG8_WAIT_L(0); PG8_BAR; PG8_MMA(0, 0, At, B0); PG8_MMA(0, 1, At, B1); PG8_BAR; PG8_SCHED;
	v_mfma_f32_16x16x32_bf16 v[28:31], v[128:131], v[188:191], 0
	v_mfma_f32_16x16x32_bf16 v[24:27], v[136:139], v[188:191], 0
	v_mfma_f32_16x16x32_bf16 v[20:23], v[128:131], v[196:199], 0
	v_mfma_f32_16x16x32_bf16 v[16:19], v[136:139], v[196:199], 0
	v_mfma_f32_16x16x32_bf16 v[12:15], v[128:131], v[204:207], 0
	v_mfma_f32_16x16x32_bf16 v[8:11], v[136:139], v[204:207], 0
	v_mfma_f32_16x16x32_bf16 v[4:7], v[128:131], v[212:215], 0
	v_mfma_f32_16x16x32_bf16 v[0:3], v[136:139], v[212:215], 0
	v_mfma_f32_16x16x32_bf16 v[28:31], v[132:135], v[192:195], v[28:31]
	v_mfma_f32_16x16x32_bf16 v[24:27], v[140:143], v[192:195], v[24:27]
	v_mfma_f32_16x16x32_bf16 v[20:23], v[132:135], v[200:203], v[20:23]
	v_mfma_f32_16x16x32_bf16 v[16:19], v[140:143], v[200:203], v[16:19]
	v_mfma_f32_16x16x32_bf16 v[12:15], v[132:135], v[208:211], v[12:15]
	v_mfma_f32_16x16x32_bf16 v[8:11], v[140:143], v[208:211], v[8:11]
	v_mfma_f32_16x16x32_bf16 v[4:7], v[132:135], v[216:219], v[4:7]
	v_mfma_f32_16x16x32_bf16 v[0:3], v[140:143], v[216:219], v[0:3]
	v_mfma_f32_16x16x32_bf16 v[92:95], v[166:169], v[188:191], 0
	v_mfma_f32_16x16x32_bf16 v[88:91], v[174:177], v[188:191], 0
	v_mfma_f32_16x16x32_bf16 v[84:87], v[166:169], v[196:199], 0
	v_mfma_f32_16x16x32_bf16 v[80:83], v[174:177], v[196:199], 0
	v_mfma_f32_16x16x32_bf16 v[76:79], v[166:169], v[204:207], 0
	v_mfma_f32_16x16x32_bf16 v[72:75], v[174:177], v[204:207], 0
	v_mfma_f32_16x16x32_bf16 v[64:67], v[166:169], v[212:215], 0
	v_mfma_f32_16x16x32_bf16 v[60:63], v[174:177], v[212:215], 0
	v_mfma_f32_16x16x32_bf16 v[92:95], v[170:173], v[192:195], v[92:95]
	v_mfma_f32_16x16x32_bf16 v[88:91], v[184:187], v[192:195], v[88:91]
	v_mfma_f32_16x16x32_bf16 v[84:87], v[170:173], v[200:203], v[84:87]
	v_mfma_f32_16x16x32_bf16 v[80:83], v[184:187], v[200:203], v[80:83]
	v_mfma_f32_16x16x32_bf16 v[76:79], v[170:173], v[208:211], v[76:79]
	v_mfma_f32_16x16x32_bf16 v[72:75], v[184:187], v[208:211], v[72:75]
	v_mfma_f32_16x16x32_bf16 v[64:67], v[170:173], v[216:219], v[64:67]
	v_mfma_f32_16x16x32_bf16 v[60:63], v[184:187], v[216:219], v[60:63]
	s_barrier
	s_add_i32 s53, 0, 0x18000
	s_add_i32 s88, 0, 0x1c000
	s_add_u32 s50, s50, 0x40000
	s_addc_u32 s51, s51, 0
	s_mov_b32 m0, s61
	s_nop 0
	global_load_lds_dwordx4 v144, s[50:51]
	s_mov_b32 m0, s62
	s_nop 0
	global_load_lds_dwordx4 v148, s[50:51]
	v_add_u32_e32 v140, s53, v179
	v_add_u32_e32 v184, s88, v179
	ds_read_b128 v[128:131], v140
	ds_read_b128 v[132:135], v140 offset:1024
	ds_read_b128 v[136:139], v140 offset:2048
	ds_read_b128 v[140:143], v140 offset:3072
	ds_read_b128 v[166:169], v184
	ds_read_b128 v[170:173], v184 offset:1024
	ds_read_b128 v[174:177], v184 offset:2048
	ds_read_b128 v[184:187], v184 offset:3072
	ds_read_b128 v[188:191], v182 offset:32768
	ds_read_b128 v[192:195], v182 offset:33792
	ds_read_b128 v[196:199], v182 offset:34816
	ds_read_b128 v[200:203], v182 offset:35840
	ds_read_b128 v[204:207], v182 offset:36864
	ds_read_b128 v[208:211], v182 offset:37888
	ds_read_b128 v[212:215], v182 offset:38912
	ds_read_b128 v[216:219], v182 offset:39936
	s_waitcnt vmcnt(8)
	s_waitcnt lgkmcnt(0)
	s_barrier
	v_mfma_f32_16x16x32_bf16 v[68:71], v[128:131], v[188:191], v[68:71]
	v_mfma_f32_16x16x32_bf16 v[56:59], v[136:139], v[188:191], v[56:59]
	v_mfma_f32_16x16x32_bf16 v[52:55], v[128:131], v[196:199], v[52:55]
	v_mfma_f32_16x16x32_bf16 v[48:51], v[136:139], v[196:199], v[48:51]
	v_mfma_f32_16x16x32_bf16 v[44:47], v[128:131], v[204:207], v[44:47]
	v_mfma_f32_16x16x32_bf16 v[40:43], v[136:139], v[204:207], v[40:43]
	v_mfma_f32_16x16x32_bf16 v[36:39], v[128:131], v[212:215], v[36:39]
	v_mfma_f32_16x16x32_bf16 v[32:35], v[136:139], v[212:215], v[32:35]
	v_mfma_f32_16x16x32_bf16 v[68:71], v[132:135], v[192:195], v[68:71]
	v_mfma_f32_16x16x32_bf16 v[56:59], v[140:143], v[192:195], v[56:59]
	v_mfma_f32_16x16x32_bf16 v[52:55], v[132:135], v[200:203], v[52:55]
	v_mfma_f32_16x16x32_bf16 v[48:51], v[140:143], v[200:203], v[48:51]
	v_mfma_f32_16x16x32_bf16 v[44:47], v[132:135], v[208:211], v[44:47]
	v_mfma_f32_16x16x32_bf16 v[40:43], v[140:143], v[208:211], v[40:43]
	v_mfma_f32_16x16x32_bf16 v[36:39], v[132:135], v[216:219], v[36:39]
	v_mfma_f32_16x16x32_bf16 v[32:35], v[140:143], v[216:219], v[32:35]
	v_mfma_f32_16x16x32_bf16 v[124:127], v[166:169], v[188:191], v[124:127]
	v_mfma_f32_16x16x32_bf16 v[120:123], v[174:177], v[188:191], v[120:123]
	v_mfma_f32_16x16x32_bf16 v[116:119], v[166:169], v[196:199], v[116:119]
	v_mfma_f32_16x16x32_bf16 v[112:115], v[174:177], v[196:199], v[112:115]
	v_mfma_f32_16x16x32_bf16 v[108:111], v[166:169], v[204:207], v[108:111]
	v_mfma_f32_16x16x32_bf16 v[104:107], v[174:177], v[204:207], v[104:107]
	v_mfma_f32_16x16x32_bf16 v[100:103], v[166:169], v[212:215], v[100:103]
	v_mfma_f32_16x16x32_bf16 v[96:99], v[174:177], v[212:215], v[96:99]
	v_mfma_f32_16x16x32_bf16 v[124:127], v[170:173], v[192:195], v[124:127]
	v_mfma_f32_16x16x32_bf16 v[120:123], v[184:187], v[192:195], v[120:123]
	v_mfma_f32_16x16x32_bf16 v[116:119], v[170:173], v[200:203], v[116:119]
	v_mfma_f32_16x16x32_bf16 v[112:115], v[184:187], v[200:203], v[112:115]
	v_mfma_f32_16x16x32_bf16 v[108:111], v[170:173], v[208:211], v[108:111]
	v_mfma_f32_16x16x32_bf16 v[104:107], v[184:187], v[208:211], v[104:107]
	v_mfma_f32_16x16x32_bf16 v[100:103], v[170:173], v[216:219], v[100:103]
	v_mfma_f32_16x16x32_bf16 v[96:99], v[184:187], v[216:219], v[96:99]
	s_barrier
; #define PG8_STAGE(bufoff, gbase, voff) do { _Pragma("unroll") for (int _i = 0; _i < 2; ++_i) \
;         __builtin_amdgcn_global_load_lds((const unsigned*)((const char*)(gbase) + (voff)[_i]), (PG8_LAS unsigned*)(lds + (bufoff) + ldsw + _i * 8192), 16, 0, 0); } while (0)
; #define PG8_LDA(dst, b, h) do { _Pragma("unroll") for (int m = 0; m < 4; ++m) _Pragma("unroll") for (int k = 0; k < 2; ++k) dst[m][k] = *(const PG8_LAS bf16x8*)(lds + PG8_SA(b, h) + aoff + m * 2048 + k * 1024); } while (0)
; #define PG8_LDB(dst, b, h) do { _Pragma("unroll") for (int n = 0; n < 2; ++n) _Pragma("unroll") for (int k = 0; k < 2; ++k) dst[n][k] = *(const PG8_LAS bf16x8*)(lds + PG8_SB(b, h) + boff + n * 2048 + k * 1024); } while (0)
; #define PG8_MMA(ai, bj, At, Bt) do { __builtin_amdgcn_s_setprio(1); _Pragma("unroll") for (int m = 0; m < 4; ++m) _Pragma("unroll") for (int n = 0; n < 2; ++n) _Pragma("unroll") for (int k = 0; k < 2; ++k) \
;         acc[ai][bj][m][n] = __builtin_amdgcn_mfma_f32_16x16x32_bf16(Bt[n][k], At[m][k], acc[ai][bj][m][n], 0, 0, 0); __builtin_amdgcn_s_setprio(0); } while (0)
; #define PG8_WAIT_V(n) asm volatile("s_waitcnt vmcnt(" #n ")" ::: "memory")
; #define PG8_WAIT_L(n) asm volatile("s_waitcnt lgkmcnt(" #n ")" ::: "memory")
; #define PG8_BAR __builtin_amdgcn_s_barrier()
; template <class Epi, class Sched, bool ALIGN_EPI = false, bool SP2 = false>
; __device__ __forceinline__ void gemm_phase(PG8_LAS unsigned char* lds, const Gemm g, const Sched& S, const Epi& E, int tid_in) {
;     ...
;             const char* a1 = cA + (size_t)(t + 1) * kstep;
;             const char* a2 = last ? nA : cA + (size_t)(t + 2) * kstep; const char* b2 = last ? nB : cB + (size_t)(t + 2) * kstep;
;             const char* a3 = a2 + kstep; const char* b3 = b2 + kstep;
;             if (last && has_next) S.a_ready(nxt);
;             if constexpr (SP2) {
;             PG8_LDB(B0, 0, 0); PG8_LDB(B1, 0, 1); PG8_SCHED; PG8_LDA(At, 0, 0); PG8_STAGE(PG8_SA(1, 1), a1 + hstep, voffA);
;             PG8_WAIT_V(8); PG8_WAIT_L(0); PG8_BAR; PG8_MMA(0, 0, At, B0); PG8_MMA(0, 1, At, B1); PG8_BAR; PG8_SCHED;
;     ...
;             PG8_LDA(At, 1, 1); PG8_STAGE(PG8_SB(1, 0), b3, voffB); PG8_STAGE(PG8_SB(1, 1), b3 + hstep, voffB); PG8_STAGE(PG8_SA(1, 0), a3, voffA);
;             PG8_WAIT_V(8); PG8_WAIT_L(0); PG8_BAR; PG8_MMA(1, 0, At, B0); PG8_MMA(1, 1, At, B1); PG8_BAR; PG8_SCHED;
	s_add_i32 s50, s53, s29
	s_mov_b32 m0, s50
	ds_read_b128 v[188:191], v182 offset:49152
	global_load_lds_dwordx4 v146, s[98:99]
	s_add_i32 m0, s50, 0x2000
	s_add_u32 s48, s48, 0x40080
	s_addc_u32 s49, s49, 0
	s_add_i32 s50, s88, s29
	global_load_lds_dwordx4 v150, s[98:99]
	s_mov_b32 m0, s50
	ds_read_b128 v[192:195], v182 offset:50176
	global_load_lds_dwordx4 v146, s[48:49]
	s_add_i32 m0, s50, 0x2000
	ds_read_b128 v[196:199], v182 offset:51200
	global_load_lds_dwordx4 v150, s[48:49]
	s_mov_b32 m0, s63
	ds_read_b128 v[200:203], v182 offset:52224
	global_load_lds_dwordx4 v144, s[100:101]
	s_mov_b32 m0, s64
	ds_read_b128 v[204:207], v182 offset:53248
	global_load_lds_dwordx4 v148, s[100:101]
	ds_read_b128 v[208:211], v182 offset:54272
	ds_read_b128 v[212:215], v182 offset:55296
	ds_read_b128 v[216:219], v182 offset:56320
	s_waitcnt vmcnt(8)
	s_waitcnt lgkmcnt(0)
	s_barrier
	v_mfma_f32_16x16x32_bf16 v[28:31], v[128:131], v[188:191], v[28:31]
	v_mfma_f32_16x16x32_bf16 v[24:27], v[136:139], v[188:191], v[24:27]
	v_mfma_f32_16x16x32_bf16 v[20:23], v[128:131], v[196:199], v[20:23]
	v_mfma_f32_16x16x32_bf16 v[16:19], v[136:139], v[196:199], v[16:19]
	v_mfma_f32_16x16x32_bf16 v[12:15], v[128:131], v[204:207], v[12:15]
	v_mfma_f32_16x16x32_bf16 v[8:11], v[136:139], v[204:207], v[8:11]
	v_mfma_f32_16x16x32_bf16 v[4:7], v[128:131], v[212:215], v[4:7]
	v_mfma_f32_16x16x32_bf16 v[0:3], v[136:139], v[212:215], v[0:3]
	v_mfma_f32_16x16x32_bf16 v[28:31], v[132:135], v[192:195], v[28:31]
	v_mfma_f32_16x16x32_bf16 v[24:27], v[140:143], v[192:195], v[24:27]
	v_mfma_f32_16x16x32_bf16 v[20:23], v[132:135], v[200:203], v[20:23]
	v_mfma_f32_16x16x32_bf16 v[16:19], v[140:143], v[200:203], v[16:19]
	v_mfma_f32_16x16x32_bf16 v[12:15], v[132:135], v[208:211], v[12:15]
	v_mfma_f32_16x16x32_bf16 v[8:11], v[140:143], v[208:211], v[8:11]
	v_mfma_f32_16x16x32_bf16 v[4:7], v[132:135], v[216:219], v[4:7]
	v_mfma_f32_16x16x32_bf16 v[0:3], v[140:143], v[216:219], v[0:3]
	v_mfma_f32_16x16x32_bf16 v[92:95], v[166:169], v[188:191], v[92:95]
	v_mfma_f32_16x16x32_bf16 v[88:91], v[174:177], v[188:191], v[88:91]
	v_mfma_f32_16x16x32_bf16 v[84:87], v[166:169], v[196:199], v[84:87]
	v_mfma_f32_16x16x32_bf16 v[80:83], v[174:177], v[196:199], v[80:83]
	v_mfma_f32_16x16x32_bf16 v[76:79], v[166:169], v[204:207], v[76:79]
	v_mfma_f32_16x16x32_bf16 v[72:75], v[174:177], v[204:207], v[72:75]
	v_mfma_f32_16x16x32_bf16 v[64:67], v[166:169], v[212:215], v[64:67]
	v_mfma_f32_16x16x32_bf16 v[60:63], v[174:177], v[212:215], v[60:63]
	v_mfma_f32_16x16x32_bf16 v[92:95], v[170:173], v[192:195], v[92:95]
	v_mfma_f32_16x16x32_bf16 v[88:91], v[184:187], v[192:195], v[88:91]
	v_mfma_f32_16x16x32_bf16 v[84:87], v[170:173], v[200:203], v[84:87]
	v_mfma_f32_16x16x32_bf16 v[80:83], v[184:187], v[200:203], v[80:83]
	v_mfma_f32_16x16x32_bf16 v[76:79], v[170:173], v[208:211], v[76:79]
	v_mfma_f32_16x16x32_bf16 v[72:75], v[184:187], v[208:211], v[72:75]
	v_mfma_f32_16x16x32_bf16 v[64:67], v[170:173], v[216:219], v[64:67]
	v_mfma_f32_16x16x32_bf16 v[60:63], v[184:187], v[216:219], v[60:63]
	s_barrier
	s_add_i32 s52, s52, 2
	s_add_u32 s46, s46, 0x100
	s_addc_u32 s47, s47, 0
	s_add_u32 s35, s35, 0x100
	s_addc_u32 s45, s45, 0
	v_readlane_b32 s98, v248, 0
	s_nop 3
	s_cmp_ge_u32 s98, 0x100
	s_cbranch_scc0 .Lgprio_skip_2
	s_setprio 1
.Lgprio_skip_2:
.LBB0_564:
	s_add_u32 s48, s46, 0xfffc0080
	s_addc_u32 s49, s47, -1
	s_cmp_eq_u32 s52, 12
	s_cselect_b32 s51, s0, s49
	s_cselect_b32 s50, s1, s48
	s_cselect_b32 s49, s7, s45
	s_cselect_b32 s48, s31, s35
	s_add_i32 m0, s59, 0xc000
	ds_read_b128 v[128:131], v180
	global_load_lds_dwordx4 v158, s[46:47]
	s_add_i32 m0, s59, 0xe000
	ds_read_b128 v[132:135], v180 offset:1024
	global_load_lds_dwordx4 v160, s[46:47]
	ds_read_b128 v[136:139], v180 offset:2048
	ds_read_b128 v[140:143], v180 offset:3072
	ds_read_b128 v[166:169], v181
	ds_read_b128 v[170:173], v181 offset:1024
	ds_read_b128 v[174:177], v181 offset:2048
	ds_read_b128 v[184:187], v181 offset:3072
	ds_read_b128 v[188:191], v182
	ds_read_b128 v[192:195], v182 offset:1024
	ds_read_b128 v[196:199], v182 offset:2048
	ds_read_b128 v[200:203], v182 offset:3072
	ds_read_b128 v[204:207], v182 offset:4096
	ds_read_b128 v[208:211], v182 offset:5120
	ds_read_b128 v[212:215], v182 offset:6144
	ds_read_b128 v[216:219], v182 offset:7168
	s_waitcnt vmcnt(8)
	s_waitcnt lgkmcnt(0)
	s_barrier
	v_mfma_f32_16x16x32_bf16 v[68:71], v[128:131], v[188:191], v[68:71]
	v_mfma_f32_16x16x32_bf16 v[56:59], v[136:139], v[188:191], v[56:59]
	v_mfma_f32_16x16x32_bf16 v[52:55], v[128:131], v[196:199], v[52:55]
	v_mfma_f32_16x16x32_bf16 v[48:51], v[136:139], v[196:199], v[48:51]
	v_mfma_f32_16x16x32_bf16 v[44:47], v[128:131], v[204:207], v[44:47]
	v_mfma_f32_16x16x32_bf16 v[40:43], v[136:139], v[204:207], v[40:43]
	v_mfma_f32_16x16x32_bf16 v[36:39], v[128:131], v[212:215], v[36:39]
	v_mfma_f32_16x16x32_bf16 v[32:35], v[136:139], v[212:215], v[32:35]
	v_mfma_f32_16x16x32_bf16 v[68:71], v[132:135], v[192:195], v[68:71]
	v_mfma_f32_16x16x32_bf16 v[56:59], v[140:143], v[192:195], v[56:59]
	v_mfma_f32_16x16x32_bf16 v[52:55], v[132:135], v[200:203], v[52:55]
	v_mfma_f32_16x16x32_bf16 v[48:51], v[140:143], v[200:203], v[48:51]
	v_mfma_f32_16x16x32_bf16 v[44:47], v[132:135], v[208:211], v[44:47]
	v_mfma_f32_16x16x32_bf16 v[40:43], v[140:143], v[208:211], v[40:43]
	v_mfma_f32_16x16x32_bf16 v[36:39], v[132:135], v[216:219], v[36:39]
	v_mfma_f32_16x16x32_bf16 v[32:35], v[140:143], v[216:219], v[32:35]
	v_mfma_f32_16x16x32_bf16 v[124:127], v[166:169], v[188:191], v[124:127]
	v_mfma_f32_16x16x32_bf16 v[120:123], v[174:177], v[188:191], v[120:123]
	v_mfma_f32_16x16x32_bf16 v[116:119], v[166:169], v[196:199], v[116:119]
	v_mfma_f32_16x16x32_bf16 v[112:115], v[174:177], v[196:199], v[112:115]
	v_mfma_f32_16x16x32_bf16 v[108:111], v[166:169], v[204:207], v[108:111]
	v_mfma_f32_16x16x32_bf16 v[104:107], v[174:177], v[204:207], v[104:107]
	v_mfma_f32_16x16x32_bf16 v[100:103], v[166:169], v[212:215], v[100:103]
	v_mfma_f32_16x16x32_bf16 v[96:99], v[174:177], v[212:215], v[96:99]
	v_mfma_f32_16x16x32_bf16 v[124:127], v[170:173], v[192:195], v[124:127]
	v_mfma_f32_16x16x32_bf16 v[120:123], v[184:187], v[192:195], v[120:123]
	v_mfma_f32_16x16x32_bf16 v[116:119], v[170:173], v[200:203], v[116:119]
	v_mfma_f32_16x16x32_bf16 v[112:115], v[184:187], v[200:203], v[112:115]
	v_mfma_f32_16x16x32_bf16 v[108:111], v[170:173], v[208:211], v[108:111]
	v_mfma_f32_16x16x32_bf16 v[104:107], v[184:187], v[208:211], v[104:107]
	v_mfma_f32_16x16x32_bf16 v[100:103], v[170:173], v[216:219], v[100:103]
	v_mfma_f32_16x16x32_bf16 v[96:99], v[184:187], v[216:219], v[96:99]
	s_barrier
; #define PG8_STAGE(bufoff, gbase, voff) do { _Pragma("unroll") for (int _i = 0; _i < 2; ++_i) \
;         __builtin_amdgcn_global_load_lds((const unsigned*)((const char*)(gbase) + (voff)[_i]), (PG8_LAS unsigned*)(lds + (bufoff) + ldsw + _i * 8192), 16, 0, 0); } while (0)
; #define PG8_LDA(dst, b, h) do { _Pragma("unroll") for (int m = 0; m < 4; ++m) _Pragma("unroll") for (int k = 0; k < 2; ++k) dst[m][k] = *(const PG8_LAS bf16x8*)(lds + PG8_SA(b, h) + aoff + m * 2048 + k * 1024); } while (0)
; #define PG8_LDB(dst, b, h) do { _Pragma("unroll") for (int n = 0; n < 2; ++n) _Pragma("unroll") for (int k = 0; k < 2; ++k) dst[n][k] = *(const PG8_LAS bf16x8*)(lds + PG8_SB(b, h) + boff + n * 2048 + k * 1024); } while (0)
; #define PG8_MMA(ai, bj, At, Bt) do { __builtin_amdgcn_s_setprio(1); _Pragma("unroll") for (int m = 0; m < 4; ++m) _Pragma("unroll") for (int n = 0; n < 2; ++n) _Pragma("unroll") for (int k = 0; k < 2; ++k) \
;         acc[ai][bj][m][n] = __builtin_amdgcn_mfma_f32_16x16x32_bf16(Bt[n][k], At[m][k], acc[ai][bj][m][n], 0, 0, 0); __builtin_amdgcn_s_setprio(0); } while (0)
; #define PG8_WAIT_V(n) asm volatile("s_waitcnt vmcnt(" #n ")" ::: "memory")
; #define PG8_WAIT_L(n) asm volatile("s_waitcnt lgkmcnt(" #n ")" ::: "memory")
; #define PG8_BAR __builtin_amdgcn_s_barrier()
; #define PG8_SCHED __builtin_amdgcn_sched_barrier(0)
; template <class Epi, class Sched, bool ALIGN_EPI = false, bool SP2 = false>
; __device__ __forceinline__ void gemm_phase(PG8_LAS unsigned char* lds, const Gemm g, const Sched& S, const Epi& E, int tid_in) {
;     ...
;             PG8_LDA(At, 0, 1); PG8_STAGE(PG8_SB(0, 0), b2, voffB); PG8_STAGE(PG8_SB(0, 1), b2 + hstep, voffB); PG8_STAGE(PG8_SA(0, 0), a2, voffA);
;             PG8_WAIT_V(8); PG8_WAIT_L(0); PG8_BAR; PG8_MMA(1, 0, At, B0); PG8_MMA(1, 1, At, B1); PG8_BAR; PG8_SCHED;
;             PG8_LDB(B0, 1, 0); PG8_LDB(B1, 1, 1); PG8_SCHED; PG8_LDA(At, 1, 0); PG8_STAGE(PG8_SA(0, 1), a2 + hstep, voffA);
	s_add_u32 s98, s48, s14
	s_addc_u32 s99, s49, s15
	s_add_u32 s100, s50, s14
	s_addc_u32 s101, s51, s15
	s_add_i32 s53, s77, s29
	s_mov_b32 m0, s53
	ds_read_b128 v[188:191], v182 offset:16384
	global_load_lds_dwordx4 v146, s[48:49]
	s_add_i32 m0, s53, 0x2000
	s_add_u32 s88, s48, 0x40000
	s_addc_u32 s89, s49, 0
	s_add_i32 s53, s78, s29
	global_load_lds_dwordx4 v150, s[48:49]
	s_mov_b32 m0, s53
	ds_read_b128 v[192:195], v182 offset:17408
	global_load_lds_dwordx4 v146, s[88:89]
	s_add_i32 m0, s53, 0x2000
	ds_read_b128 v[196:199], v182 offset:18432
	global_load_lds_dwordx4 v150, s[88:89]
	s_mov_b32 m0, s59
	ds_read_b128 v[200:203], v182 offset:19456
	global_load_lds_dwordx4 v144, s[50:51]
	s_mov_b32 m0, s60
	ds_read_b128 v[204:207], v182 offset:20480
	global_load_lds_dwordx4 v148, s[50:51]
	ds_read_b128 v[208:211], v182 offset:21504
	ds_read_b128 v[212:215], v182 offset:22528
	ds_read_b128 v[216:219], v182 offset:23552
	s_waitcnt vmcnt(8)
	s_waitcnt lgkmcnt(0)
	s_barrier
	v_mfma_f32_16x16x32_bf16 v[28:31], v[128:131], v[188:191], v[28:31]
	v_mfma_f32_16x16x32_bf16 v[24:27], v[136:139], v[188:191], v[24:27]
	v_mfma_f32_16x16x32_bf16 v[20:23], v[128:131], v[196:199], v[20:23]
	v_mfma_f32_16x16x32_bf16 v[16:19], v[136:139], v[196:199], v[16:19]
	v_mfma_f32_16x16x32_bf16 v[12:15], v[128:131], v[204:207], v[12:15]
	v_mfma_f32_16x16x32_bf16 v[8:11], v[136:139], v[204:207], v[8:11]
	v_mfma_f32_16x16x32_bf16 v[4:7], v[128:131], v[212:215], v[4:7]
	v_mfma_f32_16x16x32_bf16 v[0:3], v[136:139], v[212:215], v[0:3]
	v_mfma_f32_16x16x32_bf16 v[28:31], v[132:135], v[192:195], v[28:31]
	v_mfma_f32_16x16x32_bf16 v[24:27], v[140:143], v[192:195], v[24:27]
	v_mfma_f32_16x16x32_bf16 v[20:23], v[132:135], v[200:203], v[20:23]
	v_mfma_f32_16x16x32_bf16 v[16:19], v[140:143], v[200:203], v[16:19]
	v_mfma_f32_16x16x32_bf16 v[12:15], v[132:135], v[208:211], v[12:15]
	v_mfma_f32_16x16x32_bf16 v[8:11], v[140:143], v[208:211], v[8:11]
	v_mfma_f32_16x16x32_bf16 v[4:7], v[132:135], v[216:219], v[4:7]
	v_mfma_f32_16x16x32_bf16 v[0:3], v[140:143], v[216:219], v[0:3]
	v_mfma_f32_16x16x32_bf16 v[92:95], v[166:169], v[188:191], v[92:95]
	v_mfma_f32_16x16x32_bf16 v[88:91], v[174:177], v[188:191], v[88:91]
	v_mfma_f32_16x16x32_bf16 v[84:87], v[166:169], v[196:199], v[84:87]
	v_mfma_f32_16x16x32_bf16 v[80:83], v[174:177], v[196:199], v[80:83]
	v_mfma_f32_16x16x32_bf16 v[76:79], v[166:169], v[204:207], v[76:79]
	v_mfma_f32_16x16x32_bf16 v[72:75], v[174:177], v[204:207], v[72:75]
	v_mfma_f32_16x16x32_bf16 v[64:67], v[166:169], v[212:215], v[64:67]
	v_mfma_f32_16x16x32_bf16 v[60:63], v[174:177], v[212:215], v[60:63]
	v_mfma_f32_16x16x32_bf16 v[92:95], v[170:173], v[192:195], v[92:95]
	v_mfma_f32_16x16x32_bf16 v[88:91], v[184:187], v[192:195], v[88:91]
	v_mfma_f32_16x16x32_bf16 v[84:87], v[170:173], v[200:203], v[84:87]
	v_mfma_f32_16x16x32_bf16 v[80:83], v[184:187], v[200:203], v[80:83]
	v_mfma_f32_16x16x32_bf16 v[76:79], v[170:173], v[208:211], v[76:79]
	v_mfma_f32_16x16x32_bf16 v[72:75], v[184:187], v[208:211], v[72:75]
	v_mfma_f32_16x16x32_bf16 v[64:67], v[170:173], v[216:219], v[64:67]
	v_mfma_f32_16x16x32_bf16 v[60:63], v[184:187], v[216:219], v[60:63]
	s_barrier
	s_add_i32 s53, 0, 0x18000
	s_add_i32 s88, 0, 0x1c000
	s_add_u32 s50, s50, 0x40000
	s_addc_u32 s51, s51, 0
	s_mov_b32 m0, s61
	s_nop 0
	global_load_lds_dwordx4 v144, s[50:51]
	s_mov_b32 m0, s62
	s_nop 0
	global_load_lds_dwordx4 v148, s[50:51]
	v_add_u32_e32 v140, s53, v179
	v_add_u32_e32 v184, s88, v179
	ds_read_b128 v[128:131], v140
	ds_read_b128 v[132:135], v140 offset:1024
	ds_read_b128 v[136:139], v140 offset:2048
	ds_read_b128 v[140:143], v140 offset:3072
	ds_read_b128 v[166:169], v184
	ds_read_b128 v[170:173], v184 offset:1024
	ds_read_b128 v[174:177], v184 offset:2048
	ds_read_b128 v[184:187], v184 offset:3072
	ds_read_b128 v[188:191], v182 offset:32768
	ds_read_b128 v[192:195], v182 offset:33792
	ds_read_b128 v[196:199], v182 offset:34816
	ds_read_b128 v[200:203], v182 offset:35840
	ds_read_b128 v[204:207], v182 offset:36864
	ds_read_b128 v[208:211], v182 offset:37888
	ds_read_b128 v[212:215], v182 offset:38912
	ds_read_b128 v[216:219], v182 offset:39936
	s_waitcnt vmcnt(8)
	s_waitcnt lgkmcnt(0)
	s_barrier
; #define PG8_STAGE(bufoff, gbase, voff) do { _Pragma("unroll") for (int _i = 0; _i < 2; ++_i) \
;         __builtin_amdgcn_global_load_lds((const unsigned*)((const char*)(gbase) + (voff)[_i]), (PG8_LAS unsigned*)(lds + (bufoff) + ldsw + _i * 8192), 16, 0, 0); } while (0)
; #define PG8_LDA(dst, b, h) do { _Pragma("unroll") for (int m = 0; m < 4; ++m) _Pragma("unroll") for (int k = 0; k < 2; ++k) dst[m][k] = *(const PG8_LAS bf16x8*)(lds + PG8_SA(b, h) + aoff + m * 2048 + k * 1024); } while (0)
; #define PG8_MMA(ai, bj, At, Bt) do { __builtin_amdgcn_s_setprio(1); _Pragma("unroll") for (int m = 0; m < 4; ++m) _Pragma("unroll") for (int n = 0; n < 2; ++n) _Pragma("unroll") for (int k = 0; k < 2; ++k) \
;         acc[ai][bj][m][n] = __builtin_amdgcn_mfma_f32_16x16x32_bf16(Bt[n][k], At[m][k], acc[ai][bj][m][n], 0, 0, 0); __builtin_amdgcn_s_setprio(0); } while (0)
; #define PG8_WAIT_V(n) asm volatile("s_waitcnt vmcnt(" #n ")" ::: "memory")
; #define PG8_WAIT_L(n) asm volatile("s_waitcnt lgkmcnt(" #n ")" ::: "memory")
; #define PG8_BAR __builtin_amdgcn_s_barrier()
; #define PG8_SCHED __builtin_amdgcn_sched_barrier(0)
; template <class Epi, class Sched, bool ALIGN_EPI = false, bool SP2 = false>
; __device__ __forceinline__ void gemm_phase(PG8_LAS unsigned char* lds, const Gemm g, const Sched& S, const Epi& E, int tid_in) {
;     ...
;             PG8_WAIT_V(8); PG8_WAIT_L(0); PG8_BAR; PG8_MMA(0, 0, At, B0); PG8_MMA(0, 1, At, B1); PG8_BAR; PG8_SCHED;
;             PG8_LDA(At, 1, 1); PG8_STAGE(PG8_SB(1, 0), b3, voffB); PG8_STAGE(PG8_SB(1, 1), b3 + hstep, voffB); PG8_STAGE(PG8_SA(1, 0), a3, voffA);
;             PG8_WAIT_V(8); PG8_WAIT_L(0); PG8_BAR; PG8_MMA(1, 0, At, B0); PG8_MMA(1, 1, At, B1); PG8_BAR; PG8_SCHED;
;     ...
;         if constexpr (ALIGN_EPI) { if (wr == 0) PG8_BAR; }
	v_mfma_f32_16x16x32_bf16 v[68:71], v[128:131], v[188:191], v[68:71]
	v_mfma_f32_16x16x32_bf16 v[56:59], v[136:139], v[188:191], v[56:59]
	v_mfma_f32_16x16x32_bf16 v[52:55], v[128:131], v[196:199], v[52:55]
	v_mfma_f32_16x16x32_bf16 v[48:51], v[136:139], v[196:199], v[48:51]
	v_mfma_f32_16x16x32_bf16 v[44:47], v[128:131], v[204:207], v[44:47]
	v_mfma_f32_16x16x32_bf16 v[40:43], v[136:139], v[204:207], v[40:43]
	v_mfma_f32_16x16x32_bf16 v[36:39], v[128:131], v[212:215], v[36:39]
	v_mfma_f32_16x16x32_bf16 v[32:35], v[136:139], v[212:215], v[32:35]
	v_mfma_f32_16x16x32_bf16 v[68:71], v[132:135], v[192:195], v[68:71]
	v_mfma_f32_16x16x32_bf16 v[56:59], v[140:143], v[192:195], v[56:59]
	v_mfma_f32_16x16x32_bf16 v[52:55], v[132:135], v[200:203], v[52:55]
	v_mfma_f32_16x16x32_bf16 v[48:51], v[140:143], v[200:203], v[48:51]
	v_mfma_f32_16x16x32_bf16 v[44:47], v[132:135], v[208:211], v[44:47]
	v_mfma_f32_16x16x32_bf16 v[40:43], v[140:143], v[208:211], v[40:43]
	v_mfma_f32_16x16x32_bf16 v[36:39], v[132:135], v[216:219], v[36:39]
	v_mfma_f32_16x16x32_bf16 v[32:35], v[140:143], v[216:219], v[32:35]
	v_mfma_f32_16x16x32_bf16 v[124:127], v[166:169], v[188:191], v[124:127]
	v_mfma_f32_16x16x32_bf16 v[120:123], v[174:177], v[188:191], v[120:123]
	v_mfma_f32_16x16x32_bf16 v[116:119], v[166:169], v[196:199], v[116:119]
	v_mfma_f32_16x16x32_bf16 v[112:115], v[174:177], v[196:199], v[112:115]
	v_mfma_f32_16x16x32_bf16 v[108:111], v[166:169], v[204:207], v[108:111]
	v_mfma_f32_16x16x32_bf16 v[104:107], v[174:177], v[204:207], v[104:107]
	v_mfma_f32_16x16x32_bf16 v[100:103], v[166:169], v[212:215], v[100:103]
	v_mfma_f32_16x16x32_bf16 v[96:99], v[174:177], v[212:215], v[96:99]
	v_mfma_f32_16x16x32_bf16 v[124:127], v[170:173], v[192:195], v[124:127]
	v_mfma_f32_16x16x32_bf16 v[120:123], v[184:187], v[192:195], v[120:123]
	v_mfma_f32_16x16x32_bf16 v[116:119], v[170:173], v[200:203], v[116:119]
	v_mfma_f32_16x16x32_bf16 v[112:115], v[184:187], v[200:203], v[112:115]
	v_mfma_f32_16x16x32_bf16 v[108:111], v[170:173], v[208:211], v[108:111]
	v_mfma_f32_16x16x32_bf16 v[104:107], v[184:187], v[208:211], v[104:107]
	v_mfma_f32_16x16x32_bf16 v[100:103], v[170:173], v[216:219], v[100:103]
	v_mfma_f32_16x16x32_bf16 v[96:99], v[184:187], v[216:219], v[96:99]
	s_barrier
	s_add_i32 s50, s53, s29
	s_mov_b32 m0, s50
	ds_read_b128 v[188:191], v182 offset:49152
	global_load_lds_dwordx4 v146, s[98:99]
	s_add_i32 m0, s50, 0x2000
	s_add_u32 s48, s48, 0x40080
	s_addc_u32 s49, s49, 0
	s_add_i32 s50, s88, s29
	global_load_lds_dwordx4 v150, s[98:99]
	s_mov_b32 m0, s50
	ds_read_b128 v[192:195], v182 offset:50176
	global_load_lds_dwordx4 v146, s[48:49]
	s_add_i32 m0, s50, 0x2000
	ds_read_b128 v[196:199], v182 offset:51200
	global_load_lds_dwordx4 v150, s[48:49]
	s_mov_b32 m0, s63
	ds_read_b128 v[200:203], v182 offset:52224
	global_load_lds_dwordx4 v144, s[100:101]
	s_mov_b32 m0, s64
	ds_read_b128 v[204:207], v182 offset:53248
	global_load_lds_dwordx4 v148, s[100:101]
	ds_read_b128 v[208:211], v182 offset:54272
	ds_read_b128 v[212:215], v182 offset:55296
	ds_read_b128 v[216:219], v182 offset:56320
	s_waitcnt vmcnt(8)
	s_waitcnt lgkmcnt(0)
	s_barrier
	v_mfma_f32_16x16x32_bf16 v[28:31], v[128:131], v[188:191], v[28:31]
	v_mfma_f32_16x16x32_bf16 v[24:27], v[136:139], v[188:191], v[24:27]
	v_mfma_f32_16x16x32_bf16 v[20:23], v[128:131], v[196:199], v[20:23]
	v_mfma_f32_16x16x32_bf16 v[16:19], v[136:139], v[196:199], v[16:19]
	v_mfma_f32_16x16x32_bf16 v[12:15], v[128:131], v[204:207], v[12:15]
	v_mfma_f32_16x16x32_bf16 v[8:11], v[136:139], v[204:207], v[8:11]
	v_mfma_f32_16x16x32_bf16 v[4:7], v[128:131], v[212:215], v[4:7]
	v_mfma_f32_16x16x32_bf16 v[0:3], v[136:139], v[212:215], v[0:3]
	v_mfma_f32_16x16x32_bf16 v[28:31], v[132:135], v[192:195], v[28:31]
	v_mfma_f32_16x16x32_bf16 v[24:27], v[140:143], v[192:195], v[24:27]
	v_mfma_f32_16x16x32_bf16 v[20:23], v[132:135], v[200:203], v[20:23]
	v_mfma_f32_16x16x32_bf16 v[16:19], v[140:143], v[200:203], v[16:19]
	v_mfma_f32_16x16x32_bf16 v[12:15], v[132:135], v[208:211], v[12:15]
	v_mfma_f32_16x16x32_bf16 v[8:11], v[140:143], v[208:211], v[8:11]
	v_mfma_f32_16x16x32_bf16 v[4:7], v[132:135], v[216:219], v[4:7]
	v_mfma_f32_16x16x32_bf16 v[0:3], v[140:143], v[216:219], v[0:3]
	v_mfma_f32_16x16x32_bf16 v[92:95], v[166:169], v[188:191], v[92:95]
	v_mfma_f32_16x16x32_bf16 v[88:91], v[174:177], v[188:191], v[88:91]
	v_mfma_f32_16x16x32_bf16 v[84:87], v[166:169], v[196:199], v[84:87]
	v_mfma_f32_16x16x32_bf16 v[80:83], v[174:177], v[196:199], v[80:83]
	v_mfma_f32_16x16x32_bf16 v[76:79], v[166:169], v[204:207], v[76:79]
	v_mfma_f32_16x16x32_bf16 v[72:75], v[174:177], v[204:207], v[72:75]
	v_mfma_f32_16x16x32_bf16 v[64:67], v[166:169], v[212:215], v[64:67]
	v_mfma_f32_16x16x32_bf16 v[60:63], v[174:177], v[212:215], v[60:63]
	v_mfma_f32_16x16x32_bf16 v[92:95], v[170:173], v[192:195], v[92:95]
	v_mfma_f32_16x16x32_bf16 v[88:91], v[184:187], v[192:195], v[88:91]
	v_mfma_f32_16x16x32_bf16 v[84:87], v[170:173], v[200:203], v[84:87]
	v_mfma_f32_16x16x32_bf16 v[80:83], v[184:187], v[200:203], v[80:83]
	v_mfma_f32_16x16x32_bf16 v[76:79], v[170:173], v[208:211], v[76:79]
	v_mfma_f32_16x16x32_bf16 v[72:75], v[184:187], v[208:211], v[72:75]
	v_mfma_f32_16x16x32_bf16 v[64:67], v[170:173], v[216:219], v[64:67]
	v_mfma_f32_16x16x32_bf16 v[60:63], v[184:187], v[216:219], v[60:63]
	s_barrier
	s_add_i32 s52, s52, 2
	s_add_u32 s46, s46, 0x100
	s_addc_u32 s47, s47, 0
	s_add_u32 s35, s35, 0x100
	s_addc_u32 s45, s45, 0
	s_cmp_gt_u32 s52, 13
	s_cbranch_scc0 .LBB0_564
	s_setprio 0
	s_cmp_eq_u32 s86, 1
	s_cbranch_scc0 .Lww_done_p3
	v_readlane_b32 s98, v248, 0
	s_nop 3
	s_cmp_eq_u32 s98, 0
	s_cbranch_scc0 .Lww_bar_p3
	v_readlane_b32 s98, v248, 32
	s_nop 3
	s_cmp_eq_u32 s98, 1
	s_cbranch_scc0 .Lww_bar_p3
	v_mov_b32_e32 v246, 0x3500
	s_mov_b32 s98, 0

; #define PG8_STAGE(bufoff, gbase, voff) do { _Pragma("unroll") for (int _i = 0; _i < 2; ++_i) \
;         __builtin_amdgcn_global_load_lds((const unsigned*)((const char*)(gbase) + (voff)[_i]), (PG8_LAS unsigned*)(lds + (bufoff) + ldsw + _i * 8192), 16, 0, 0); } while (0)
; #define PG8_LDA(dst, b, h) do { _Pragma("unroll") for (int m = 0; m < 4; ++m) _Pragma("unroll") for (int k = 0; k < 2; ++k) dst[m][k] = *(const PG8_LAS bf16x8*)(lds + PG8_SA(b, h) + aoff + m * 2048 + k * 1024); } while (0)
; #define PG8_LDB(dst, b, h) do { _Pragma("unroll") for (int n = 0; n < 2; ++n) _Pragma("unroll") for (int k = 0; k < 2; ++k) dst[n][k] = *(const PG8_LAS bf16x8*)(lds + PG8_SB(b, h) + boff + n * 2048 + k * 1024); } while (0)
; #define PG8_WAIT_V(n) asm volatile("s_waitcnt vmcnt(" #n ")" ::: "memory")
; #define PG8_WAIT_L(n) asm volatile("s_waitcnt lgkmcnt(" #n ")" ::: "memory")
; #define PG8_BAR __builtin_amdgcn_s_barrier()
; #define PG8_SCHED __builtin_amdgcn_sched_barrier(0)
; template <class Epi, class Sched, bool ALIGN_EPI = false, bool SP2 = false>
; __device__ __forceinline__ void gemm_phase(PG8_LAS unsigned char* lds, const Gemm g, const Sched& S, const Epi& E, int tid_in) {
;     ...
;         const bool has_next = S.next(ui + 1, nxt);
;         const char* nA = has_next ? (const char*)g.A + (size_t)nxt.pm * tstep : cA; const char* nB = has_next ? (const char*)g.Bt + (size_t)nxt.pn * tstep : cB;
;         for (int t = 0; t < nt; t += 2) {
;             if constexpr (Epi::MIDK) { if (t == Epi::MIDK_T) { if (wr == 0) PG8_BAR; E.mid(acc, cur, wr, wc, fr, fq); if (wr == 1) PG8_BAR; } }
;             const bool last = (t == nt - 2);
;             const char* a1 = cA + (size_t)(t + 1) * kstep;
;             const char* a2 = last ? nA : cA + (size_t)(t + 2) * kstep; const char* b2 = last ? nB : cB + (size_t)(t + 2) * kstep;
;             const char* a3 = a2 + kstep; const char* b3 = b2 + kstep;
;             if (last && has_next) S.a_ready(nxt);
;             if constexpr (SP2) {
;             PG8_LDB(B0, 0, 0); PG8_LDB(B1, 0, 1); PG8_SCHED; PG8_LDA(At, 0, 0); PG8_STAGE(PG8_SA(1, 1), a1 + hstep, voffA);
;             PG8_WAIT_V(8); PG8_WAIT_L(0); PG8_BAR; PG8_MMA(0, 0, At, B0); PG8_MMA(0, 1, At, B1); PG8_BAR; PG8_SCHED;
;             PG8_LDA(At, 0, 1); PG8_STAGE(PG8_SB(0, 0), b2, voffB); PG8_STAGE(PG8_SB(0, 1), b2 + hstep, voffB); PG8_STAGE(PG8_SA(0, 0), a2, voffA);
.LBB0_1147:
	s_ashr_i32 s23, s22, 31
	s_lshl_b64 s[24:25], s[22:23], 19
	s_add_u32 s24, s38, s24
	s_addc_u32 s25, s39, s25
	s_and_b64 s[26:27], s[4:5], exec
	s_cselect_b32 s23, s25, s31
	s_cselect_b32 s29, s24, s30
	s_ashr_i32 s21, s20, 31
	s_lshl_b64 s[26:27], s[20:21], 19
	s_add_u32 s26, s44, s26
	s_addc_u32 s27, s45, s27
	s_and_b64 s[36:37], s[4:5], exec
	s_cselect_b32 s21, s27, s35
	s_cselect_b32 s57, s26, s34
	s_add_u32 s30, s30, 0x40080
	s_addc_u32 s31, s31, 0
	s_add_u32 s58, s34, 0x100
	s_addc_u32 s59, s35, 0
	s_mov_b32 s60, -2
	s_waitcnt lgkmcnt(0)
	s_add_u32 s34, s30, 0xfffc0080
	s_addc_u32 s35, s31, -1
	s_cmp_eq_u32 s60, 12
	s_cselect_b32 s37, s23, s35
	s_cselect_b32 s36, s29, s34
	s_cselect_b32 s35, s21, s59
	s_cselect_b32 s34, s57, s58
	s_add_i32 m0, s1, 0xc000
	ds_read_b128 v[128:131], v191
	global_load_lds_dwordx4 v160, s[30:31]
	s_add_i32 m0, s1, 0xe000
	ds_read_b128 v[132:135], v191 offset:1024
	global_load_lds_dwordx4 v162, s[30:31]
	ds_read_b128 v[136:139], v191 offset:2048
	ds_read_b128 v[140:143], v191 offset:3072
	ds_read_b128 v[144:147], v192
	ds_read_b128 v[148:151], v192 offset:1024
	ds_read_b128 v[168:171], v192 offset:2048
	ds_read_b128 v[172:175], v192 offset:3072
	ds_read_b128 v[176:179], v193
	ds_read_b128 v[180:183], v193 offset:1024
	ds_read_b128 v[194:197], v193 offset:2048
	ds_read_b128 v[198:201], v193 offset:3072
	ds_read_b128 v[202:205], v193 offset:4096
	ds_read_b128 v[206:209], v193 offset:5120
	ds_read_b128 v[210:213], v193 offset:6144
	ds_read_b128 v[214:217], v193 offset:7168
	s_waitcnt vmcnt(8)
	s_waitcnt lgkmcnt(0)
	s_barrier
	v_mfma_f32_16x16x32_bf16 v[124:127], v[128:131], v[176:179], 0
	v_mfma_f32_16x16x32_bf16 v[120:123], v[136:139], v[176:179], 0
	v_mfma_f32_16x16x32_bf16 v[108:111], v[128:131], v[194:197], 0
	v_mfma_f32_16x16x32_bf16 v[104:107], v[136:139], v[194:197], 0
	v_mfma_f32_16x16x32_bf16 v[92:95], v[128:131], v[202:205], 0
	v_mfma_f32_16x16x32_bf16 v[88:91], v[136:139], v[202:205], 0
	v_mfma_f32_16x16x32_bf16 v[76:79], v[128:131], v[210:213], 0
	v_mfma_f32_16x16x32_bf16 v[72:75], v[136:139], v[210:213], 0
	v_mfma_f32_16x16x32_bf16 v[124:127], v[132:135], v[180:183], v[124:127]
	v_mfma_f32_16x16x32_bf16 v[120:123], v[140:143], v[180:183], v[120:123]
	v_mfma_f32_16x16x32_bf16 v[108:111], v[132:135], v[198:201], v[108:111]
	v_mfma_f32_16x16x32_bf16 v[104:107], v[140:143], v[198:201], v[104:107]
	v_mfma_f32_16x16x32_bf16 v[92:95], v[132:135], v[206:209], v[92:95]
	v_mfma_f32_16x16x32_bf16 v[88:91], v[140:143], v[206:209], v[88:91]
	v_mfma_f32_16x16x32_bf16 v[76:79], v[132:135], v[214:217], v[76:79]
	v_mfma_f32_16x16x32_bf16 v[72:75], v[140:143], v[214:217], v[72:75]
	v_mfma_f32_16x16x32_bf16 v[116:119], v[144:147], v[176:179], 0
	v_mfma_f32_16x16x32_bf16 v[112:115], v[168:171], v[176:179], 0
	v_mfma_f32_16x16x32_bf16 v[100:103], v[144:147], v[194:197], 0
	v_mfma_f32_16x16x32_bf16 v[96:99], v[168:171], v[194:197], 0
	v_mfma_f32_16x16x32_bf16 v[84:87], v[144:147], v[202:205], 0
	v_mfma_f32_16x16x32_bf16 v[80:83], v[168:171], v[202:205], 0
	v_mfma_f32_16x16x32_bf16 v[68:71], v[144:147], v[210:213], 0
	v_mfma_f32_16x16x32_bf16 v[64:67], v[168:171], v[210:213], 0
	v_mfma_f32_16x16x32_bf16 v[116:119], v[148:151], v[180:183], v[116:119]
	v_mfma_f32_16x16x32_bf16 v[112:115], v[172:175], v[180:183], v[112:115]
	v_mfma_f32_16x16x32_bf16 v[100:103], v[148:151], v[198:201], v[100:103]
	v_mfma_f32_16x16x32_bf16 v[96:99], v[172:175], v[198:201], v[96:99]
	v_mfma_f32_16x16x32_bf16 v[84:87], v[148:151], v[206:209], v[84:87]
	v_mfma_f32_16x16x32_bf16 v[80:83], v[172:175], v[206:209], v[80:83]
	v_mfma_f32_16x16x32_bf16 v[68:71], v[148:151], v[214:217], v[68:71]
	v_mfma_f32_16x16x32_bf16 v[64:67], v[172:175], v[214:217], v[64:67]
	s_barrier
	s_add_u32 s98, s34, s16
	s_addc_u32 s99, s35, s17
	s_add_u32 s100, s36, s16
	s_addc_u32 s101, s37, s17
	s_add_i32 s61, s54, s0
	s_mov_b32 m0, s61
	ds_read_b128 v[176:179], v193 offset:16384
	global_load_lds_dwordx4 v154, s[34:35]
	s_add_i32 m0, s61, 0x2000
	s_add_u32 s62, s34, 0x40000
	s_addc_u32 s63, s35, 0
	s_add_i32 s61, s55, s0
	global_load_lds_dwordx4 v158, s[34:35]
	s_mov_b32 m0, s61
	ds_read_b128 v[180:183], v193 offset:17408
	global_load_lds_dwordx4 v154, s[62:63]
	s_add_i32 m0, s61, 0x2000
	ds_read_b128 v[194:197], v193 offset:18432
	global_load_lds_dwordx4 v158, s[62:63]
	s_mov_b32 m0, s1
	ds_read_b128 v[198:201], v193 offset:19456
	global_load_lds_dwordx4 v152, s[36:37]
	s_mov_b32 m0, s46
	ds_read_b128 v[202:205], v193 offset:20480
	global_load_lds_dwordx4 v156, s[36:37]
	ds_read_b128 v[206:209], v193 offset:21504
	ds_read_b128 v[210:213], v193 offset:22528
	ds_read_b128 v[214:217], v193 offset:23552
	s_waitcnt vmcnt(8)
	s_waitcnt lgkmcnt(0)
	s_barrier
; #define PG8_STAGE(bufoff, gbase, voff) do { _Pragma("unroll") for (int _i = 0; _i < 2; ++_i) \
;         __builtin_amdgcn_global_load_lds((const unsigned*)((const char*)(gbase) + (voff)[_i]), (PG8_LAS unsigned*)(lds + (bufoff) + ldsw + _i * 8192), 16, 0, 0); } while (0)
; #define PG8_LDA(dst, b, h) do { _Pragma("unroll") for (int m = 0; m < 4; ++m) _Pragma("unroll") for (int k = 0; k < 2; ++k) dst[m][k] = *(const PG8_LAS bf16x8*)(lds + PG8_SA(b, h) + aoff + m * 2048 + k * 1024); } while (0)
; #define PG8_LDB(dst, b, h) do { _Pragma("unroll") for (int n = 0; n < 2; ++n) _Pragma("unroll") for (int k = 0; k < 2; ++k) dst[n][k] = *(const PG8_LAS bf16x8*)(lds + PG8_SB(b, h) + boff + n * 2048 + k * 1024); } while (0)
; #define PG8_MMA(ai, bj, At, Bt) do { __builtin_amdgcn_s_setprio(1); _Pragma("unroll") for (int m = 0; m < 4; ++m) _Pragma("unroll") for (int n = 0; n < 2; ++n) _Pragma("unroll") for (int k = 0; k < 2; ++k) \
;         acc[ai][bj][m][n] = __builtin_amdgcn_mfma_f32_16x16x32_bf16(Bt[n][k], At[m][k], acc[ai][bj][m][n], 0, 0, 0); __builtin_amdgcn_s_setprio(0); } while (0)
; #define PG8_WAIT_V(n) asm volatile("s_waitcnt vmcnt(" #n ")" ::: "memory")
; #define PG8_WAIT_L(n) asm volatile("s_waitcnt lgkmcnt(" #n ")" ::: "memory")
; #define PG8_BAR __builtin_amdgcn_s_barrier()
; #define PG8_SCHED __builtin_amdgcn_sched_barrier(0)
; template <class Epi, class Sched, bool ALIGN_EPI = false, bool SP2 = false>
; __device__ __forceinline__ void gemm_phase(PG8_LAS unsigned char* lds, const Gemm g, const Sched& S, const Epi& E, int tid_in) {
;     ...
;             PG8_WAIT_V(8); PG8_WAIT_L(0); PG8_BAR; PG8_MMA(1, 0, At, B0); PG8_MMA(1, 1, At, B1); PG8_BAR; PG8_SCHED;
;             PG8_LDB(B0, 1, 0); PG8_LDB(B1, 1, 1); PG8_SCHED; PG8_LDA(At, 1, 0); PG8_STAGE(PG8_SA(0, 1), a2 + hstep, voffA);
;             PG8_WAIT_V(8); PG8_WAIT_L(0); PG8_BAR; PG8_MMA(0, 0, At, B0); PG8_MMA(0, 1, At, B1); PG8_BAR; PG8_SCHED;
	v_mfma_f32_16x16x32_bf16 v[60:63], v[128:131], v[176:179], 0
	v_mfma_f32_16x16x32_bf16 v[56:59], v[136:139], v[176:179], 0
	v_mfma_f32_16x16x32_bf16 v[44:47], v[128:131], v[194:197], 0
	v_mfma_f32_16x16x32_bf16 v[40:43], v[136:139], v[194:197], 0
	v_mfma_f32_16x16x32_bf16 v[28:31], v[128:131], v[202:205], 0
	v_mfma_f32_16x16x32_bf16 v[24:27], v[136:139], v[202:205], 0
	v_mfma_f32_16x16x32_bf16 v[12:15], v[128:131], v[210:213], 0
	v_mfma_f32_16x16x32_bf16 v[8:11], v[136:139], v[210:213], 0
	v_mfma_f32_16x16x32_bf16 v[60:63], v[132:135], v[180:183], v[60:63]
	v_mfma_f32_16x16x32_bf16 v[56:59], v[140:143], v[180:183], v[56:59]
	v_mfma_f32_16x16x32_bf16 v[44:47], v[132:135], v[198:201], v[44:47]
	v_mfma_f32_16x16x32_bf16 v[40:43], v[140:143], v[198:201], v[40:43]
	v_mfma_f32_16x16x32_bf16 v[28:31], v[132:135], v[206:209], v[28:31]
	v_mfma_f32_16x16x32_bf16 v[24:27], v[140:143], v[206:209], v[24:27]
	v_mfma_f32_16x16x32_bf16 v[12:15], v[132:135], v[214:217], v[12:15]
	v_mfma_f32_16x16x32_bf16 v[8:11], v[140:143], v[214:217], v[8:11]
	v_mfma_f32_16x16x32_bf16 v[52:55], v[144:147], v[176:179], 0
	v_mfma_f32_16x16x32_bf16 v[48:51], v[168:171], v[176:179], 0
	v_mfma_f32_16x16x32_bf16 v[36:39], v[144:147], v[194:197], 0
	v_mfma_f32_16x16x32_bf16 v[32:35], v[168:171], v[194:197], 0
	v_mfma_f32_16x16x32_bf16 v[20:23], v[144:147], v[202:205], 0
	v_mfma_f32_16x16x32_bf16 v[16:19], v[168:171], v[202:205], 0
	v_mfma_f32_16x16x32_bf16 v[4:7], v[144:147], v[210:213], 0
	v_mfma_f32_16x16x32_bf16 v[0:3], v[168:171], v[210:213], 0
	v_mfma_f32_16x16x32_bf16 v[52:55], v[148:151], v[180:183], v[52:55]
	v_mfma_f32_16x16x32_bf16 v[48:51], v[172:175], v[180:183], v[48:51]
	v_mfma_f32_16x16x32_bf16 v[36:39], v[148:151], v[198:201], v[36:39]
	v_mfma_f32_16x16x32_bf16 v[32:35], v[172:175], v[198:201], v[32:35]
	v_mfma_f32_16x16x32_bf16 v[20:23], v[148:151], v[206:209], v[20:23]
	v_mfma_f32_16x16x32_bf16 v[16:19], v[172:175], v[206:209], v[16:19]
	v_mfma_f32_16x16x32_bf16 v[4:7], v[148:151], v[214:217], v[4:7]
	v_mfma_f32_16x16x32_bf16 v[0:3], v[172:175], v[214:217], v[0:3]
	s_barrier
	s_add_i32 s61, 0, 0x18000
	s_add_i32 s62, 0, 0x1c000
	s_add_u32 s36, s36, 0x40000
	s_addc_u32 s37, s37, 0
	s_mov_b32 m0, s47
	s_nop 0
	global_load_lds_dwordx4 v152, s[36:37]
	s_mov_b32 m0, s48
	s_nop 0
	global_load_lds_dwordx4 v156, s[36:37]
	v_add_u32_e32 v140, s61, v187
	v_add_u32_e32 v172, s62, v187
	ds_read_b128 v[128:131], v140
	ds_read_b128 v[132:135], v140 offset:1024
	ds_read_b128 v[136:139], v140 offset:2048
	ds_read_b128 v[140:143], v140 offset:3072
	ds_read_b128 v[144:147], v172
	ds_read_b128 v[148:151], v172 offset:1024
	ds_read_b128 v[168:171], v172 offset:2048
	ds_read_b128 v[172:175], v172 offset:3072
	ds_read_b128 v[176:179], v193 offset:32768
	ds_read_b128 v[180:183], v193 offset:33792
	ds_read_b128 v[194:197], v193 offset:34816
	ds_read_b128 v[198:201], v193 offset:35840
	ds_read_b128 v[202:205], v193 offset:36864
	ds_read_b128 v[206:209], v193 offset:37888
	ds_read_b128 v[210:213], v193 offset:38912
	ds_read_b128 v[214:217], v193 offset:39936
	s_waitcnt vmcnt(8)
	s_waitcnt lgkmcnt(0)
	s_barrier
	v_mfma_f32_16x16x32_bf16 v[124:127], v[128:131], v[176:179], v[124:127]
	v_mfma_f32_16x16x32_bf16 v[120:123], v[136:139], v[176:179], v[120:123]
	v_mfma_f32_16x16x32_bf16 v[108:111], v[128:131], v[194:197], v[108:111]
	v_mfma_f32_16x16x32_bf16 v[104:107], v[136:139], v[194:197], v[104:107]
	v_mfma_f32_16x16x32_bf16 v[92:95], v[128:131], v[202:205], v[92:95]
	v_mfma_f32_16x16x32_bf16 v[88:91], v[136:139], v[202:205], v[88:91]
	v_mfma_f32_16x16x32_bf16 v[76:79], v[128:131], v[210:213], v[76:79]
	v_mfma_f32_16x16x32_bf16 v[72:75], v[136:139], v[210:213], v[72:75]
	v_mfma_f32_16x16x32_bf16 v[124:127], v[132:135], v[180:183], v[124:127]
	v_mfma_f32_16x16x32_bf16 v[120:123], v[140:143], v[180:183], v[120:123]
	v_mfma_f32_16x16x32_bf16 v[108:111], v[132:135], v[198:201], v[108:111]
	v_mfma_f32_16x16x32_bf16 v[104:107], v[140:143], v[198:201], v[104:107]
	v_mfma_f32_16x16x32_bf16 v[92:95], v[132:135], v[206:209], v[92:95]
	v_mfma_f32_16x16x32_bf16 v[88:91], v[140:143], v[206:209], v[88:91]
	v_mfma_f32_16x16x32_bf16 v[76:79], v[132:135], v[214:217], v[76:79]
	v_mfma_f32_16x16x32_bf16 v[72:75], v[140:143], v[214:217], v[72:75]
	v_mfma_f32_16x16x32_bf16 v[116:119], v[144:147], v[176:179], v[116:119]
	v_mfma_f32_16x16x32_bf16 v[112:115], v[168:171], v[176:179], v[112:115]
	v_mfma_f32_16x16x32_bf16 v[100:103], v[144:147], v[194:197], v[100:103]
	v_mfma_f32_16x16x32_bf16 v[96:99], v[168:171], v[194:197], v[96:99]
	v_mfma_f32_16x16x32_bf16 v[84:87], v[144:147], v[202:205], v[84:87]
	v_mfma_f32_16x16x32_bf16 v[80:83], v[168:171], v[202:205], v[80:83]
	v_mfma_f32_16x16x32_bf16 v[68:71], v[144:147], v[210:213], v[68:71]
	v_mfma_f32_16x16x32_bf16 v[64:67], v[168:171], v[210:213], v[64:67]
	v_mfma_f32_16x16x32_bf16 v[116:119], v[148:151], v[180:183], v[116:119]
	v_mfma_f32_16x16x32_bf16 v[112:115], v[172:175], v[180:183], v[112:115]
	v_mfma_f32_16x16x32_bf16 v[100:103], v[148:151], v[198:201], v[100:103]
	v_mfma_f32_16x16x32_bf16 v[96:99], v[172:175], v[198:201], v[96:99]
	v_mfma_f32_16x16x32_bf16 v[84:87], v[148:151], v[206:209], v[84:87]
	v_mfma_f32_16x16x32_bf16 v[80:83], v[172:175], v[206:209], v[80:83]
	v_mfma_f32_16x16x32_bf16 v[68:71], v[148:151], v[214:217], v[68:71]
	v_mfma_f32_16x16x32_bf16 v[64:67], v[172:175], v[214:217], v[64:67]
	s_barrier
; #define PG8_STAGE(bufoff, gbase, voff) do { _Pragma("unroll") for (int _i = 0; _i < 2; ++_i) \
;         __builtin_amdgcn_global_load_lds((const unsigned*)((const char*)(gbase) + (voff)[_i]), (PG8_LAS unsigned*)(lds + (bufoff) + ldsw + _i * 8192), 16, 0, 0); } while (0)
; #define PG8_LDA(dst, b, h) do { _Pragma("unroll") for (int m = 0; m < 4; ++m) _Pragma("unroll") for (int k = 0; k < 2; ++k) dst[m][k] = *(const PG8_LAS bf16x8*)(lds + PG8_SA(b, h) + aoff + m * 2048 + k * 1024); } while (0)
; #define PG8_LDB(dst, b, h) do { _Pragma("unroll") for (int n = 0; n < 2; ++n) _Pragma("unroll") for (int k = 0; k < 2; ++k) dst[n][k] = *(const PG8_LAS bf16x8*)(lds + PG8_SB(b, h) + boff + n * 2048 + k * 1024); } while (0)
; #define PG8_MMA(ai, bj, At, Bt) do { __builtin_amdgcn_s_setprio(1); _Pragma("unroll") for (int m = 0; m < 4; ++m) _Pragma("unroll") for (int n = 0; n < 2; ++n) _Pragma("unroll") for (int k = 0; k < 2; ++k) \
;         acc[ai][bj][m][n] = __builtin_amdgcn_mfma_f32_16x16x32_bf16(Bt[n][k], At[m][k], acc[ai][bj][m][n], 0, 0, 0); __builtin_amdgcn_s_setprio(0); } while (0)
; #define PG8_WAIT_V(n) asm volatile("s_waitcnt vmcnt(" #n ")" ::: "memory")
; #define PG8_WAIT_L(n) asm volatile("s_waitcnt lgkmcnt(" #n ")" ::: "memory")
; #define PG8_BAR __builtin_amdgcn_s_barrier()
; template <class Epi, class Sched, bool ALIGN_EPI = false, bool SP2 = false>
; __device__ __forceinline__ void gemm_phase(PG8_LAS unsigned char* lds, const Gemm g, const Sched& S, const Epi& E, int tid_in) {
;     ...
;             const char* a1 = cA + (size_t)(t + 1) * kstep;
;             const char* a2 = last ? nA : cA + (size_t)(t + 2) * kstep; const char* b2 = last ? nB : cB + (size_t)(t + 2) * kstep;
;             const char* a3 = a2 + kstep; const char* b3 = b2 + kstep;
;             if (last && has_next) S.a_ready(nxt);
;             if constexpr (SP2) {
;             PG8_LDB(B0, 0, 0); PG8_LDB(B1, 0, 1); PG8_SCHED; PG8_LDA(At, 0, 0); PG8_STAGE(PG8_SA(1, 1), a1 + hstep, voffA);
;             PG8_WAIT_V(8); PG8_WAIT_L(0); PG8_BAR; PG8_MMA(0, 0, At, B0); PG8_MMA(0, 1, At, B1); PG8_BAR; PG8_SCHED;
;     ...
;             PG8_LDA(At, 1, 1); PG8_STAGE(PG8_SB(1, 0), b3, voffB); PG8_STAGE(PG8_SB(1, 1), b3 + hstep, voffB); PG8_STAGE(PG8_SA(1, 0), a3, voffA);
;             PG8_WAIT_V(8); PG8_WAIT_L(0); PG8_BAR; PG8_MMA(1, 0, At, B0); PG8_MMA(1, 1, At, B1); PG8_BAR; PG8_SCHED;
	s_add_i32 s36, s61, s0
	s_mov_b32 m0, s36
	ds_read_b128 v[176:179], v193 offset:49152
	global_load_lds_dwordx4 v154, s[98:99]
	s_add_i32 m0, s36, 0x2000
	s_add_u32 s34, s34, 0x40080
	s_addc_u32 s35, s35, 0
	s_add_i32 s36, s62, s0
	global_load_lds_dwordx4 v158, s[98:99]
	s_mov_b32 m0, s36
	ds_read_b128 v[180:183], v193 offset:50176
	global_load_lds_dwordx4 v154, s[34:35]
	s_add_i32 m0, s36, 0x2000
	ds_read_b128 v[194:197], v193 offset:51200
	global_load_lds_dwordx4 v158, s[34:35]
	s_mov_b32 m0, s50
	ds_read_b128 v[198:201], v193 offset:52224
	global_load_lds_dwordx4 v152, s[100:101]
	s_mov_b32 m0, s51
	ds_read_b128 v[202:205], v193 offset:53248
	global_load_lds_dwordx4 v156, s[100:101]
	ds_read_b128 v[206:209], v193 offset:54272
	ds_read_b128 v[210:213], v193 offset:55296
	ds_read_b128 v[214:217], v193 offset:56320
	s_waitcnt vmcnt(8)
	s_waitcnt lgkmcnt(0)
	s_barrier
	v_mfma_f32_16x16x32_bf16 v[60:63], v[128:131], v[176:179], v[60:63]
	v_mfma_f32_16x16x32_bf16 v[56:59], v[136:139], v[176:179], v[56:59]
	v_mfma_f32_16x16x32_bf16 v[44:47], v[128:131], v[194:197], v[44:47]
	v_mfma_f32_16x16x32_bf16 v[40:43], v[136:139], v[194:197], v[40:43]
	v_mfma_f32_16x16x32_bf16 v[28:31], v[128:131], v[202:205], v[28:31]
	v_mfma_f32_16x16x32_bf16 v[24:27], v[136:139], v[202:205], v[24:27]
	v_mfma_f32_16x16x32_bf16 v[12:15], v[128:131], v[210:213], v[12:15]
	v_mfma_f32_16x16x32_bf16 v[8:11], v[136:139], v[210:213], v[8:11]
	v_mfma_f32_16x16x32_bf16 v[60:63], v[132:135], v[180:183], v[60:63]
	v_mfma_f32_16x16x32_bf16 v[56:59], v[140:143], v[180:183], v[56:59]
	v_mfma_f32_16x16x32_bf16 v[44:47], v[132:135], v[198:201], v[44:47]
	v_mfma_f32_16x16x32_bf16 v[40:43], v[140:143], v[198:201], v[40:43]
	v_mfma_f32_16x16x32_bf16 v[28:31], v[132:135], v[206:209], v[28:31]
	v_mfma_f32_16x16x32_bf16 v[24:27], v[140:143], v[206:209], v[24:27]
	v_mfma_f32_16x16x32_bf16 v[12:15], v[132:135], v[214:217], v[12:15]
	v_mfma_f32_16x16x32_bf16 v[8:11], v[140:143], v[214:217], v[8:11]
	v_mfma_f32_16x16x32_bf16 v[52:55], v[144:147], v[176:179], v[52:55]
	v_mfma_f32_16x16x32_bf16 v[48:51], v[168:171], v[176:179], v[48:51]
	v_mfma_f32_16x16x32_bf16 v[36:39], v[144:147], v[194:197], v[36:39]
	v_mfma_f32_16x16x32_bf16 v[32:35], v[168:171], v[194:197], v[32:35]
	v_mfma_f32_16x16x32_bf16 v[20:23], v[144:147], v[202:205], v[20:23]
	v_mfma_f32_16x16x32_bf16 v[16:19], v[168:171], v[202:205], v[16:19]
	v_mfma_f32_16x16x32_bf16 v[4:7], v[144:147], v[210:213], v[4:7]
	v_mfma_f32_16x16x32_bf16 v[0:3], v[168:171], v[210:213], v[0:3]
	v_mfma_f32_16x16x32_bf16 v[52:55], v[148:151], v[180:183], v[52:55]
	v_mfma_f32_16x16x32_bf16 v[48:51], v[172:175], v[180:183], v[48:51]
	v_mfma_f32_16x16x32_bf16 v[36:39], v[148:151], v[198:201], v[36:39]
	v_mfma_f32_16x16x32_bf16 v[32:35], v[172:175], v[198:201], v[32:35]
	v_mfma_f32_16x16x32_bf16 v[20:23], v[148:151], v[206:209], v[20:23]
	v_mfma_f32_16x16x32_bf16 v[16:19], v[172:175], v[206:209], v[16:19]
	v_mfma_f32_16x16x32_bf16 v[4:7], v[148:151], v[214:217], v[4:7]
	v_mfma_f32_16x16x32_bf16 v[0:3], v[172:175], v[214:217], v[0:3]
	s_barrier
	s_add_i32 s60, s60, 2
	s_add_u32 s30, s30, 0x100
	s_addc_u32 s31, s31, 0
	s_add_u32 s58, s58, 0x100
	s_addc_u32 s59, s59, 0
	v_readlane_b32 s98, v248, 0
	s_nop 3
	s_cmp_ge_u32 s98, 0x100
	s_cbranch_scc0 .Lgprio_skip_3
	s_setprio 1
.Lgprio_skip_3:
.LBB0_1148:
	s_add_u32 s34, s30, 0xfffc0080
	s_addc_u32 s35, s31, -1
	s_cmp_eq_u32 s60, 12
	s_cselect_b32 s37, s23, s35
	s_cselect_b32 s36, s29, s34
	s_cselect_b32 s35, s21, s59
	s_cselect_b32 s34, s57, s58
	s_add_i32 m0, s1, 0xc000
	ds_read_b128 v[128:131], v191
	global_load_lds_dwordx4 v160, s[30:31]
	s_add_i32 m0, s1, 0xe000
	ds_read_b128 v[132:135], v191 offset:1024
	global_load_lds_dwordx4 v162, s[30:31]
	ds_read_b128 v[136:139], v191 offset:2048
	ds_read_b128 v[140:143], v191 offset:3072
	ds_read_b128 v[144:147], v192
	ds_read_b128 v[148:151], v192 offset:1024
	ds_read_b128 v[168:171], v192 offset:2048
	ds_read_b128 v[172:175], v192 offset:3072
	ds_read_b128 v[176:179], v193
	ds_read_b128 v[180:183], v193 offset:1024
	ds_read_b128 v[194:197], v193 offset:2048
	ds_read_b128 v[198:201], v193 offset:3072
	ds_read_b128 v[202:205], v193 offset:4096
	ds_read_b128 v[206:209], v193 offset:5120
	ds_read_b128 v[210:213], v193 offset:6144
	ds_read_b128 v[214:217], v193 offset:7168
	s_waitcnt vmcnt(8)
	s_waitcnt lgkmcnt(0)
	s_barrier
	v_mfma_f32_16x16x32_bf16 v[124:127], v[128:131], v[176:179], v[124:127]
	v_mfma_f32_16x16x32_bf16 v[120:123], v[136:139], v[176:179], v[120:123]
	v_mfma_f32_16x16x32_bf16 v[108:111], v[128:131], v[194:197], v[108:111]
	v_mfma_f32_16x16x32_bf16 v[104:107], v[136:139], v[194:197], v[104:107]
	v_mfma_f32_16x16x32_bf16 v[92:95], v[128:131], v[202:205], v[92:95]
	v_mfma_f32_16x16x32_bf16 v[88:91], v[136:139], v[202:205], v[88:91]
	v_mfma_f32_16x16x32_bf16 v[76:79], v[128:131], v[210:213], v[76:79]
	v_mfma_f32_16x16x32_bf16 v[72:75], v[136:139], v[210:213], v[72:75]
	v_mfma_f32_16x16x32_bf16 v[124:127], v[132:135], v[180:183], v[124:127]
	v_mfma_f32_16x16x32_bf16 v[120:123], v[140:143], v[180:183], v[120:123]
	v_mfma_f32_16x16x32_bf16 v[108:111], v[132:135], v[198:201], v[108:111]
	v_mfma_f32_16x16x32_bf16 v[104:107], v[140:143], v[198:201], v[104:107]
	v_mfma_f32_16x16x32_bf16 v[92:95], v[132:135], v[206:209], v[92:95]
	v_mfma_f32_16x16x32_bf16 v[88:91], v[140:143], v[206:209], v[88:91]
	v_mfma_f32_16x16x32_bf16 v[76:79], v[132:135], v[214:217], v[76:79]
	v_mfma_f32_16x16x32_bf16 v[72:75], v[140:143], v[214:217], v[72:75]
	v_mfma_f32_16x16x32_bf16 v[116:119], v[144:147], v[176:179], v[116:119]
	v_mfma_f32_16x16x32_bf16 v[112:115], v[168:171], v[176:179], v[112:115]
	v_mfma_f32_16x16x32_bf16 v[100:103], v[144:147], v[194:197], v[100:103]
	v_mfma_f32_16x16x32_bf16 v[96:99], v[168:171], v[194:197], v[96:99]
	v_mfma_f32_16x16x32_bf16 v[84:87], v[144:147], v[202:205], v[84:87]
	v_mfma_f32_16x16x32_bf16 v[80:83], v[168:171], v[202:205], v[80:83]
	v_mfma_f32_16x16x32_bf16 v[68:71], v[144:147], v[210:213], v[68:71]
	v_mfma_f32_16x16x32_bf16 v[64:67], v[168:171], v[210:213], v[64:67]
	v_mfma_f32_16x16x32_bf16 v[116:119], v[148:151], v[180:183], v[116:119]
	v_mfma_f32_16x16x32_bf16 v[112:115], v[172:175], v[180:183], v[112:115]
	v_mfma_f32_16x16x32_bf16 v[100:103], v[148:151], v[198:201], v[100:103]
	v_mfma_f32_16x16x32_bf16 v[96:99], v[172:175], v[198:201], v[96:99]
	v_mfma_f32_16x16x32_bf16 v[84:87], v[148:151], v[206:209], v[84:87]
	v_mfma_f32_16x16x32_bf16 v[80:83], v[172:175], v[206:209], v[80:83]
	v_mfma_f32_16x16x32_bf16 v[68:71], v[148:151], v[214:217], v[68:71]
	v_mfma_f32_16x16x32_bf16 v[64:67], v[172:175], v[214:217], v[64:67]
	s_barrier
; #define PG8_STAGE(bufoff, gbase, voff) do { _Pragma("unroll") for (int _i = 0; _i < 2; ++_i) \
;         __builtin_amdgcn_global_load_lds((const unsigned*)((const char*)(gbase) + (voff)[_i]), (PG8_LAS unsigned*)(lds + (bufoff) + ldsw + _i * 8192), 16, 0, 0); } while (0)
; #define PG8_LDA(dst, b, h) do { _Pragma("unroll") for (int m = 0; m < 4; ++m) _Pragma("unroll") for (int k = 0; k < 2; ++k) dst[m][k] = *(const PG8_LAS bf16x8*)(lds + PG8_SA(b, h) + aoff + m * 2048 + k * 1024); } while (0)
; #define PG8_LDB(dst, b, h) do { _Pragma("unroll") for (int n = 0; n < 2; ++n) _Pragma("unroll") for (int k = 0; k < 2; ++k) dst[n][k] = *(const PG8_LAS bf16x8*)(lds + PG8_SB(b, h) + boff + n * 2048 + k * 1024); } while (0)
; #define PG8_MMA(ai, bj, At, Bt) do { __builtin_amdgcn_s_setprio(1); _Pragma("unroll") for (int m = 0; m < 4; ++m) _Pragma("unroll") for (int n = 0; n < 2; ++n) _Pragma("unroll") for (int k = 0; k < 2; ++k) \
;         acc[ai][bj][m][n] = __builtin_amdgcn_mfma_f32_16x16x32_bf16(Bt[n][k], At[m][k], acc[ai][bj][m][n], 0, 0, 0); __builtin_amdgcn_s_setprio(0); } while (0)
; #define PG8_WAIT_V(n) asm volatile("s_waitcnt vmcnt(" #n ")" ::: "memory")
; #define PG8_WAIT_L(n) asm volatile("s_waitcnt lgkmcnt(" #n ")" ::: "memory")
; #define PG8_BAR __builtin_amdgcn_s_barrier()
; #define PG8_SCHED __builtin_amdgcn_sched_barrier(0)
; template <class Epi, class Sched, bool ALIGN_EPI = false, bool SP2 = false>
; __device__ __forceinline__ void gemm_phase(PG8_LAS unsigned char* lds, const Gemm g, const Sched& S, const Epi& E, int tid_in) {
;     ...
;             PG8_LDA(At, 0, 1); PG8_STAGE(PG8_SB(0, 0), b2, voffB); PG8_STAGE(PG8_SB(0, 1), b2 + hstep, voffB); PG8_STAGE(PG8_SA(0, 0), a2, voffA);
;             PG8_WAIT_V(8); PG8_WAIT_L(0); PG8_BAR; PG8_MMA(1, 0, At, B0); PG8_MMA(1, 1, At, B1); PG8_BAR; PG8_SCHED;
;             PG8_LDB(B0, 1, 0); PG8_LDB(B1, 1, 1); PG8_SCHED; PG8_LDA(At, 1, 0); PG8_STAGE(PG8_SA(0, 1), a2 + hstep, voffA);
	s_add_u32 s98, s34, s16
	s_addc_u32 s99, s35, s17
	s_add_u32 s100, s36, s16
	s_addc_u32 s101, s37, s17
	s_add_i32 s61, s54, s0
	s_mov_b32 m0, s61
	ds_read_b128 v[176:179], v193 offset:16384
	global_load_lds_dwordx4 v154, s[34:35]
	s_add_i32 m0, s61, 0x2000
	s_add_u32 s62, s34, 0x40000
	s_addc_u32 s63, s35, 0
	s_add_i32 s61, s55, s0
	global_load_lds_dwordx4 v158, s[34:35]
	s_mov_b32 m0, s61
	ds_read_b128 v[180:183], v193 offset:17408
	global_load_lds_dwordx4 v154, s[62:63]
	s_add_i32 m0, s61, 0x2000
	ds_read_b128 v[194:197], v193 offset:18432
	global_load_lds_dwordx4 v158, s[62:63]
	s_mov_b32 m0, s1
	ds_read_b128 v[198:201], v193 offset:19456
	global_load_lds_dwordx4 v152, s[36:37]
	s_mov_b32 m0, s46
	ds_read_b128 v[202:205], v193 offset:20480
	global_load_lds_dwordx4 v156, s[36:37]
	ds_read_b128 v[206:209], v193 offset:21504
	ds_read_b128 v[210:213], v193 offset:22528
	ds_read_b128 v[214:217], v193 offset:23552
	s_waitcnt vmcnt(8)
	s_waitcnt lgkmcnt(0)
	s_barrier
	v_mfma_f32_16x16x32_bf16 v[60:63], v[128:131], v[176:179], v[60:63]
	v_mfma_f32_16x16x32_bf16 v[56:59], v[136:139], v[176:179], v[56:59]
	v_mfma_f32_16x16x32_bf16 v[44:47], v[128:131], v[194:197], v[44:47]
	v_mfma_f32_16x16x32_bf16 v[40:43], v[136:139], v[194:197], v[40:43]
	v_mfma_f32_16x16x32_bf16 v[28:31], v[128:131], v[202:205], v[28:31]
	v_mfma_f32_16x16x32_bf16 v[24:27], v[136:139], v[202:205], v[24:27]
	v_mfma_f32_16x16x32_bf16 v[12:15], v[128:131], v[210:213], v[12:15]
	v_mfma_f32_16x16x32_bf16 v[8:11], v[136:139], v[210:213], v[8:11]
	v_mfma_f32_16x16x32_bf16 v[60:63], v[132:135], v[180:183], v[60:63]
	v_mfma_f32_16x16x32_bf16 v[56:59], v[140:143], v[180:183], v[56:59]
	v_mfma_f32_16x16x32_bf16 v[44:47], v[132:135], v[198:201], v[44:47]
	v_mfma_f32_16x16x32_bf16 v[40:43], v[140:143], v[198:201], v[40:43]
	v_mfma_f32_16x16x32_bf16 v[28:31], v[132:135], v[206:209], v[28:31]
	v_mfma_f32_16x16x32_bf16 v[24:27], v[140:143], v[206:209], v[24:27]
	v_mfma_f32_16x16x32_bf16 v[12:15], v[132:135], v[214:217], v[12:15]
	v_mfma_f32_16x16x32_bf16 v[8:11], v[140:143], v[214:217], v[8:11]
	v_mfma_f32_16x16x32_bf16 v[52:55], v[144:147], v[176:179], v[52:55]
	v_mfma_f32_16x16x32_bf16 v[48:51], v[168:171], v[176:179], v[48:51]
	v_mfma_f32_16x16x32_bf16 v[36:39], v[144:147], v[194:197], v[36:39]
	v_mfma_f32_16x16x32_bf16 v[32:35], v[168:171], v[194:197], v[32:35]
	v_mfma_f32_16x16x32_bf16 v[20:23], v[144:147], v[202:205], v[20:23]
	v_mfma_f32_16x16x32_bf16 v[16:19], v[168:171], v[202:205], v[16:19]
	v_mfma_f32_16x16x32_bf16 v[4:7], v[144:147], v[210:213], v[4:7]
	v_mfma_f32_16x16x32_bf16 v[0:3], v[168:171], v[210:213], v[0:3]
	v_mfma_f32_16x16x32_bf16 v[52:55], v[148:151], v[180:183], v[52:55]
	v_mfma_f32_16x16x32_bf16 v[48:51], v[172:175], v[180:183], v[48:51]
	v_mfma_f32_16x16x32_bf16 v[36:39], v[148:151], v[198:201], v[36:39]
	v_mfma_f32_16x16x32_bf16 v[32:35], v[172:175], v[198:201], v[32:35]
	v_mfma_f32_16x16x32_bf16 v[20:23], v[148:151], v[206:209], v[20:23]
	v_mfma_f32_16x16x32_bf16 v[16:19], v[172:175], v[206:209], v[16:19]
	v_mfma_f32_16x16x32_bf16 v[4:7], v[148:151], v[214:217], v[4:7]
	v_mfma_f32_16x16x32_bf16 v[0:3], v[172:175], v[214:217], v[0:3]
	s_barrier
	s_add_i32 s61, 0, 0x18000
	s_add_i32 s62, 0, 0x1c000
	s_add_u32 s36, s36, 0x40000
	s_addc_u32 s37, s37, 0
	s_mov_b32 m0, s47
	s_nop 0
	global_load_lds_dwordx4 v152, s[36:37]
	s_mov_b32 m0, s48
	s_nop 0
	global_load_lds_dwordx4 v156, s[36:37]
	v_add_u32_e32 v140, s61, v187
	v_add_u32_e32 v172, s62, v187
	ds_read_b128 v[128:131], v140
	ds_read_b128 v[132:135], v140 offset:1024
	ds_read_b128 v[136:139], v140 offset:2048
	ds_read_b128 v[140:143], v140 offset:3072
	ds_read_b128 v[144:147], v172
	ds_read_b128 v[148:151], v172 offset:1024
	ds_read_b128 v[168:171], v172 offset:2048
	ds_read_b128 v[172:175], v172 offset:3072
	ds_read_b128 v[176:179], v193 offset:32768
	ds_read_b128 v[180:183], v193 offset:33792
	ds_read_b128 v[194:197], v193 offset:34816
	ds_read_b128 v[198:201], v193 offset:35840
	ds_read_b128 v[202:205], v193 offset:36864
	ds_read_b128 v[206:209], v193 offset:37888
	ds_read_b128 v[210:213], v193 offset:38912
	ds_read_b128 v[214:217], v193 offset:39936
	s_waitcnt vmcnt(8)
	s_waitcnt lgkmcnt(0)
	s_barrier
; #define PG8_STAGE(bufoff, gbase, voff) do { _Pragma("unroll") for (int _i = 0; _i < 2; ++_i) \
;         __builtin_amdgcn_global_load_lds((const unsigned*)((const char*)(gbase) + (voff)[_i]), (PG8_LAS unsigned*)(lds + (bufoff) + ldsw + _i * 8192), 16, 0, 0); } while (0)
; #define PG8_LDA(dst, b, h) do { _Pragma("unroll") for (int m = 0; m < 4; ++m) _Pragma("unroll") for (int k = 0; k < 2; ++k) dst[m][k] = *(const PG8_LAS bf16x8*)(lds + PG8_SA(b, h) + aoff + m * 2048 + k * 1024); } while (0)
; #define PG8_MMA(ai, bj, At, Bt) do { __builtin_amdgcn_s_setprio(1); _Pragma("unroll") for (int m = 0; m < 4; ++m) _Pragma("unroll") for (int n = 0; n < 2; ++n) _Pragma("unroll") for (int k = 0; k < 2; ++k) \
;         acc[ai][bj][m][n] = __builtin_amdgcn_mfma_f32_16x16x32_bf16(Bt[n][k], At[m][k], acc[ai][bj][m][n], 0, 0, 0); __builtin_amdgcn_s_setprio(0); } while (0)
; #define PG8_WAIT_V(n) asm volatile("s_waitcnt vmcnt(" #n ")" ::: "memory")
; #define PG8_WAIT_L(n) asm volatile("s_waitcnt lgkmcnt(" #n ")" ::: "memory")
; #define PG8_BAR __builtin_amdgcn_s_barrier()
; #define PG8_SCHED __builtin_amdgcn_sched_barrier(0)
; template <class Epi, class Sched, bool ALIGN_EPI = false, bool SP2 = false>
; __device__ __forceinline__ void gemm_phase(PG8_LAS unsigned char* lds, const Gemm g, const Sched& S, const Epi& E, int tid_in) {
;     ...
;             PG8_WAIT_V(8); PG8_WAIT_L(0); PG8_BAR; PG8_MMA(0, 0, At, B0); PG8_MMA(0, 1, At, B1); PG8_BAR; PG8_SCHED;
;             PG8_LDA(At, 1, 1); PG8_STAGE(PG8_SB(1, 0), b3, voffB); PG8_STAGE(PG8_SB(1, 1), b3 + hstep, voffB); PG8_STAGE(PG8_SA(1, 0), a3, voffA);
;             PG8_WAIT_V(8); PG8_WAIT_L(0); PG8_BAR; PG8_MMA(1, 0, At, B0); PG8_MMA(1, 1, At, B1); PG8_BAR; PG8_SCHED;
;     ...
;         if constexpr (ALIGN_EPI) { if (wr == 0) PG8_BAR; }
	v_mfma_f32_16x16x32_bf16 v[124:127], v[128:131], v[176:179], v[124:127]
	v_mfma_f32_16x16x32_bf16 v[120:123], v[136:139], v[176:179], v[120:123]
	v_mfma_f32_16x16x32_bf16 v[108:111], v[128:131], v[194:197], v[108:111]
	v_mfma_f32_16x16x32_bf16 v[104:107], v[136:139], v[194:197], v[104:107]
	v_mfma_f32_16x16x32_bf16 v[92:95], v[128:131], v[202:205], v[92:95]
	v_mfma_f32_16x16x32_bf16 v[88:91], v[136:139], v[202:205], v[88:91]
	v_mfma_f32_16x16x32_bf16 v[76:79], v[128:131], v[210:213], v[76:79]
	v_mfma_f32_16x16x32_bf16 v[72:75], v[136:139], v[210:213], v[72:75]
	v_mfma_f32_16x16x32_bf16 v[124:127], v[132:135], v[180:183], v[124:127]
	v_mfma_f32_16x16x32_bf16 v[120:123], v[140:143], v[180:183], v[120:123]
	v_mfma_f32_16x16x32_bf16 v[108:111], v[132:135], v[198:201], v[108:111]
	v_mfma_f32_16x16x32_bf16 v[104:107], v[140:143], v[198:201], v[104:107]
	v_mfma_f32_16x16x32_bf16 v[92:95], v[132:135], v[206:209], v[92:95]
	v_mfma_f32_16x16x32_bf16 v[88:91], v[140:143], v[206:209], v[88:91]
	v_mfma_f32_16x16x32_bf16 v[76:79], v[132:135], v[214:217], v[76:79]
	v_mfma_f32_16x16x32_bf16 v[72:75], v[140:143], v[214:217], v[72:75]
	v_mfma_f32_16x16x32_bf16 v[116:119], v[144:147], v[176:179], v[116:119]
	v_mfma_f32_16x16x32_bf16 v[112:115], v[168:171], v[176:179], v[112:115]
	v_mfma_f32_16x16x32_bf16 v[100:103], v[144:147], v[194:197], v[100:103]
	v_mfma_f32_16x16x32_bf16 v[96:99], v[168:171], v[194:197], v[96:99]
	v_mfma_f32_16x16x32_bf16 v[84:87], v[144:147], v[202:205], v[84:87]
	v_mfma_f32_16x16x32_bf16 v[80:83], v[168:171], v[202:205], v[80:83]
	v_mfma_f32_16x16x32_bf16 v[68:71], v[144:147], v[210:213], v[68:71]
	v_mfma_f32_16x16x32_bf16 v[64:67], v[168:171], v[210:213], v[64:67]
	v_mfma_f32_16x16x32_bf16 v[116:119], v[148:151], v[180:183], v[116:119]
	v_mfma_f32_16x16x32_bf16 v[112:115], v[172:175], v[180:183], v[112:115]
	v_mfma_f32_16x16x32_bf16 v[100:103], v[148:151], v[198:201], v[100:103]
	v_mfma_f32_16x16x32_bf16 v[96:99], v[172:175], v[198:201], v[96:99]
	v_mfma_f32_16x16x32_bf16 v[84:87], v[148:151], v[206:209], v[84:87]
	v_mfma_f32_16x16x32_bf16 v[80:83], v[172:175], v[206:209], v[80:83]
	v_mfma_f32_16x16x32_bf16 v[68:71], v[148:151], v[214:217], v[68:71]
	v_mfma_f32_16x16x32_bf16 v[64:67], v[172:175], v[214:217], v[64:67]
	s_barrier
	s_add_i32 s36, s61, s0
	s_mov_b32 m0, s36
	ds_read_b128 v[176:179], v193 offset:49152
	global_load_lds_dwordx4 v154, s[98:99]
	s_add_i32 m0, s36, 0x2000
	s_add_u32 s34, s34, 0x40080
	s_addc_u32 s35, s35, 0
	s_add_i32 s36, s62, s0
	global_load_lds_dwordx4 v158, s[98:99]
	s_mov_b32 m0, s36
	ds_read_b128 v[180:183], v193 offset:50176
	global_load_lds_dwordx4 v154, s[34:35]
	s_add_i32 m0, s36, 0x2000
	ds_read_b128 v[194:197], v193 offset:51200
	global_load_lds_dwordx4 v158, s[34:35]
	s_mov_b32 m0, s50
	ds_read_b128 v[198:201], v193 offset:52224
	global_load_lds_dwordx4 v152, s[100:101]
	s_mov_b32 m0, s51
	ds_read_b128 v[202:205], v193 offset:53248
	global_load_lds_dwordx4 v156, s[100:101]
	ds_read_b128 v[206:209], v193 offset:54272
	ds_read_b128 v[210:213], v193 offset:55296
	ds_read_b128 v[214:217], v193 offset:56320
	s_waitcnt vmcnt(8)
	s_waitcnt lgkmcnt(0)
	s_barrier
	v_mfma_f32_16x16x32_bf16 v[60:63], v[128:131], v[176:179], v[60:63]
	v_mfma_f32_16x16x32_bf16 v[56:59], v[136:139], v[176:179], v[56:59]
	v_mfma_f32_16x16x32_bf16 v[44:47], v[128:131], v[194:197], v[44:47]
	v_mfma_f32_16x16x32_bf16 v[40:43], v[136:139], v[194:197], v[40:43]
	v_mfma_f32_16x16x32_bf16 v[28:31], v[128:131], v[202:205], v[28:31]
	v_mfma_f32_16x16x32_bf16 v[24:27], v[136:139], v[202:205], v[24:27]
	v_mfma_f32_16x16x32_bf16 v[12:15], v[128:131], v[210:213], v[12:15]
	v_mfma_f32_16x16x32_bf16 v[8:11], v[136:139], v[210:213], v[8:11]
	v_mfma_f32_16x16x32_bf16 v[60:63], v[132:135], v[180:183], v[60:63]
	v_mfma_f32_16x16x32_bf16 v[56:59], v[140:143], v[180:183], v[56:59]
	v_mfma_f32_16x16x32_bf16 v[44:47], v[132:135], v[198:201], v[44:47]
	v_mfma_f32_16x16x32_bf16 v[40:43], v[140:143], v[198:201], v[40:43]
	v_mfma_f32_16x16x32_bf16 v[28:31], v[132:135], v[206:209], v[28:31]
	v_mfma_f32_16x16x32_bf16 v[24:27], v[140:143], v[206:209], v[24:27]
	v_mfma_f32_16x16x32_bf16 v[12:15], v[132:135], v[214:217], v[12:15]
	v_mfma_f32_16x16x32_bf16 v[8:11], v[140:143], v[214:217], v[8:11]
	v_mfma_f32_16x16x32_bf16 v[52:55], v[144:147], v[176:179], v[52:55]
	v_mfma_f32_16x16x32_bf16 v[48:51], v[168:171], v[176:179], v[48:51]
	v_mfma_f32_16x16x32_bf16 v[36:39], v[144:147], v[194:197], v[36:39]
	v_mfma_f32_16x16x32_bf16 v[32:35], v[168:171], v[194:197], v[32:35]
	v_mfma_f32_16x16x32_bf16 v[20:23], v[144:147], v[202:205], v[20:23]
	v_mfma_f32_16x16x32_bf16 v[16:19], v[168:171], v[202:205], v[16:19]
	v_mfma_f32_16x16x32_bf16 v[4:7], v[144:147], v[210:213], v[4:7]
	v_mfma_f32_16x16x32_bf16 v[0:3], v[168:171], v[210:213], v[0:3]
	v_mfma_f32_16x16x32_bf16 v[52:55], v[148:151], v[180:183], v[52:55]
	v_mfma_f32_16x16x32_bf16 v[48:51], v[172:175], v[180:183], v[48:51]
	v_mfma_f32_16x16x32_bf16 v[36:39], v[148:151], v[198:201], v[36:39]
	v_mfma_f32_16x16x32_bf16 v[32:35], v[172:175], v[198:201], v[32:35]
	v_mfma_f32_16x16x32_bf16 v[20:23], v[148:151], v[206:209], v[20:23]
	v_mfma_f32_16x16x32_bf16 v[16:19], v[172:175], v[206:209], v[16:19]
	v_mfma_f32_16x16x32_bf16 v[4:7], v[148:151], v[214:217], v[4:7]
	v_mfma_f32_16x16x32_bf16 v[0:3], v[172:175], v[214:217], v[0:3]
	s_barrier
	s_add_i32 s60, s60, 2
	s_add_u32 s30, s30, 0x100
	s_addc_u32 s31, s31, 0
	s_add_u32 s58, s58, 0x100
	s_addc_u32 s59, s59, 0
	s_cmp_gt_u32 s60, 13
	s_cbranch_scc0 .LBB0_1148
	s_setprio 0
	s_and_b64 vcc, exec, s[18:19]
	s_cbranch_vccz .LBB0_1151
	s_barrier

; #define PG8_STAGE(bufoff, gbase, voff) do { _Pragma("unroll") for (int _i = 0; _i < 2; ++_i) \
;         __builtin_amdgcn_global_load_lds((const unsigned*)((const char*)(gbase) + (voff)[_i]), (PG8_LAS unsigned*)(lds + (bufoff) + ldsw + _i * 8192), 16, 0, 0); } while (0)
; #define PG8_LDA(dst, b, h) do { _Pragma("unroll") for (int m = 0; m < 4; ++m) _Pragma("unroll") for (int k = 0; k < 2; ++k) dst[m][k] = *(const PG8_LAS bf16x8*)(lds + PG8_SA(b, h) + aoff + m * 2048 + k * 1024); } while (0)
; #define PG8_LDB(dst, b, h) do { _Pragma("unroll") for (int n = 0; n < 2; ++n) _Pragma("unroll") for (int k = 0; k < 2; ++k) dst[n][k] = *(const PG8_LAS bf16x8*)(lds + PG8_SB(b, h) + boff + n * 2048 + k * 1024); } while (0)
; #define PG8_WAIT_V(n) asm volatile("s_waitcnt vmcnt(" #n ")" ::: "memory")
; #define PG8_WAIT_L(n) asm volatile("s_waitcnt lgkmcnt(" #n ")" ::: "memory")
; #define PG8_BAR __builtin_amdgcn_s_barrier()
; #define PG8_SCHED __builtin_amdgcn_sched_barrier(0)
; template <class Epi, class Sched, bool ALIGN_EPI = false, bool SP2 = false>
; __device__ __forceinline__ void gemm_phase(PG8_LAS unsigned char* lds, const Gemm g, const Sched& S, const Epi& E, int tid_in) {
;     ...
;         const bool has_next = S.next(ui + 1, nxt);
;         const char* nA = has_next ? (const char*)g.A + (size_t)nxt.pm * tstep : cA; const char* nB = has_next ? (const char*)g.Bt + (size_t)nxt.pn * tstep : cB;
;         for (int t = 0; t < nt; t += 2) {
;             if constexpr (Epi::MIDK) { if (t == Epi::MIDK_T) { if (wr == 0) PG8_BAR; E.mid(acc, cur, wr, wc, fr, fq); if (wr == 1) PG8_BAR; } }
;             const bool last = (t == nt - 2);
;             const char* a1 = cA + (size_t)(t + 1) * kstep;
;             const char* a2 = last ? nA : cA + (size_t)(t + 2) * kstep; const char* b2 = last ? nB : cB + (size_t)(t + 2) * kstep;
;             const char* a3 = a2 + kstep; const char* b3 = b2 + kstep;
;             if (last && has_next) S.a_ready(nxt);
;             if constexpr (SP2) {
;             PG8_LDB(B0, 0, 0); PG8_LDB(B1, 0, 1); PG8_SCHED; PG8_LDA(At, 0, 0); PG8_STAGE(PG8_SA(1, 1), a1 + hstep, voffA);
;             PG8_WAIT_V(8); PG8_WAIT_L(0); PG8_BAR; PG8_MMA(0, 0, At, B0); PG8_MMA(0, 1, At, B1); PG8_BAR; PG8_SCHED;
;             PG8_LDA(At, 0, 1); PG8_STAGE(PG8_SB(0, 0), b2, voffB); PG8_STAGE(PG8_SB(0, 1), b2 + hstep, voffB); PG8_STAGE(PG8_SA(0, 0), a2, voffA);
.LBB0_1237:
	s_ashr_i32 s17, s16, 31
	s_lshl_b64 s[18:19], s[16:17], 19
	s_add_u32 s18, s1, s18
	s_addc_u32 s19, s30, s19
	s_and_b64 s[20:21], s[2:3], exec
	s_cselect_b32 s17, s19, s25
	s_cselect_b32 s54, s18, s24
	s_ashr_i32 s15, s14, 31
	s_lshl_b64 s[20:21], s[14:15], 19
	s_add_u32 s20, s31, s20
	s_addc_u32 s21, s34, s21
	s_and_b64 s[28:29], s[2:3], exec
	s_cselect_b32 s15, s21, s27
	s_cselect_b32 s55, s20, s26
	s_add_u32 s24, s24, 0x40080
	s_addc_u32 s25, s25, 0
	s_add_u32 s56, s26, 0x100
	s_addc_u32 s57, s27, 0
	s_mov_b32 s58, -2
	s_add_u32 s26, s24, 0xfffc0080
	s_addc_u32 s27, s25, -1
	s_cmp_eq_u32 s58, 12
	s_cselect_b32 s29, s17, s27
	s_cselect_b32 s28, s54, s26
	s_cselect_b32 s27, s15, s57
	s_cselect_b32 s26, s55, s56
	s_add_i32 m0, s23, 0xc000
	ds_read_b128 v[144:147], v154
	global_load_lds_dwordx4 v136, s[24:25]
	s_add_i32 m0, s23, 0xe000
	ds_read_b128 v[158:161], v154 offset:1024
	global_load_lds_dwordx4 v138, s[24:25]
	ds_read_b128 v[162:165], v154 offset:2048
	ds_read_b128 v[166:169], v154 offset:3072
	ds_read_b128 v[170:173], v155
	ds_read_b128 v[174:177], v155 offset:1024
	ds_read_b128 v[178:181], v155 offset:2048
	ds_read_b128 v[182:185], v155 offset:3072
	ds_read_b128 v[186:189], v156
	ds_read_b128 v[190:193], v156 offset:1024
	ds_read_b128 v[194:197], v156 offset:2048
	ds_read_b128 v[198:201], v156 offset:3072
	ds_read_b128 v[202:205], v156 offset:4096
	ds_read_b128 v[206:209], v156 offset:5120
	ds_read_b128 v[210:213], v156 offset:6144
	ds_read_b128 v[214:217], v156 offset:7168
	s_waitcnt vmcnt(8)
	s_waitcnt lgkmcnt(0)
	s_barrier
	v_mfma_f32_16x16x32_bf16 v[124:127], v[144:147], v[186:189], 0
	v_mfma_f32_16x16x32_bf16 v[120:123], v[162:165], v[186:189], 0
	v_mfma_f32_16x16x32_bf16 v[108:111], v[144:147], v[194:197], 0
	v_mfma_f32_16x16x32_bf16 v[104:107], v[162:165], v[194:197], 0
	v_mfma_f32_16x16x32_bf16 v[92:95], v[144:147], v[202:205], 0
	v_mfma_f32_16x16x32_bf16 v[88:91], v[162:165], v[202:205], 0
	v_mfma_f32_16x16x32_bf16 v[76:79], v[144:147], v[210:213], 0
	v_mfma_f32_16x16x32_bf16 v[72:75], v[162:165], v[210:213], 0
	v_mfma_f32_16x16x32_bf16 v[124:127], v[158:161], v[190:193], v[124:127]
	v_mfma_f32_16x16x32_bf16 v[120:123], v[166:169], v[190:193], v[120:123]
	v_mfma_f32_16x16x32_bf16 v[108:111], v[158:161], v[198:201], v[108:111]
	v_mfma_f32_16x16x32_bf16 v[104:107], v[166:169], v[198:201], v[104:107]
	v_mfma_f32_16x16x32_bf16 v[92:95], v[158:161], v[206:209], v[92:95]
	v_mfma_f32_16x16x32_bf16 v[88:91], v[166:169], v[206:209], v[88:91]
	v_mfma_f32_16x16x32_bf16 v[76:79], v[158:161], v[214:217], v[76:79]
	v_mfma_f32_16x16x32_bf16 v[72:75], v[166:169], v[214:217], v[72:75]
	v_mfma_f32_16x16x32_bf16 v[116:119], v[170:173], v[186:189], 0
	v_mfma_f32_16x16x32_bf16 v[112:115], v[178:181], v[186:189], 0
	v_mfma_f32_16x16x32_bf16 v[100:103], v[170:173], v[194:197], 0
	v_mfma_f32_16x16x32_bf16 v[96:99], v[178:181], v[194:197], 0
	v_mfma_f32_16x16x32_bf16 v[84:87], v[170:173], v[202:205], 0
	v_mfma_f32_16x16x32_bf16 v[80:83], v[178:181], v[202:205], 0
	v_mfma_f32_16x16x32_bf16 v[68:71], v[170:173], v[210:213], 0
	v_mfma_f32_16x16x32_bf16 v[64:67], v[178:181], v[210:213], 0
	v_mfma_f32_16x16x32_bf16 v[116:119], v[174:177], v[190:193], v[116:119]
	v_mfma_f32_16x16x32_bf16 v[112:115], v[182:185], v[190:193], v[112:115]
	v_mfma_f32_16x16x32_bf16 v[100:103], v[174:177], v[198:201], v[100:103]
	v_mfma_f32_16x16x32_bf16 v[96:99], v[182:185], v[198:201], v[96:99]
	v_mfma_f32_16x16x32_bf16 v[84:87], v[174:177], v[206:209], v[84:87]
	v_mfma_f32_16x16x32_bf16 v[80:83], v[182:185], v[206:209], v[80:83]
	v_mfma_f32_16x16x32_bf16 v[68:71], v[174:177], v[214:217], v[68:71]
	v_mfma_f32_16x16x32_bf16 v[64:67], v[182:185], v[214:217], v[64:67]
	s_barrier
	s_add_u32 s98, s26, s10
	s_addc_u32 s99, s27, s11
	s_add_u32 s100, s28, s10
	s_addc_u32 s101, s29, s11
	s_add_i32 s59, s47, s0
	s_mov_b32 m0, s59
	ds_read_b128 v[186:189], v156 offset:16384
	global_load_lds_dwordx4 v132, s[26:27]
	s_add_i32 m0, s59, 0x2000
	s_add_u32 s60, s26, 0x40000
	s_addc_u32 s61, s27, 0
	s_add_i32 s59, s48, s0
	global_load_lds_dwordx4 v128, s[26:27]
	s_mov_b32 m0, s59
	ds_read_b128 v[190:193], v156 offset:17408
	global_load_lds_dwordx4 v132, s[60:61]
	s_add_i32 m0, s59, 0x2000
	ds_read_b128 v[194:197], v156 offset:18432
	global_load_lds_dwordx4 v128, s[60:61]
	s_mov_b32 m0, s23
	ds_read_b128 v[198:201], v156 offset:19456
	global_load_lds_dwordx4 v134, s[28:29]
	s_mov_b32 m0, s37
	ds_read_b128 v[202:205], v156 offset:20480
	global_load_lds_dwordx4 v130, s[28:29]
	ds_read_b128 v[206:209], v156 offset:21504
	ds_read_b128 v[210:213], v156 offset:22528
	ds_read_b128 v[214:217], v156 offset:23552
	s_waitcnt vmcnt(8)
	s_waitcnt lgkmcnt(0)
	s_barrier
; #define PG8_STAGE(bufoff, gbase, voff) do { _Pragma("unroll") for (int _i = 0; _i < 2; ++_i) \
;         __builtin_amdgcn_global_load_lds((const unsigned*)((const char*)(gbase) + (voff)[_i]), (PG8_LAS unsigned*)(lds + (bufoff) + ldsw + _i * 8192), 16, 0, 0); } while (0)
; #define PG8_LDA(dst, b, h) do { _Pragma("unroll") for (int m = 0; m < 4; ++m) _Pragma("unroll") for (int k = 0; k < 2; ++k) dst[m][k] = *(const PG8_LAS bf16x8*)(lds + PG8_SA(b, h) + aoff + m * 2048 + k * 1024); } while (0)
; #define PG8_LDB(dst, b, h) do { _Pragma("unroll") for (int n = 0; n < 2; ++n) _Pragma("unroll") for (int k = 0; k < 2; ++k) dst[n][k] = *(const PG8_LAS bf16x8*)(lds + PG8_SB(b, h) + boff + n * 2048 + k * 1024); } while (0)
; #define PG8_MMA(ai, bj, At, Bt) do { __builtin_amdgcn_s_setprio(1); _Pragma("unroll") for (int m = 0; m < 4; ++m) _Pragma("unroll") for (int n = 0; n < 2; ++n) _Pragma("unroll") for (int k = 0; k < 2; ++k) \
;         acc[ai][bj][m][n] = __builtin_amdgcn_mfma_f32_16x16x32_bf16(Bt[n][k], At[m][k], acc[ai][bj][m][n], 0, 0, 0); __builtin_amdgcn_s_setprio(0); } while (0)
; #define PG8_WAIT_V(n) asm volatile("s_waitcnt vmcnt(" #n ")" ::: "memory")
; #define PG8_WAIT_L(n) asm volatile("s_waitcnt lgkmcnt(" #n ")" ::: "memory")
; #define PG8_BAR __builtin_amdgcn_s_barrier()
; #define PG8_SCHED __builtin_amdgcn_sched_barrier(0)
; template <class Epi, class Sched, bool ALIGN_EPI = false, bool SP2 = false>
; __device__ __forceinline__ void gemm_phase(PG8_LAS unsigned char* lds, const Gemm g, const Sched& S, const Epi& E, int tid_in) {
;     ...
;             PG8_WAIT_V(8); PG8_WAIT_L(0); PG8_BAR; PG8_MMA(1, 0, At, B0); PG8_MMA(1, 1, At, B1); PG8_BAR; PG8_SCHED;
;             PG8_LDB(B0, 1, 0); PG8_LDB(B1, 1, 1); PG8_SCHED; PG8_LDA(At, 1, 0); PG8_STAGE(PG8_SA(0, 1), a2 + hstep, voffA);
;             PG8_WAIT_V(8); PG8_WAIT_L(0); PG8_BAR; PG8_MMA(0, 0, At, B0); PG8_MMA(0, 1, At, B1); PG8_BAR; PG8_SCHED;
	v_mfma_f32_16x16x32_bf16 v[60:63], v[144:147], v[186:189], 0
	v_mfma_f32_16x16x32_bf16 v[56:59], v[162:165], v[186:189], 0
	v_mfma_f32_16x16x32_bf16 v[44:47], v[144:147], v[194:197], 0
	v_mfma_f32_16x16x32_bf16 v[40:43], v[162:165], v[194:197], 0
	v_mfma_f32_16x16x32_bf16 v[28:31], v[144:147], v[202:205], 0
	v_mfma_f32_16x16x32_bf16 v[24:27], v[162:165], v[202:205], 0
	v_mfma_f32_16x16x32_bf16 v[12:15], v[144:147], v[210:213], 0
	v_mfma_f32_16x16x32_bf16 v[8:11], v[162:165], v[210:213], 0
	v_mfma_f32_16x16x32_bf16 v[60:63], v[158:161], v[190:193], v[60:63]
	v_mfma_f32_16x16x32_bf16 v[56:59], v[166:169], v[190:193], v[56:59]
	v_mfma_f32_16x16x32_bf16 v[44:47], v[158:161], v[198:201], v[44:47]
	v_mfma_f32_16x16x32_bf16 v[40:43], v[166:169], v[198:201], v[40:43]
	v_mfma_f32_16x16x32_bf16 v[28:31], v[158:161], v[206:209], v[28:31]
	v_mfma_f32_16x16x32_bf16 v[24:27], v[166:169], v[206:209], v[24:27]
	v_mfma_f32_16x16x32_bf16 v[12:15], v[158:161], v[214:217], v[12:15]
	v_mfma_f32_16x16x32_bf16 v[8:11], v[166:169], v[214:217], v[8:11]
	v_mfma_f32_16x16x32_bf16 v[52:55], v[170:173], v[186:189], 0
	v_mfma_f32_16x16x32_bf16 v[48:51], v[178:181], v[186:189], 0
	v_mfma_f32_16x16x32_bf16 v[36:39], v[170:173], v[194:197], 0
	v_mfma_f32_16x16x32_bf16 v[32:35], v[178:181], v[194:197], 0
	v_mfma_f32_16x16x32_bf16 v[20:23], v[170:173], v[202:205], 0
	v_mfma_f32_16x16x32_bf16 v[16:19], v[178:181], v[202:205], 0
	v_mfma_f32_16x16x32_bf16 v[4:7], v[170:173], v[210:213], 0
	v_mfma_f32_16x16x32_bf16 v[0:3], v[178:181], v[210:213], 0
	v_mfma_f32_16x16x32_bf16 v[52:55], v[174:177], v[190:193], v[52:55]
	v_mfma_f32_16x16x32_bf16 v[48:51], v[182:185], v[190:193], v[48:51]
	v_mfma_f32_16x16x32_bf16 v[36:39], v[174:177], v[198:201], v[36:39]
	v_mfma_f32_16x16x32_bf16 v[32:35], v[182:185], v[198:201], v[32:35]
	v_mfma_f32_16x16x32_bf16 v[20:23], v[174:177], v[206:209], v[20:23]
	v_mfma_f32_16x16x32_bf16 v[16:19], v[182:185], v[206:209], v[16:19]
	v_mfma_f32_16x16x32_bf16 v[4:7], v[174:177], v[214:217], v[4:7]
	v_mfma_f32_16x16x32_bf16 v[0:3], v[182:185], v[214:217], v[0:3]
	s_barrier
	s_add_i32 s59, 0, 0x18000
	s_add_i32 s60, 0, 0x1c000
	s_add_u32 s28, s28, 0x40000
	s_addc_u32 s29, s29, 0
	s_mov_b32 m0, s38
	v_add_u32_e32 v157, s59, v151
	global_load_lds_dwordx4 v134, s[28:29]
	s_mov_b32 m0, s39
	ds_read_b128 v[144:147], v157
	global_load_lds_dwordx4 v130, s[28:29]
	ds_read_b128 v[158:161], v157 offset:1024
	ds_read_b128 v[162:165], v157 offset:2048
	ds_read_b128 v[166:169], v157 offset:3072
	v_add_u32_e32 v157, s60, v151
	ds_read_b128 v[170:173], v157
	ds_read_b128 v[174:177], v157 offset:1024
	ds_read_b128 v[178:181], v157 offset:2048
	ds_read_b128 v[182:185], v157 offset:3072
	ds_read_b128 v[186:189], v156 offset:32768
	ds_read_b128 v[190:193], v156 offset:33792
	ds_read_b128 v[194:197], v156 offset:34816
	ds_read_b128 v[198:201], v156 offset:35840
	ds_read_b128 v[202:205], v156 offset:36864
	ds_read_b128 v[206:209], v156 offset:37888
	ds_read_b128 v[210:213], v156 offset:38912
	ds_read_b128 v[214:217], v156 offset:39936
	s_waitcnt vmcnt(8)
	s_waitcnt lgkmcnt(0)
	s_barrier
	v_mfma_f32_16x16x32_bf16 v[124:127], v[144:147], v[186:189], v[124:127]
	v_mfma_f32_16x16x32_bf16 v[120:123], v[162:165], v[186:189], v[120:123]
	v_mfma_f32_16x16x32_bf16 v[108:111], v[144:147], v[194:197], v[108:111]
	v_mfma_f32_16x16x32_bf16 v[104:107], v[162:165], v[194:197], v[104:107]
	v_mfma_f32_16x16x32_bf16 v[92:95], v[144:147], v[202:205], v[92:95]
	v_mfma_f32_16x16x32_bf16 v[88:91], v[162:165], v[202:205], v[88:91]
	v_mfma_f32_16x16x32_bf16 v[76:79], v[144:147], v[210:213], v[76:79]
	v_mfma_f32_16x16x32_bf16 v[72:75], v[162:165], v[210:213], v[72:75]
	v_mfma_f32_16x16x32_bf16 v[124:127], v[158:161], v[190:193], v[124:127]
	v_mfma_f32_16x16x32_bf16 v[120:123], v[166:169], v[190:193], v[120:123]
	v_mfma_f32_16x16x32_bf16 v[108:111], v[158:161], v[198:201], v[108:111]
	v_mfma_f32_16x16x32_bf16 v[104:107], v[166:169], v[198:201], v[104:107]
	v_mfma_f32_16x16x32_bf16 v[92:95], v[158:161], v[206:209], v[92:95]
	v_mfma_f32_16x16x32_bf16 v[88:91], v[166:169], v[206:209], v[88:91]
	v_mfma_f32_16x16x32_bf16 v[76:79], v[158:161], v[214:217], v[76:79]
	v_mfma_f32_16x16x32_bf16 v[72:75], v[166:169], v[214:217], v[72:75]
	v_mfma_f32_16x16x32_bf16 v[116:119], v[170:173], v[186:189], v[116:119]
	v_mfma_f32_16x16x32_bf16 v[112:115], v[178:181], v[186:189], v[112:115]
	v_mfma_f32_16x16x32_bf16 v[100:103], v[170:173], v[194:197], v[100:103]
	v_mfma_f32_16x16x32_bf16 v[96:99], v[178:181], v[194:197], v[96:99]
	v_mfma_f32_16x16x32_bf16 v[84:87], v[170:173], v[202:205], v[84:87]
	v_mfma_f32_16x16x32_bf16 v[80:83], v[178:181], v[202:205], v[80:83]
	v_mfma_f32_16x16x32_bf16 v[68:71], v[170:173], v[210:213], v[68:71]
	v_mfma_f32_16x16x32_bf16 v[64:67], v[178:181], v[210:213], v[64:67]
	v_mfma_f32_16x16x32_bf16 v[116:119], v[174:177], v[190:193], v[116:119]
	v_mfma_f32_16x16x32_bf16 v[112:115], v[182:185], v[190:193], v[112:115]
	v_mfma_f32_16x16x32_bf16 v[100:103], v[174:177], v[198:201], v[100:103]
	v_mfma_f32_16x16x32_bf16 v[96:99], v[182:185], v[198:201], v[96:99]
	v_mfma_f32_16x16x32_bf16 v[84:87], v[174:177], v[206:209], v[84:87]
	v_mfma_f32_16x16x32_bf16 v[80:83], v[182:185], v[206:209], v[80:83]
	v_mfma_f32_16x16x32_bf16 v[68:71], v[174:177], v[214:217], v[68:71]
	v_mfma_f32_16x16x32_bf16 v[64:67], v[182:185], v[214:217], v[64:67]
	s_barrier
; #define PG8_STAGE(bufoff, gbase, voff) do { _Pragma("unroll") for (int _i = 0; _i < 2; ++_i) \
;         __builtin_amdgcn_global_load_lds((const unsigned*)((const char*)(gbase) + (voff)[_i]), (PG8_LAS unsigned*)(lds + (bufoff) + ldsw + _i * 8192), 16, 0, 0); } while (0)
; #define PG8_LDA(dst, b, h) do { _Pragma("unroll") for (int m = 0; m < 4; ++m) _Pragma("unroll") for (int k = 0; k < 2; ++k) dst[m][k] = *(const PG8_LAS bf16x8*)(lds + PG8_SA(b, h) + aoff + m * 2048 + k * 1024); } while (0)
; #define PG8_LDB(dst, b, h) do { _Pragma("unroll") for (int n = 0; n < 2; ++n) _Pragma("unroll") for (int k = 0; k < 2; ++k) dst[n][k] = *(const PG8_LAS bf16x8*)(lds + PG8_SB(b, h) + boff + n * 2048 + k * 1024); } while (0)
; #define PG8_MMA(ai, bj, At, Bt) do { __builtin_amdgcn_s_setprio(1); _Pragma("unroll") for (int m = 0; m < 4; ++m) _Pragma("unroll") for (int n = 0; n < 2; ++n) _Pragma("unroll") for (int k = 0; k < 2; ++k) \
;         acc[ai][bj][m][n] = __builtin_amdgcn_mfma_f32_16x16x32_bf16(Bt[n][k], At[m][k], acc[ai][bj][m][n], 0, 0, 0); __builtin_amdgcn_s_setprio(0); } while (0)
; #define PG8_WAIT_V(n) asm volatile("s_waitcnt vmcnt(" #n ")" ::: "memory")
; #define PG8_WAIT_L(n) asm volatile("s_waitcnt lgkmcnt(" #n ")" ::: "memory")
; #define PG8_BAR __builtin_amdgcn_s_barrier()
; template <class Epi, class Sched, bool ALIGN_EPI = false, bool SP2 = false>
; __device__ __forceinline__ void gemm_phase(PG8_LAS unsigned char* lds, const Gemm g, const Sched& S, const Epi& E, int tid_in) {
;     ...
;             const char* a1 = cA + (size_t)(t + 1) * kstep;
;             const char* a2 = last ? nA : cA + (size_t)(t + 2) * kstep; const char* b2 = last ? nB : cB + (size_t)(t + 2) * kstep;
;             const char* a3 = a2 + kstep; const char* b3 = b2 + kstep;
;             if (last && has_next) S.a_ready(nxt);
;             if constexpr (SP2) {
;             PG8_LDB(B0, 0, 0); PG8_LDB(B1, 0, 1); PG8_SCHED; PG8_LDA(At, 0, 0); PG8_STAGE(PG8_SA(1, 1), a1 + hstep, voffA);
;             PG8_WAIT_V(8); PG8_WAIT_L(0); PG8_BAR; PG8_MMA(0, 0, At, B0); PG8_MMA(0, 1, At, B1); PG8_BAR; PG8_SCHED;
;     ...
;             PG8_LDA(At, 1, 1); PG8_STAGE(PG8_SB(1, 0), b3, voffB); PG8_STAGE(PG8_SB(1, 1), b3 + hstep, voffB); PG8_STAGE(PG8_SA(1, 0), a3, voffA);
;             PG8_WAIT_V(8); PG8_WAIT_L(0); PG8_BAR; PG8_MMA(1, 0, At, B0); PG8_MMA(1, 1, At, B1); PG8_BAR; PG8_SCHED;
	s_add_i32 s28, s59, s0
	s_mov_b32 m0, s28
	ds_read_b128 v[186:189], v156 offset:49152
	global_load_lds_dwordx4 v132, s[98:99]
	s_add_i32 m0, s28, 0x2000
	s_add_u32 s26, s26, 0x40080
	s_addc_u32 s27, s27, 0
	s_add_i32 s28, s60, s0
	global_load_lds_dwordx4 v128, s[98:99]
	s_mov_b32 m0, s28
	ds_read_b128 v[190:193], v156 offset:50176
	global_load_lds_dwordx4 v132, s[26:27]
	s_add_i32 m0, s28, 0x2000
	ds_read_b128 v[194:197], v156 offset:51200
	global_load_lds_dwordx4 v128, s[26:27]
	s_mov_b32 m0, s44
	ds_read_b128 v[198:201], v156 offset:52224
	global_load_lds_dwordx4 v134, s[100:101]
	s_mov_b32 m0, s45
	ds_read_b128 v[202:205], v156 offset:53248
	global_load_lds_dwordx4 v130, s[100:101]
	ds_read_b128 v[206:209], v156 offset:54272
	ds_read_b128 v[210:213], v156 offset:55296
	ds_read_b128 v[214:217], v156 offset:56320
	s_waitcnt vmcnt(8)
	s_waitcnt lgkmcnt(0)
	s_barrier
	v_mfma_f32_16x16x32_bf16 v[60:63], v[144:147], v[186:189], v[60:63]
	v_mfma_f32_16x16x32_bf16 v[56:59], v[162:165], v[186:189], v[56:59]
	v_mfma_f32_16x16x32_bf16 v[44:47], v[144:147], v[194:197], v[44:47]
	v_mfma_f32_16x16x32_bf16 v[40:43], v[162:165], v[194:197], v[40:43]
	v_mfma_f32_16x16x32_bf16 v[28:31], v[144:147], v[202:205], v[28:31]
	v_mfma_f32_16x16x32_bf16 v[24:27], v[162:165], v[202:205], v[24:27]
	v_mfma_f32_16x16x32_bf16 v[12:15], v[144:147], v[210:213], v[12:15]
	v_mfma_f32_16x16x32_bf16 v[8:11], v[162:165], v[210:213], v[8:11]
	v_mfma_f32_16x16x32_bf16 v[60:63], v[158:161], v[190:193], v[60:63]
	v_mfma_f32_16x16x32_bf16 v[56:59], v[166:169], v[190:193], v[56:59]
	v_mfma_f32_16x16x32_bf16 v[44:47], v[158:161], v[198:201], v[44:47]
	v_mfma_f32_16x16x32_bf16 v[40:43], v[166:169], v[198:201], v[40:43]
	v_mfma_f32_16x16x32_bf16 v[28:31], v[158:161], v[206:209], v[28:31]
	v_mfma_f32_16x16x32_bf16 v[24:27], v[166:169], v[206:209], v[24:27]
	v_mfma_f32_16x16x32_bf16 v[12:15], v[158:161], v[214:217], v[12:15]
	v_mfma_f32_16x16x32_bf16 v[8:11], v[166:169], v[214:217], v[8:11]
	v_mfma_f32_16x16x32_bf16 v[52:55], v[170:173], v[186:189], v[52:55]
	v_mfma_f32_16x16x32_bf16 v[48:51], v[178:181], v[186:189], v[48:51]
	v_mfma_f32_16x16x32_bf16 v[36:39], v[170:173], v[194:197], v[36:39]
	v_mfma_f32_16x16x32_bf16 v[32:35], v[178:181], v[194:197], v[32:35]
	v_mfma_f32_16x16x32_bf16 v[20:23], v[170:173], v[202:205], v[20:23]
	v_mfma_f32_16x16x32_bf16 v[16:19], v[178:181], v[202:205], v[16:19]
	v_mfma_f32_16x16x32_bf16 v[4:7], v[170:173], v[210:213], v[4:7]
	v_mfma_f32_16x16x32_bf16 v[0:3], v[178:181], v[210:213], v[0:3]
	v_mfma_f32_16x16x32_bf16 v[52:55], v[174:177], v[190:193], v[52:55]
	v_mfma_f32_16x16x32_bf16 v[48:51], v[182:185], v[190:193], v[48:51]
	v_mfma_f32_16x16x32_bf16 v[36:39], v[174:177], v[198:201], v[36:39]
	v_mfma_f32_16x16x32_bf16 v[32:35], v[182:185], v[198:201], v[32:35]
	v_mfma_f32_16x16x32_bf16 v[20:23], v[174:177], v[206:209], v[20:23]
	v_mfma_f32_16x16x32_bf16 v[16:19], v[182:185], v[206:209], v[16:19]
	v_mfma_f32_16x16x32_bf16 v[4:7], v[174:177], v[214:217], v[4:7]
	v_mfma_f32_16x16x32_bf16 v[0:3], v[182:185], v[214:217], v[0:3]
	s_barrier
	s_add_i32 s58, s58, 2
	s_add_u32 s24, s24, 0x100
	s_addc_u32 s25, s25, 0
	s_add_u32 s56, s56, 0x100
	s_addc_u32 s57, s57, 0
	v_readlane_b32 s98, v248, 0
	s_nop 3
	s_cmp_ge_u32 s98, 0x100
	s_cbranch_scc0 .Lgprio_skip_4
	s_setprio 1
.Lgprio_skip_4:
.LBB0_1238:
	s_add_u32 s26, s24, 0xfffc0080
	s_addc_u32 s27, s25, -1
	s_cmp_eq_u32 s58, 12
	s_cselect_b32 s29, s17, s27
	s_cselect_b32 s28, s54, s26
	s_cselect_b32 s27, s15, s57
	s_cselect_b32 s26, s55, s56
	s_add_i32 m0, s23, 0xc000
	ds_read_b128 v[144:147], v154
	global_load_lds_dwordx4 v136, s[24:25]
	s_add_i32 m0, s23, 0xe000
	ds_read_b128 v[158:161], v154 offset:1024
	global_load_lds_dwordx4 v138, s[24:25]
	ds_read_b128 v[162:165], v154 offset:2048
	ds_read_b128 v[166:169], v154 offset:3072
	ds_read_b128 v[170:173], v155
	ds_read_b128 v[174:177], v155 offset:1024
	ds_read_b128 v[178:181], v155 offset:2048
	ds_read_b128 v[182:185], v155 offset:3072
	ds_read_b128 v[186:189], v156
	ds_read_b128 v[190:193], v156 offset:1024
	ds_read_b128 v[194:197], v156 offset:2048
	ds_read_b128 v[198:201], v156 offset:3072
	ds_read_b128 v[202:205], v156 offset:4096
	ds_read_b128 v[206:209], v156 offset:5120
	ds_read_b128 v[210:213], v156 offset:6144
	ds_read_b128 v[214:217], v156 offset:7168
	s_waitcnt vmcnt(8)
	s_waitcnt lgkmcnt(0)
	s_barrier
	v_mfma_f32_16x16x32_bf16 v[124:127], v[144:147], v[186:189], v[124:127]
	v_mfma_f32_16x16x32_bf16 v[120:123], v[162:165], v[186:189], v[120:123]
	v_mfma_f32_16x16x32_bf16 v[108:111], v[144:147], v[194:197], v[108:111]
	v_mfma_f32_16x16x32_bf16 v[104:107], v[162:165], v[194:197], v[104:107]
	v_mfma_f32_16x16x32_bf16 v[92:95], v[144:147], v[202:205], v[92:95]
	v_mfma_f32_16x16x32_bf16 v[88:91], v[162:165], v[202:205], v[88:91]
	v_mfma_f32_16x16x32_bf16 v[76:79], v[144:147], v[210:213], v[76:79]
	v_mfma_f32_16x16x32_bf16 v[72:75], v[162:165], v[210:213], v[72:75]
	v_mfma_f32_16x16x32_bf16 v[124:127], v[158:161], v[190:193], v[124:127]
	v_mfma_f32_16x16x32_bf16 v[120:123], v[166:169], v[190:193], v[120:123]
	v_mfma_f32_16x16x32_bf16 v[108:111], v[158:161], v[198:201], v[108:111]
	v_mfma_f32_16x16x32_bf16 v[104:107], v[166:169], v[198:201], v[104:107]
	v_mfma_f32_16x16x32_bf16 v[92:95], v[158:161], v[206:209], v[92:95]
	v_mfma_f32_16x16x32_bf16 v[88:91], v[166:169], v[206:209], v[88:91]
	v_mfma_f32_16x16x32_bf16 v[76:79], v[158:161], v[214:217], v[76:79]
	v_mfma_f32_16x16x32_bf16 v[72:75], v[166:169], v[214:217], v[72:75]
	v_mfma_f32_16x16x32_bf16 v[116:119], v[170:173], v[186:189], v[116:119]
	v_mfma_f32_16x16x32_bf16 v[112:115], v[178:181], v[186:189], v[112:115]
	v_mfma_f32_16x16x32_bf16 v[100:103], v[170:173], v[194:197], v[100:103]
	v_mfma_f32_16x16x32_bf16 v[96:99], v[178:181], v[194:197], v[96:99]
	v_mfma_f32_16x16x32_bf16 v[84:87], v[170:173], v[202:205], v[84:87]
	v_mfma_f32_16x16x32_bf16 v[80:83], v[178:181], v[202:205], v[80:83]
	v_mfma_f32_16x16x32_bf16 v[68:71], v[170:173], v[210:213], v[68:71]
	v_mfma_f32_16x16x32_bf16 v[64:67], v[178:181], v[210:213], v[64:67]
	v_mfma_f32_16x16x32_bf16 v[116:119], v[174:177], v[190:193], v[116:119]
	v_mfma_f32_16x16x32_bf16 v[112:115], v[182:185], v[190:193], v[112:115]
	v_mfma_f32_16x16x32_bf16 v[100:103], v[174:177], v[198:201], v[100:103]
	v_mfma_f32_16x16x32_bf16 v[96:99], v[182:185], v[198:201], v[96:99]
	v_mfma_f32_16x16x32_bf16 v[84:87], v[174:177], v[206:209], v[84:87]
	v_mfma_f32_16x16x32_bf16 v[80:83], v[182:185], v[206:209], v[80:83]
	v_mfma_f32_16x16x32_bf16 v[68:71], v[174:177], v[214:217], v[68:71]
	v_mfma_f32_16x16x32_bf16 v[64:67], v[182:185], v[214:217], v[64:67]
	s_barrier
; #define PG8_STAGE(bufoff, gbase, voff) do { _Pragma("unroll") for (int _i = 0; _i < 2; ++_i) \
;         __builtin_amdgcn_global_load_lds((const unsigned*)((const char*)(gbase) + (voff)[_i]), (PG8_LAS unsigned*)(lds + (bufoff) + ldsw + _i * 8192), 16, 0, 0); } while (0)
; #define PG8_LDA(dst, b, h) do { _Pragma("unroll") for (int m = 0; m < 4; ++m) _Pragma("unroll") for (int k = 0; k < 2; ++k) dst[m][k] = *(const PG8_LAS bf16x8*)(lds + PG8_SA(b, h) + aoff + m * 2048 + k * 1024); } while (0)
; #define PG8_LDB(dst, b, h) do { _Pragma("unroll") for (int n = 0; n < 2; ++n) _Pragma("unroll") for (int k = 0; k < 2; ++k) dst[n][k] = *(const PG8_LAS bf16x8*)(lds + PG8_SB(b, h) + boff + n * 2048 + k * 1024); } while (0)
; #define PG8_MMA(ai, bj, At, Bt) do { __builtin_amdgcn_s_setprio(1); _Pragma("unroll") for (int m = 0; m < 4; ++m) _Pragma("unroll") for (int n = 0; n < 2; ++n) _Pragma("unroll") for (int k = 0; k < 2; ++k) \
;         acc[ai][bj][m][n] = __builtin_amdgcn_mfma_f32_16x16x32_bf16(Bt[n][k], At[m][k], acc[ai][bj][m][n], 0, 0, 0); __builtin_amdgcn_s_setprio(0); } while (0)
; #define PG8_WAIT_V(n) asm volatile("s_waitcnt vmcnt(" #n ")" ::: "memory")
; #define PG8_WAIT_L(n) asm volatile("s_waitcnt lgkmcnt(" #n ")" ::: "memory")
; #define PG8_BAR __builtin_amdgcn_s_barrier()
; #define PG8_SCHED __builtin_amdgcn_sched_barrier(0)
; template <class Epi, class Sched, bool ALIGN_EPI = false, bool SP2 = false>
; __device__ __forceinline__ void gemm_phase(PG8_LAS unsigned char* lds, const Gemm g, const Sched& S, const Epi& E, int tid_in) {
;     ...
;             PG8_LDA(At, 0, 1); PG8_STAGE(PG8_SB(0, 0), b2, voffB); PG8_STAGE(PG8_SB(0, 1), b2 + hstep, voffB); PG8_STAGE(PG8_SA(0, 0), a2, voffA);
;             PG8_WAIT_V(8); PG8_WAIT_L(0); PG8_BAR; PG8_MMA(1, 0, At, B0); PG8_MMA(1, 1, At, B1); PG8_BAR; PG8_SCHED;
;             PG8_LDB(B0, 1, 0); PG8_LDB(B1, 1, 1); PG8_SCHED; PG8_LDA(At, 1, 0); PG8_STAGE(PG8_SA(0, 1), a2 + hstep, voffA);
	s_add_u32 s98, s26, s10
	s_addc_u32 s99, s27, s11
	s_add_u32 s100, s28, s10
	s_addc_u32 s101, s29, s11
	s_add_i32 s59, s47, s0
	s_mov_b32 m0, s59
	ds_read_b128 v[186:189], v156 offset:16384
	global_load_lds_dwordx4 v132, s[26:27]
	s_add_i32 m0, s59, 0x2000
	s_add_u32 s60, s26, 0x40000
	s_addc_u32 s61, s27, 0
	s_add_i32 s59, s48, s0
	global_load_lds_dwordx4 v128, s[26:27]
	s_mov_b32 m0, s59
	ds_read_b128 v[190:193], v156 offset:17408
	global_load_lds_dwordx4 v132, s[60:61]
	s_add_i32 m0, s59, 0x2000
	ds_read_b128 v[194:197], v156 offset:18432
	global_load_lds_dwordx4 v128, s[60:61]
	s_mov_b32 m0, s23
	ds_read_b128 v[198:201], v156 offset:19456
	global_load_lds_dwordx4 v134, s[28:29]
	s_mov_b32 m0, s37
	ds_read_b128 v[202:205], v156 offset:20480
	global_load_lds_dwordx4 v130, s[28:29]
	ds_read_b128 v[206:209], v156 offset:21504
	ds_read_b128 v[210:213], v156 offset:22528
	ds_read_b128 v[214:217], v156 offset:23552
	s_waitcnt vmcnt(8)
	s_waitcnt lgkmcnt(0)
	s_barrier
	v_mfma_f32_16x16x32_bf16 v[60:63], v[144:147], v[186:189], v[60:63]
	v_mfma_f32_16x16x32_bf16 v[56:59], v[162:165], v[186:189], v[56:59]
	v_mfma_f32_16x16x32_bf16 v[44:47], v[144:147], v[194:197], v[44:47]
	v_mfma_f32_16x16x32_bf16 v[40:43], v[162:165], v[194:197], v[40:43]
	v_mfma_f32_16x16x32_bf16 v[28:31], v[144:147], v[202:205], v[28:31]
	v_mfma_f32_16x16x32_bf16 v[24:27], v[162:165], v[202:205], v[24:27]
	v_mfma_f32_16x16x32_bf16 v[12:15], v[144:147], v[210:213], v[12:15]
	v_mfma_f32_16x16x32_bf16 v[8:11], v[162:165], v[210:213], v[8:11]
	v_mfma_f32_16x16x32_bf16 v[60:63], v[158:161], v[190:193], v[60:63]
	v_mfma_f32_16x16x32_bf16 v[56:59], v[166:169], v[190:193], v[56:59]
	v_mfma_f32_16x16x32_bf16 v[44:47], v[158:161], v[198:201], v[44:47]
	v_mfma_f32_16x16x32_bf16 v[40:43], v[166:169], v[198:201], v[40:43]
	v_mfma_f32_16x16x32_bf16 v[28:31], v[158:161], v[206:209], v[28:31]
	v_mfma_f32_16x16x32_bf16 v[24:27], v[166:169], v[206:209], v[24:27]
	v_mfma_f32_16x16x32_bf16 v[12:15], v[158:161], v[214:217], v[12:15]
	v_mfma_f32_16x16x32_bf16 v[8:11], v[166:169], v[214:217], v[8:11]
	v_mfma_f32_16x16x32_bf16 v[52:55], v[170:173], v[186:189], v[52:55]
	v_mfma_f32_16x16x32_bf16 v[48:51], v[178:181], v[186:189], v[48:51]
	v_mfma_f32_16x16x32_bf16 v[36:39], v[170:173], v[194:197], v[36:39]
	v_mfma_f32_16x16x32_bf16 v[32:35], v[178:181], v[194:197], v[32:35]
	v_mfma_f32_16x16x32_bf16 v[20:23], v[170:173], v[202:205], v[20:23]
	v_mfma_f32_16x16x32_bf16 v[16:19], v[178:181], v[202:205], v[16:19]
	v_mfma_f32_16x16x32_bf16 v[4:7], v[170:173], v[210:213], v[4:7]
	v_mfma_f32_16x16x32_bf16 v[0:3], v[178:181], v[210:213], v[0:3]
	v_mfma_f32_16x16x32_bf16 v[52:55], v[174:177], v[190:193], v[52:55]
	v_mfma_f32_16x16x32_bf16 v[48:51], v[182:185], v[190:193], v[48:51]
	v_mfma_f32_16x16x32_bf16 v[36:39], v[174:177], v[198:201], v[36:39]
	v_mfma_f32_16x16x32_bf16 v[32:35], v[182:185], v[198:201], v[32:35]
	v_mfma_f32_16x16x32_bf16 v[20:23], v[174:177], v[206:209], v[20:23]
	v_mfma_f32_16x16x32_bf16 v[16:19], v[182:185], v[206:209], v[16:19]
	v_mfma_f32_16x16x32_bf16 v[4:7], v[174:177], v[214:217], v[4:7]
	v_mfma_f32_16x16x32_bf16 v[0:3], v[182:185], v[214:217], v[0:3]
	s_barrier
	s_add_i32 s59, 0, 0x18000
	s_add_i32 s60, 0, 0x1c000
	s_add_u32 s28, s28, 0x40000
	s_addc_u32 s29, s29, 0
	s_mov_b32 m0, s38
	v_add_u32_e32 v157, s59, v151
	global_load_lds_dwordx4 v134, s[28:29]
	s_mov_b32 m0, s39
	ds_read_b128 v[144:147], v157
	global_load_lds_dwordx4 v130, s[28:29]
	ds_read_b128 v[158:161], v157 offset:1024
	ds_read_b128 v[162:165], v157 offset:2048
	ds_read_b128 v[166:169], v157 offset:3072
	v_add_u32_e32 v157, s60, v151
	ds_read_b128 v[170:173], v157
	ds_read_b128 v[174:177], v157 offset:1024
	ds_read_b128 v[178:181], v157 offset:2048
	ds_read_b128 v[182:185], v157 offset:3072
	ds_read_b128 v[186:189], v156 offset:32768
	ds_read_b128 v[190:193], v156 offset:33792
	ds_read_b128 v[194:197], v156 offset:34816
	ds_read_b128 v[198:201], v156 offset:35840
	ds_read_b128 v[202:205], v156 offset:36864
	ds_read_b128 v[206:209], v156 offset:37888
	ds_read_b128 v[210:213], v156 offset:38912
	ds_read_b128 v[214:217], v156 offset:39936
	s_waitcnt vmcnt(8)
	s_waitcnt lgkmcnt(0)
	s_barrier
; #define PG8_STAGE(bufoff, gbase, voff) do { _Pragma("unroll") for (int _i = 0; _i < 2; ++_i) \
;         __builtin_amdgcn_global_load_lds((const unsigned*)((const char*)(gbase) + (voff)[_i]), (PG8_LAS unsigned*)(lds + (bufoff) + ldsw + _i * 8192), 16, 0, 0); } while (0)
; #define PG8_LDA(dst, b, h) do { _Pragma("unroll") for (int m = 0; m < 4; ++m) _Pragma("unroll") for (int k = 0; k < 2; ++k) dst[m][k] = *(const PG8_LAS bf16x8*)(lds + PG8_SA(b, h) + aoff + m * 2048 + k * 1024); } while (0)
; #define PG8_MMA(ai, bj, At, Bt) do { __builtin_amdgcn_s_setprio(1); _Pragma("unroll") for (int m = 0; m < 4; ++m) _Pragma("unroll") for (int n = 0; n < 2; ++n) _Pragma("unroll") for (int k = 0; k < 2; ++k) \
;         acc[ai][bj][m][n] = __builtin_amdgcn_mfma_f32_16x16x32_bf16(Bt[n][k], At[m][k], acc[ai][bj][m][n], 0, 0, 0); __builtin_amdgcn_s_setprio(0); } while (0)
; #define PG8_WAIT_V(n) asm volatile("s_waitcnt vmcnt(" #n ")" ::: "memory")
; #define PG8_WAIT_L(n) asm volatile("s_waitcnt lgkmcnt(" #n ")" ::: "memory")
; #define PG8_BAR __builtin_amdgcn_s_barrier()
; #define PG8_SCHED __builtin_amdgcn_sched_barrier(0)
; template <class Epi, class Sched, bool ALIGN_EPI = false, bool SP2 = false>
; __device__ __forceinline__ void gemm_phase(PG8_LAS unsigned char* lds, const Gemm g, const Sched& S, const Epi& E, int tid_in) {
;     ...
;             PG8_WAIT_V(8); PG8_WAIT_L(0); PG8_BAR; PG8_MMA(0, 0, At, B0); PG8_MMA(0, 1, At, B1); PG8_BAR; PG8_SCHED;
;             PG8_LDA(At, 1, 1); PG8_STAGE(PG8_SB(1, 0), b3, voffB); PG8_STAGE(PG8_SB(1, 1), b3 + hstep, voffB); PG8_STAGE(PG8_SA(1, 0), a3, voffA);
;             PG8_WAIT_V(8); PG8_WAIT_L(0); PG8_BAR; PG8_MMA(1, 0, At, B0); PG8_MMA(1, 1, At, B1); PG8_BAR; PG8_SCHED;
;     ...
;         if constexpr (ALIGN_EPI) { if (wr == 0) PG8_BAR; }
	v_mfma_f32_16x16x32_bf16 v[124:127], v[144:147], v[186:189], v[124:127]
	v_mfma_f32_16x16x32_bf16 v[120:123], v[162:165], v[186:189], v[120:123]
	v_mfma_f32_16x16x32_bf16 v[108:111], v[144:147], v[194:197], v[108:111]
	v_mfma_f32_16x16x32_bf16 v[104:107], v[162:165], v[194:197], v[104:107]
	v_mfma_f32_16x16x32_bf16 v[92:95], v[144:147], v[202:205], v[92:95]
	v_mfma_f32_16x16x32_bf16 v[88:91], v[162:165], v[202:205], v[88:91]
	v_mfma_f32_16x16x32_bf16 v[76:79], v[144:147], v[210:213], v[76:79]
	v_mfma_f32_16x16x32_bf16 v[72:75], v[162:165], v[210:213], v[72:75]
	v_mfma_f32_16x16x32_bf16 v[124:127], v[158:161], v[190:193], v[124:127]
	v_mfma_f32_16x16x32_bf16 v[120:123], v[166:169], v[190:193], v[120:123]
	v_mfma_f32_16x16x32_bf16 v[108:111], v[158:161], v[198:201], v[108:111]
	v_mfma_f32_16x16x32_bf16 v[104:107], v[166:169], v[198:201], v[104:107]
	v_mfma_f32_16x16x32_bf16 v[92:95], v[158:161], v[206:209], v[92:95]
	v_mfma_f32_16x16x32_bf16 v[88:91], v[166:169], v[206:209], v[88:91]
	v_mfma_f32_16x16x32_bf16 v[76:79], v[158:161], v[214:217], v[76:79]
	v_mfma_f32_16x16x32_bf16 v[72:75], v[166:169], v[214:217], v[72:75]
	v_mfma_f32_16x16x32_bf16 v[116:119], v[170:173], v[186:189], v[116:119]
	v_mfma_f32_16x16x32_bf16 v[112:115], v[178:181], v[186:189], v[112:115]
	v_mfma_f32_16x16x32_bf16 v[100:103], v[170:173], v[194:197], v[100:103]
	v_mfma_f32_16x16x32_bf16 v[96:99], v[178:181], v[194:197], v[96:99]
	v_mfma_f32_16x16x32_bf16 v[84:87], v[170:173], v[202:205], v[84:87]
	v_mfma_f32_16x16x32_bf16 v[80:83], v[178:181], v[202:205], v[80:83]
	v_mfma_f32_16x16x32_bf16 v[68:71], v[170:173], v[210:213], v[68:71]
	v_mfma_f32_16x16x32_bf16 v[64:67], v[178:181], v[210:213], v[64:67]
	v_mfma_f32_16x16x32_bf16 v[116:119], v[174:177], v[190:193], v[116:119]
	v_mfma_f32_16x16x32_bf16 v[112:115], v[182:185], v[190:193], v[112:115]
	v_mfma_f32_16x16x32_bf16 v[100:103], v[174:177], v[198:201], v[100:103]
	v_mfma_f32_16x16x32_bf16 v[96:99], v[182:185], v[198:201], v[96:99]
	v_mfma_f32_16x16x32_bf16 v[84:87], v[174:177], v[206:209], v[84:87]
	v_mfma_f32_16x16x32_bf16 v[80:83], v[182:185], v[206:209], v[80:83]
	v_mfma_f32_16x16x32_bf16 v[68:71], v[174:177], v[214:217], v[68:71]
	v_mfma_f32_16x16x32_bf16 v[64:67], v[182:185], v[214:217], v[64:67]
	s_barrier
	s_add_i32 s28, s59, s0
	s_mov_b32 m0, s28
	ds_read_b128 v[186:189], v156 offset:49152
	global_load_lds_dwordx4 v132, s[98:99]
	s_add_i32 m0, s28, 0x2000
	s_add_u32 s26, s26, 0x40080
	s_addc_u32 s27, s27, 0
	s_add_i32 s28, s60, s0
	global_load_lds_dwordx4 v128, s[98:99]
	s_mov_b32 m0, s28
	ds_read_b128 v[190:193], v156 offset:50176
	global_load_lds_dwordx4 v132, s[26:27]
	s_add_i32 m0, s28, 0x2000
	ds_read_b128 v[194:197], v156 offset:51200
	global_load_lds_dwordx4 v128, s[26:27]
	s_mov_b32 m0, s44
	ds_read_b128 v[198:201], v156 offset:52224
	global_load_lds_dwordx4 v134, s[100:101]
	s_mov_b32 m0, s45
	ds_read_b128 v[202:205], v156 offset:53248
	global_load_lds_dwordx4 v130, s[100:101]
	ds_read_b128 v[206:209], v156 offset:54272
	ds_read_b128 v[210:213], v156 offset:55296
	ds_read_b128 v[214:217], v156 offset:56320
	s_waitcnt vmcnt(8)
	s_waitcnt lgkmcnt(0)
	s_barrier
	v_mfma_f32_16x16x32_bf16 v[60:63], v[144:147], v[186:189], v[60:63]
	v_mfma_f32_16x16x32_bf16 v[56:59], v[162:165], v[186:189], v[56:59]
	v_mfma_f32_16x16x32_bf16 v[44:47], v[144:147], v[194:197], v[44:47]
	v_mfma_f32_16x16x32_bf16 v[40:43], v[162:165], v[194:197], v[40:43]
	v_mfma_f32_16x16x32_bf16 v[28:31], v[144:147], v[202:205], v[28:31]
	v_mfma_f32_16x16x32_bf16 v[24:27], v[162:165], v[202:205], v[24:27]
	v_mfma_f32_16x16x32_bf16 v[12:15], v[144:147], v[210:213], v[12:15]
	v_mfma_f32_16x16x32_bf16 v[8:11], v[162:165], v[210:213], v[8:11]
	v_mfma_f32_16x16x32_bf16 v[60:63], v[158:161], v[190:193], v[60:63]
	v_mfma_f32_16x16x32_bf16 v[56:59], v[166:169], v[190:193], v[56:59]
	v_mfma_f32_16x16x32_bf16 v[44:47], v[158:161], v[198:201], v[44:47]
	v_mfma_f32_16x16x32_bf16 v[40:43], v[166:169], v[198:201], v[40:43]
	v_mfma_f32_16x16x32_bf16 v[28:31], v[158:161], v[206:209], v[28:31]
	v_mfma_f32_16x16x32_bf16 v[24:27], v[166:169], v[206:209], v[24:27]
	v_mfma_f32_16x16x32_bf16 v[12:15], v[158:161], v[214:217], v[12:15]
	v_mfma_f32_16x16x32_bf16 v[8:11], v[166:169], v[214:217], v[8:11]
	v_mfma_f32_16x16x32_bf16 v[52:55], v[170:173], v[186:189], v[52:55]
	v_mfma_f32_16x16x32_bf16 v[48:51], v[178:181], v[186:189], v[48:51]
	v_mfma_f32_16x16x32_bf16 v[36:39], v[170:173], v[194:197], v[36:39]
	v_mfma_f32_16x16x32_bf16 v[32:35], v[178:181], v[194:197], v[32:35]
	v_mfma_f32_16x16x32_bf16 v[20:23], v[170:173], v[202:205], v[20:23]
	v_mfma_f32_16x16x32_bf16 v[16:19], v[178:181], v[202:205], v[16:19]
	v_mfma_f32_16x16x32_bf16 v[4:7], v[170:173], v[210:213], v[4:7]
	v_mfma_f32_16x16x32_bf16 v[0:3], v[178:181], v[210:213], v[0:3]
	v_mfma_f32_16x16x32_bf16 v[52:55], v[174:177], v[190:193], v[52:55]
	v_mfma_f32_16x16x32_bf16 v[48:51], v[182:185], v[190:193], v[48:51]
	v_mfma_f32_16x16x32_bf16 v[36:39], v[174:177], v[198:201], v[36:39]
	v_mfma_f32_16x16x32_bf16 v[32:35], v[182:185], v[198:201], v[32:35]
	v_mfma_f32_16x16x32_bf16 v[20:23], v[174:177], v[206:209], v[20:23]
	v_mfma_f32_16x16x32_bf16 v[16:19], v[182:185], v[206:209], v[16:19]
	v_mfma_f32_16x16x32_bf16 v[4:7], v[174:177], v[214:217], v[4:7]
	v_mfma_f32_16x16x32_bf16 v[0:3], v[182:185], v[214:217], v[0:3]
	s_barrier
	s_add_i32 s58, s58, 2
	s_add_u32 s24, s24, 0x100
	s_addc_u32 s25, s25, 0
	s_add_u32 s56, s56, 0x100
	s_addc_u32 s57, s57, 0
	s_cmp_gt_u32 s58, 13
	s_cbranch_scc0 .LBB0_1238
	s_setprio 0
	s_cmp_eq_u32 s50, 1
	s_cbranch_scc0 .Lww_done_p9
	v_readlane_b32 s98, v248, 0
	s_nop 3
	s_cmp_eq_u32 s98, 0
	s_cbranch_scc0 .Lww_bar_p9
	v_readlane_b32 s98, v248, 32
	s_nop 3
	s_cmp_eq_u32 s98, 1
	s_cbranch_scc0 .Lww_bar_p9
	v_mov_b32_e32 v246, 0x3500
	s_mov_b32 s98, 0

; #define PG8_STAGE(bufoff, gbase, voff) do { _Pragma("unroll") for (int _i = 0; _i < 2; ++_i) \
;         __builtin_amdgcn_global_load_lds((const unsigned*)((const char*)(gbase) + (voff)[_i]), (PG8_LAS unsigned*)(lds + (bufoff) + ldsw + _i * 8192), 16, 0, 0); } while (0)
; #define PG8_LDA(dst, b, h) do { _Pragma("unroll") for (int m = 0; m < 4; ++m) _Pragma("unroll") for (int k = 0; k < 2; ++k) dst[m][k] = *(const PG8_LAS bf16x8*)(lds + PG8_SA(b, h) + aoff + m * 2048 + k * 1024); } while (0)
; #define PG8_LDB(dst, b, h) do { _Pragma("unroll") for (int n = 0; n < 2; ++n) _Pragma("unroll") for (int k = 0; k < 2; ++k) dst[n][k] = *(const PG8_LAS bf16x8*)(lds + PG8_SB(b, h) + boff + n * 2048 + k * 1024); } while (0)
; #define PG8_WAIT_V(n) asm volatile("s_waitcnt vmcnt(" #n ")" ::: "memory")
; #define PG8_BAR __builtin_amdgcn_s_barrier()
; template <class Epi, class Sched, bool ALIGN_EPI = false, bool SP2 = false>
; __device__ __forceinline__ void gemm_phase(PG8_LAS unsigned char* lds, const Gemm g, const Sched& S, const Epi& E, int tid_in) {
;     ...
;         const bool has_next = S.next(ui + 1, nxt);
;         const char* nA = has_next ? (const char*)g.A + (size_t)nxt.pm * tstep : cA; const char* nB = has_next ? (const char*)g.Bt + (size_t)nxt.pn * tstep : cB;
;         for (int t = 0; t < nt; t += 2) {
;             if constexpr (Epi::MIDK) { if (t == Epi::MIDK_T) { if (wr == 0) PG8_BAR; E.mid(acc, cur, wr, wc, fr, fq); if (wr == 1) PG8_BAR; } }
;             const bool last = (t == nt - 2);
;             const char* a1 = cA + (size_t)(t + 1) * kstep;
;             const char* a2 = last ? nA : cA + (size_t)(t + 2) * kstep; const char* b2 = last ? nB : cB + (size_t)(t + 2) * kstep;
;             const char* a3 = a2 + kstep; const char* b3 = b2 + kstep;
;             if (last && has_next) S.a_ready(nxt);
;             if constexpr (SP2) {
;             PG8_LDB(B0, 0, 0); PG8_LDB(B1, 0, 1); PG8_SCHED; PG8_LDA(At, 0, 0); PG8_STAGE(PG8_SA(1, 1), a1 + hstep, voffA);
;             PG8_WAIT_V(8); PG8_WAIT_L(0); PG8_BAR; PG8_MMA(0, 0, At, B0); PG8_MMA(0, 1, At, B1); PG8_BAR; PG8_SCHED;
;             PG8_LDA(At, 0, 1); PG8_STAGE(PG8_SB(0, 0), b2, voffB); PG8_STAGE(PG8_SB(0, 1), b2 + hstep, voffB); PG8_STAGE(PG8_SA(0, 0), a2, voffA);
;             PG8_WAIT_V(8); PG8_WAIT_L(0); PG8_BAR; PG8_MMA(1, 0, At, B0); PG8_MMA(1, 1, At, B1); PG8_BAR; PG8_SCHED;
.LBB0_1320:
	s_add_u32 s48, s22, 0x100
	s_addc_u32 s49, s23, 0
	s_mov_b32 s50, -2
	s_waitcnt vmcnt(0)
	s_add_u32 s2, s20, 0x100
	s_addc_u32 s3, s21, 0
	s_cmp_eq_u32 s50, 40
	s_cselect_b32 s25, s17, s3
	s_cselect_b32 s24, s16, s2
	s_cselect_b32 s23, s19, s49
	s_cselect_b32 s22, s18, s48
	s_add_i32 m0, s34, 0xc000
	ds_read_b128 v[128:131], v195
	global_load_lds_dwordx4 v168, s[20:21]
	s_add_i32 m0, s34, 0xe000
	ds_read_b128 v[132:135], v195 offset:1024
	global_load_lds_dwordx4 v170, s[20:21]
	ds_read_b128 v[136:139], v195 offset:2048
	ds_read_b128 v[140:143], v195 offset:3072
	ds_read_b128 v[144:147], v196
	ds_read_b128 v[148:151], v196 offset:1024
	ds_read_b128 v[152:155], v196 offset:2048
	ds_read_b128 v[156:159], v196 offset:3072
	ds_read_b128 v[176:179], v197
	ds_read_b128 v[180:183], v197 offset:1024
	ds_read_b128 v[184:187], v197 offset:2048
	ds_read_b128 v[188:191], v197 offset:3072
	ds_read_b128 v[198:201], v197 offset:4096
	ds_read_b128 v[202:205], v197 offset:5120
	ds_read_b128 v[206:209], v197 offset:6144
	ds_read_b128 v[210:213], v197 offset:7168
	s_waitcnt vmcnt(8)
	s_waitcnt lgkmcnt(0)
	s_barrier
	v_mfma_f32_16x16x32_bf16 v[120:123], v[128:131], v[176:179], 0
	v_mfma_f32_16x16x32_bf16 v[124:127], v[136:139], v[176:179], 0
	v_mfma_f32_16x16x32_bf16 v[104:107], v[128:131], v[184:187], 0
	v_mfma_f32_16x16x32_bf16 v[108:111], v[136:139], v[184:187], 0
	v_mfma_f32_16x16x32_bf16 v[88:91], v[128:131], v[198:201], 0
	v_mfma_f32_16x16x32_bf16 v[92:95], v[136:139], v[198:201], 0
	v_mfma_f32_16x16x32_bf16 v[72:75], v[128:131], v[206:209], 0
	v_mfma_f32_16x16x32_bf16 v[76:79], v[136:139], v[206:209], 0
	v_mfma_f32_16x16x32_bf16 v[120:123], v[132:135], v[180:183], v[120:123]
	v_mfma_f32_16x16x32_bf16 v[124:127], v[140:143], v[180:183], v[124:127]
	v_mfma_f32_16x16x32_bf16 v[104:107], v[132:135], v[188:191], v[104:107]
	v_mfma_f32_16x16x32_bf16 v[108:111], v[140:143], v[188:191], v[108:111]
	v_mfma_f32_16x16x32_bf16 v[88:91], v[132:135], v[202:205], v[88:91]
	v_mfma_f32_16x16x32_bf16 v[92:95], v[140:143], v[202:205], v[92:95]
	v_mfma_f32_16x16x32_bf16 v[72:75], v[132:135], v[210:213], v[72:75]
	v_mfma_f32_16x16x32_bf16 v[76:79], v[140:143], v[210:213], v[76:79]
	v_mfma_f32_16x16x32_bf16 v[112:115], v[144:147], v[176:179], 0
	v_mfma_f32_16x16x32_bf16 v[116:119], v[152:155], v[176:179], 0
	v_mfma_f32_16x16x32_bf16 v[96:99], v[144:147], v[184:187], 0
	v_mfma_f32_16x16x32_bf16 v[100:103], v[152:155], v[184:187], 0
	v_mfma_f32_16x16x32_bf16 v[80:83], v[144:147], v[198:201], 0
	v_mfma_f32_16x16x32_bf16 v[84:87], v[152:155], v[198:201], 0
	v_mfma_f32_16x16x32_bf16 v[64:67], v[144:147], v[206:209], 0
	v_mfma_f32_16x16x32_bf16 v[68:71], v[152:155], v[206:209], 0
	v_mfma_f32_16x16x32_bf16 v[112:115], v[148:151], v[180:183], v[112:115]
	v_mfma_f32_16x16x32_bf16 v[116:119], v[156:159], v[180:183], v[116:119]
	v_mfma_f32_16x16x32_bf16 v[96:99], v[148:151], v[188:191], v[96:99]
	v_mfma_f32_16x16x32_bf16 v[100:103], v[156:159], v[188:191], v[100:103]
	v_mfma_f32_16x16x32_bf16 v[80:83], v[148:151], v[202:205], v[80:83]
	v_mfma_f32_16x16x32_bf16 v[84:87], v[156:159], v[202:205], v[84:87]
	v_mfma_f32_16x16x32_bf16 v[64:67], v[148:151], v[210:213], v[64:67]
	v_mfma_f32_16x16x32_bf16 v[68:71], v[156:159], v[210:213], v[68:71]
	s_barrier
	s_add_u32 s98, s22, s10
	s_addc_u32 s99, s23, s11
	s_add_u32 s100, s24, s10
	s_addc_u32 s101, s25, s11
	s_add_i32 s20, s42, s31
	s_mov_b32 m0, s20
	ds_read_b128 v[176:179], v197 offset:16384
	global_load_lds_dwordx4 v162, s[22:23]
	s_add_i32 m0, s20, 0x2000
	s_add_u32 s20, s22, 0xb0000
	s_addc_u32 s21, s23, 0
	s_add_i32 s51, s43, s31
	global_load_lds_dwordx4 v166, s[22:23]
	s_mov_b32 m0, s51
	ds_read_b128 v[180:183], v197 offset:17408
	global_load_lds_dwordx4 v162, s[20:21]
	s_add_i32 m0, s51, 0x2000
	ds_read_b128 v[184:187], v197 offset:18432
	global_load_lds_dwordx4 v166, s[20:21]
	s_mov_b32 m0, s34
	ds_read_b128 v[188:191], v197 offset:19456
	global_load_lds_dwordx4 v160, s[24:25]
	s_mov_b32 m0, s35
	ds_read_b128 v[198:201], v197 offset:20480
	global_load_lds_dwordx4 v164, s[24:25]
	ds_read_b128 v[202:205], v197 offset:21504
	ds_read_b128 v[206:209], v197 offset:22528
	ds_read_b128 v[210:213], v197 offset:23552
	s_waitcnt vmcnt(8)
	s_waitcnt lgkmcnt(0)
	s_barrier
	v_mfma_f32_16x16x32_bf16 v[56:59], v[128:131], v[176:179], 0
	v_mfma_f32_16x16x32_bf16 v[60:63], v[136:139], v[176:179], 0
	v_mfma_f32_16x16x32_bf16 v[40:43], v[128:131], v[184:187], 0
	v_mfma_f32_16x16x32_bf16 v[44:47], v[136:139], v[184:187], 0
	v_mfma_f32_16x16x32_bf16 v[24:27], v[128:131], v[198:201], 0
	v_mfma_f32_16x16x32_bf16 v[28:31], v[136:139], v[198:201], 0
	v_mfma_f32_16x16x32_bf16 v[8:11], v[128:131], v[206:209], 0
	v_mfma_f32_16x16x32_bf16 v[12:15], v[136:139], v[206:209], 0
	v_mfma_f32_16x16x32_bf16 v[56:59], v[132:135], v[180:183], v[56:59]
	v_mfma_f32_16x16x32_bf16 v[60:63], v[140:143], v[180:183], v[60:63]
	v_mfma_f32_16x16x32_bf16 v[40:43], v[132:135], v[188:191], v[40:43]
	v_mfma_f32_16x16x32_bf16 v[44:47], v[140:143], v[188:191], v[44:47]
	v_mfma_f32_16x16x32_bf16 v[24:27], v[132:135], v[202:205], v[24:27]
	v_mfma_f32_16x16x32_bf16 v[28:31], v[140:143], v[202:205], v[28:31]
	v_mfma_f32_16x16x32_bf16 v[8:11], v[132:135], v[210:213], v[8:11]
	v_mfma_f32_16x16x32_bf16 v[12:15], v[140:143], v[210:213], v[12:15]
	v_mfma_f32_16x16x32_bf16 v[48:51], v[144:147], v[176:179], 0
	v_mfma_f32_16x16x32_bf16 v[52:55], v[152:155], v[176:179], 0
	v_mfma_f32_16x16x32_bf16 v[32:35], v[144:147], v[184:187], 0
	v_mfma_f32_16x16x32_bf16 v[36:39], v[152:155], v[184:187], 0
	v_mfma_f32_16x16x32_bf16 v[16:19], v[144:147], v[198:201], 0
	v_mfma_f32_16x16x32_bf16 v[20:23], v[152:155], v[198:201], 0
	v_mfma_f32_16x16x32_bf16 v[4:7], v[144:147], v[206:209], 0
	v_mfma_f32_16x16x32_bf16 v[0:3], v[152:155], v[206:209], 0
	v_mfma_f32_16x16x32_bf16 v[48:51], v[148:151], v[180:183], v[48:51]
	v_mfma_f32_16x16x32_bf16 v[52:55], v[156:159], v[180:183], v[52:55]
	v_mfma_f32_16x16x32_bf16 v[32:35], v[148:151], v[188:191], v[32:35]
	v_mfma_f32_16x16x32_bf16 v[36:39], v[156:159], v[188:191], v[36:39]
	v_mfma_f32_16x16x32_bf16 v[16:19], v[148:151], v[202:205], v[16:19]
	v_mfma_f32_16x16x32_bf16 v[20:23], v[156:159], v[202:205], v[20:23]
	v_mfma_f32_16x16x32_bf16 v[4:7], v[148:151], v[210:213], v[4:7]
	v_mfma_f32_16x16x32_bf16 v[0:3], v[156:159], v[210:213], v[0:3]
	s_barrier
; #define PG8_STAGE(bufoff, gbase, voff) do { _Pragma("unroll") for (int _i = 0; _i < 2; ++_i) \
;         __builtin_amdgcn_global_load_lds((const unsigned*)((const char*)(gbase) + (voff)[_i]), (PG8_LAS unsigned*)(lds + (bufoff) + ldsw + _i * 8192), 16, 0, 0); } while (0)
; #define PG8_LDA(dst, b, h) do { _Pragma("unroll") for (int m = 0; m < 4; ++m) _Pragma("unroll") for (int k = 0; k < 2; ++k) dst[m][k] = *(const PG8_LAS bf16x8*)(lds + PG8_SA(b, h) + aoff + m * 2048 + k * 1024); } while (0)
; #define PG8_LDB(dst, b, h) do { _Pragma("unroll") for (int n = 0; n < 2; ++n) _Pragma("unroll") for (int k = 0; k < 2; ++k) dst[n][k] = *(const PG8_LAS bf16x8*)(lds + PG8_SB(b, h) + boff + n * 2048 + k * 1024); } while (0)
; #define PG8_MMA(ai, bj, At, Bt) do { __builtin_amdgcn_s_setprio(1); _Pragma("unroll") for (int m = 0; m < 4; ++m) _Pragma("unroll") for (int n = 0; n < 2; ++n) _Pragma("unroll") for (int k = 0; k < 2; ++k) \
;         acc[ai][bj][m][n] = __builtin_amdgcn_mfma_f32_16x16x32_bf16(Bt[n][k], At[m][k], acc[ai][bj][m][n], 0, 0, 0); __builtin_amdgcn_s_setprio(0); } while (0)
; #define PG8_WAIT_V(n) asm volatile("s_waitcnt vmcnt(" #n ")" ::: "memory")
; #define PG8_WAIT_L(n) asm volatile("s_waitcnt lgkmcnt(" #n ")" ::: "memory")
; #define PG8_BAR __builtin_amdgcn_s_barrier()
; #define PG8_SCHED __builtin_amdgcn_sched_barrier(0)
; template <class Epi, class Sched, bool ALIGN_EPI = false, bool SP2 = false>
; __device__ __forceinline__ void gemm_phase(PG8_LAS unsigned char* lds, const Gemm g, const Sched& S, const Epi& E, int tid_in) {
;     ...
;             PG8_LDB(B0, 1, 0); PG8_LDB(B1, 1, 1); PG8_SCHED; PG8_LDA(At, 1, 0); PG8_STAGE(PG8_SA(0, 1), a2 + hstep, voffA);
;             PG8_WAIT_V(8); PG8_WAIT_L(0); PG8_BAR; PG8_MMA(0, 0, At, B0); PG8_MMA(0, 1, At, B1); PG8_BAR; PG8_SCHED;
;             PG8_LDA(At, 1, 1); PG8_STAGE(PG8_SB(1, 0), b3, voffB); PG8_STAGE(PG8_SB(1, 1), b3 + hstep, voffB); PG8_STAGE(PG8_SA(1, 0), a3, voffA);
;             PG8_WAIT_V(8); PG8_WAIT_L(0); PG8_BAR; PG8_MMA(1, 0, At, B0); PG8_MMA(1, 1, At, B1); PG8_BAR; PG8_SCHED;
	s_add_i32 s51, 0, 0x18000
	s_add_i32 s52, 0, 0x1c000
	s_add_u32 s20, s24, 0xb0000
	s_addc_u32 s21, s25, 0
	s_mov_b32 m0, s36
	s_nop 0
	global_load_lds_dwordx4 v160, s[20:21]
	s_mov_b32 m0, s37
	s_nop 0
	global_load_lds_dwordx4 v164, s[20:21]
	v_add_u32_e32 v140, s51, v193
	v_add_u32_e32 v156, s52, v193
	ds_read_b128 v[128:131], v140
	ds_read_b128 v[132:135], v140 offset:1024
	ds_read_b128 v[136:139], v140 offset:2048
	ds_read_b128 v[140:143], v140 offset:3072
	ds_read_b128 v[144:147], v156
	ds_read_b128 v[148:151], v156 offset:1024
	ds_read_b128 v[152:155], v156 offset:2048
	ds_read_b128 v[156:159], v156 offset:3072
	ds_read_b128 v[176:179], v197 offset:32768
	ds_read_b128 v[180:183], v197 offset:33792
	ds_read_b128 v[184:187], v197 offset:34816
	ds_read_b128 v[188:191], v197 offset:35840
	ds_read_b128 v[198:201], v197 offset:36864
	ds_read_b128 v[202:205], v197 offset:37888
	ds_read_b128 v[206:209], v197 offset:38912
	ds_read_b128 v[210:213], v197 offset:39936
	s_waitcnt vmcnt(8)
	s_waitcnt lgkmcnt(0)
	s_barrier
	v_mfma_f32_16x16x32_bf16 v[120:123], v[128:131], v[176:179], v[120:123]
	v_mfma_f32_16x16x32_bf16 v[124:127], v[136:139], v[176:179], v[124:127]
	v_mfma_f32_16x16x32_bf16 v[104:107], v[128:131], v[184:187], v[104:107]
	v_mfma_f32_16x16x32_bf16 v[108:111], v[136:139], v[184:187], v[108:111]
	v_mfma_f32_16x16x32_bf16 v[88:91], v[128:131], v[198:201], v[88:91]
	v_mfma_f32_16x16x32_bf16 v[92:95], v[136:139], v[198:201], v[92:95]
	v_mfma_f32_16x16x32_bf16 v[72:75], v[128:131], v[206:209], v[72:75]
	v_mfma_f32_16x16x32_bf16 v[76:79], v[136:139], v[206:209], v[76:79]
	v_mfma_f32_16x16x32_bf16 v[120:123], v[132:135], v[180:183], v[120:123]
	v_mfma_f32_16x16x32_bf16 v[124:127], v[140:143], v[180:183], v[124:127]
	v_mfma_f32_16x16x32_bf16 v[104:107], v[132:135], v[188:191], v[104:107]
	v_mfma_f32_16x16x32_bf16 v[108:111], v[140:143], v[188:191], v[108:111]
	v_mfma_f32_16x16x32_bf16 v[88:91], v[132:135], v[202:205], v[88:91]
	v_mfma_f32_16x16x32_bf16 v[92:95], v[140:143], v[202:205], v[92:95]
	v_mfma_f32_16x16x32_bf16 v[72:75], v[132:135], v[210:213], v[72:75]
	v_mfma_f32_16x16x32_bf16 v[76:79], v[140:143], v[210:213], v[76:79]
	v_mfma_f32_16x16x32_bf16 v[112:115], v[144:147], v[176:179], v[112:115]
	v_mfma_f32_16x16x32_bf16 v[116:119], v[152:155], v[176:179], v[116:119]
	v_mfma_f32_16x16x32_bf16 v[96:99], v[144:147], v[184:187], v[96:99]
	v_mfma_f32_16x16x32_bf16 v[100:103], v[152:155], v[184:187], v[100:103]
	v_mfma_f32_16x16x32_bf16 v[80:83], v[144:147], v[198:201], v[80:83]
	v_mfma_f32_16x16x32_bf16 v[84:87], v[152:155], v[198:201], v[84:87]
	v_mfma_f32_16x16x32_bf16 v[64:67], v[144:147], v[206:209], v[64:67]
	v_mfma_f32_16x16x32_bf16 v[68:71], v[152:155], v[206:209], v[68:71]
	v_mfma_f32_16x16x32_bf16 v[112:115], v[148:151], v[180:183], v[112:115]
	v_mfma_f32_16x16x32_bf16 v[116:119], v[156:159], v[180:183], v[116:119]
	v_mfma_f32_16x16x32_bf16 v[96:99], v[148:151], v[188:191], v[96:99]
	v_mfma_f32_16x16x32_bf16 v[100:103], v[156:159], v[188:191], v[100:103]
	v_mfma_f32_16x16x32_bf16 v[80:83], v[148:151], v[202:205], v[80:83]
	v_mfma_f32_16x16x32_bf16 v[84:87], v[156:159], v[202:205], v[84:87]
	v_mfma_f32_16x16x32_bf16 v[64:67], v[148:151], v[210:213], v[64:67]
	v_mfma_f32_16x16x32_bf16 v[68:71], v[156:159], v[210:213], v[68:71]
	s_barrier
	s_add_i32 s20, s51, s31
	s_mov_b32 m0, s20
	ds_read_b128 v[176:179], v197 offset:49152
	global_load_lds_dwordx4 v162, s[98:99]
	s_add_i32 m0, s20, 0x2000
	s_add_u32 s20, s22, 0xb0080
	s_addc_u32 s21, s23, 0
	s_add_i32 s22, s52, s31
	global_load_lds_dwordx4 v166, s[98:99]
	s_mov_b32 m0, s22
	ds_read_b128 v[180:183], v197 offset:50176
	global_load_lds_dwordx4 v162, s[20:21]
	s_add_i32 m0, s22, 0x2000
	ds_read_b128 v[184:187], v197 offset:51200
	global_load_lds_dwordx4 v166, s[20:21]
	s_mov_b32 m0, s39
	ds_read_b128 v[188:191], v197 offset:52224
	global_load_lds_dwordx4 v160, s[100:101]
	s_mov_b32 m0, s40
	ds_read_b128 v[198:201], v197 offset:53248
	global_load_lds_dwordx4 v164, s[100:101]
	ds_read_b128 v[202:205], v197 offset:54272
	ds_read_b128 v[206:209], v197 offset:55296
	ds_read_b128 v[210:213], v197 offset:56320
	s_waitcnt vmcnt(8)
	s_waitcnt lgkmcnt(0)
	s_barrier
	v_mfma_f32_16x16x32_bf16 v[56:59], v[128:131], v[176:179], v[56:59]
	v_mfma_f32_16x16x32_bf16 v[60:63], v[136:139], v[176:179], v[60:63]
	v_mfma_f32_16x16x32_bf16 v[40:43], v[128:131], v[184:187], v[40:43]
	v_mfma_f32_16x16x32_bf16 v[44:47], v[136:139], v[184:187], v[44:47]
	v_mfma_f32_16x16x32_bf16 v[24:27], v[128:131], v[198:201], v[24:27]
	v_mfma_f32_16x16x32_bf16 v[28:31], v[136:139], v[198:201], v[28:31]
	v_mfma_f32_16x16x32_bf16 v[8:11], v[128:131], v[206:209], v[8:11]
	v_mfma_f32_16x16x32_bf16 v[12:15], v[136:139], v[206:209], v[12:15]
	v_mfma_f32_16x16x32_bf16 v[56:59], v[132:135], v[180:183], v[56:59]
	v_mfma_f32_16x16x32_bf16 v[60:63], v[140:143], v[180:183], v[60:63]
	v_mfma_f32_16x16x32_bf16 v[40:43], v[132:135], v[188:191], v[40:43]
	v_mfma_f32_16x16x32_bf16 v[44:47], v[140:143], v[188:191], v[44:47]
	v_mfma_f32_16x16x32_bf16 v[24:27], v[132:135], v[202:205], v[24:27]
	v_mfma_f32_16x16x32_bf16 v[28:31], v[140:143], v[202:205], v[28:31]
	v_mfma_f32_16x16x32_bf16 v[8:11], v[132:135], v[210:213], v[8:11]
	v_mfma_f32_16x16x32_bf16 v[12:15], v[140:143], v[210:213], v[12:15]
	v_mfma_f32_16x16x32_bf16 v[48:51], v[144:147], v[176:179], v[48:51]
	v_mfma_f32_16x16x32_bf16 v[52:55], v[152:155], v[176:179], v[52:55]
	v_mfma_f32_16x16x32_bf16 v[32:35], v[144:147], v[184:187], v[32:35]
	v_mfma_f32_16x16x32_bf16 v[36:39], v[152:155], v[184:187], v[36:39]
	v_mfma_f32_16x16x32_bf16 v[16:19], v[144:147], v[198:201], v[16:19]
	v_mfma_f32_16x16x32_bf16 v[20:23], v[152:155], v[198:201], v[20:23]
	v_mfma_f32_16x16x32_bf16 v[4:7], v[144:147], v[206:209], v[4:7]
	v_mfma_f32_16x16x32_bf16 v[0:3], v[152:155], v[206:209], v[0:3]
	v_mfma_f32_16x16x32_bf16 v[48:51], v[148:151], v[180:183], v[48:51]
	v_mfma_f32_16x16x32_bf16 v[52:55], v[156:159], v[180:183], v[52:55]
	v_mfma_f32_16x16x32_bf16 v[32:35], v[148:151], v[188:191], v[32:35]
	v_mfma_f32_16x16x32_bf16 v[36:39], v[156:159], v[188:191], v[36:39]
	v_mfma_f32_16x16x32_bf16 v[16:19], v[148:151], v[202:205], v[16:19]
	v_mfma_f32_16x16x32_bf16 v[20:23], v[156:159], v[202:205], v[20:23]
	v_mfma_f32_16x16x32_bf16 v[4:7], v[148:151], v[210:213], v[4:7]
	v_mfma_f32_16x16x32_bf16 v[0:3], v[156:159], v[210:213], v[0:3]
	s_barrier
	s_add_i32 s50, s50, 2
	s_add_u32 s48, s48, 0x100
	s_addc_u32 s49, s49, 0
	s_mov_b64 s[20:21], s[2:3]
	v_readlane_b32 s98, v248, 0
	s_nop 3
	s_cmp_ge_u32 s98, 0x100
	s_cbranch_scc0 .Lgprio_skip_5
	s_setprio 1
; #define PG8_STAGE(bufoff, gbase, voff) do { _Pragma("unroll") for (int _i = 0; _i < 2; ++_i) \
;         __builtin_amdgcn_global_load_lds((const unsigned*)((const char*)(gbase) + (voff)[_i]), (PG8_LAS unsigned*)(lds + (bufoff) + ldsw + _i * 8192), 16, 0, 0); } while (0)
; #define PG8_LDA(dst, b, h) do { _Pragma("unroll") for (int m = 0; m < 4; ++m) _Pragma("unroll") for (int k = 0; k < 2; ++k) dst[m][k] = *(const PG8_LAS bf16x8*)(lds + PG8_SA(b, h) + aoff + m * 2048 + k * 1024); } while (0)
; #define PG8_LDB(dst, b, h) do { _Pragma("unroll") for (int n = 0; n < 2; ++n) _Pragma("unroll") for (int k = 0; k < 2; ++k) dst[n][k] = *(const PG8_LAS bf16x8*)(lds + PG8_SB(b, h) + boff + n * 2048 + k * 1024); } while (0)
; #define PG8_MMA(ai, bj, At, Bt) do { __builtin_amdgcn_s_setprio(1); _Pragma("unroll") for (int m = 0; m < 4; ++m) _Pragma("unroll") for (int n = 0; n < 2; ++n) _Pragma("unroll") for (int k = 0; k < 2; ++k) \
;         acc[ai][bj][m][n] = __builtin_amdgcn_mfma_f32_16x16x32_bf16(Bt[n][k], At[m][k], acc[ai][bj][m][n], 0, 0, 0); __builtin_amdgcn_s_setprio(0); } while (0)
; #define PG8_WAIT_V(n) asm volatile("s_waitcnt vmcnt(" #n ")" ::: "memory")
; #define PG8_WAIT_L(n) asm volatile("s_waitcnt lgkmcnt(" #n ")" ::: "memory")
; #define PG8_BAR __builtin_amdgcn_s_barrier()
; template <class Epi, class Sched, bool ALIGN_EPI = false, bool SP2 = false>
; __device__ __forceinline__ void gemm_phase(PG8_LAS unsigned char* lds, const Gemm g, const Sched& S, const Epi& E, int tid_in) {
;     ...
;             const char* a1 = cA + (size_t)(t + 1) * kstep;
;             const char* a2 = last ? nA : cA + (size_t)(t + 2) * kstep; const char* b2 = last ? nB : cB + (size_t)(t + 2) * kstep;
;             const char* a3 = a2 + kstep; const char* b3 = b2 + kstep;
;             if (last && has_next) S.a_ready(nxt);
;             if constexpr (SP2) {
;             PG8_LDB(B0, 0, 0); PG8_LDB(B1, 0, 1); PG8_SCHED; PG8_LDA(At, 0, 0); PG8_STAGE(PG8_SA(1, 1), a1 + hstep, voffA);
;             PG8_WAIT_V(8); PG8_WAIT_L(0); PG8_BAR; PG8_MMA(0, 0, At, B0); PG8_MMA(0, 1, At, B1); PG8_BAR; PG8_SCHED;
;             PG8_LDA(At, 0, 1); PG8_STAGE(PG8_SB(0, 0), b2, voffB); PG8_STAGE(PG8_SB(0, 1), b2 + hstep, voffB); PG8_STAGE(PG8_SA(0, 0), a2, voffA);
;             PG8_WAIT_V(8); PG8_WAIT_L(0); PG8_BAR; PG8_MMA(1, 0, At, B0); PG8_MMA(1, 1, At, B1); PG8_BAR; PG8_SCHED;
.Lgprio_skip_5:
.LBB0_1321:
	s_add_u32 s2, s20, 0x100
	s_addc_u32 s3, s21, 0
	s_cmp_eq_u32 s50, 40
	s_cselect_b32 s25, s17, s3
	s_cselect_b32 s24, s16, s2
	s_cselect_b32 s23, s19, s49
	s_cselect_b32 s22, s18, s48
	s_add_i32 m0, s34, 0xc000
	ds_read_b128 v[128:131], v195
	global_load_lds_dwordx4 v168, s[20:21]
	s_add_i32 m0, s34, 0xe000
	ds_read_b128 v[132:135], v195 offset:1024
	global_load_lds_dwordx4 v170, s[20:21]
	ds_read_b128 v[136:139], v195 offset:2048
	ds_read_b128 v[140:143], v195 offset:3072
	ds_read_b128 v[144:147], v196
	ds_read_b128 v[148:151], v196 offset:1024
	ds_read_b128 v[152:155], v196 offset:2048
	ds_read_b128 v[156:159], v196 offset:3072
	ds_read_b128 v[176:179], v197
	ds_read_b128 v[180:183], v197 offset:1024
	ds_read_b128 v[184:187], v197 offset:2048
	ds_read_b128 v[188:191], v197 offset:3072
	ds_read_b128 v[198:201], v197 offset:4096
	ds_read_b128 v[202:205], v197 offset:5120
	ds_read_b128 v[206:209], v197 offset:6144
	ds_read_b128 v[210:213], v197 offset:7168
	s_waitcnt vmcnt(8)
	s_waitcnt lgkmcnt(0)
	s_barrier
	v_mfma_f32_16x16x32_bf16 v[120:123], v[128:131], v[176:179], v[120:123]
	v_mfma_f32_16x16x32_bf16 v[124:127], v[136:139], v[176:179], v[124:127]
	v_mfma_f32_16x16x32_bf16 v[104:107], v[128:131], v[184:187], v[104:107]
	v_mfma_f32_16x16x32_bf16 v[108:111], v[136:139], v[184:187], v[108:111]
	v_mfma_f32_16x16x32_bf16 v[88:91], v[128:131], v[198:201], v[88:91]
	v_mfma_f32_16x16x32_bf16 v[92:95], v[136:139], v[198:201], v[92:95]
	v_mfma_f32_16x16x32_bf16 v[72:75], v[128:131], v[206:209], v[72:75]
	v_mfma_f32_16x16x32_bf16 v[76:79], v[136:139], v[206:209], v[76:79]
	v_mfma_f32_16x16x32_bf16 v[120:123], v[132:135], v[180:183], v[120:123]
	v_mfma_f32_16x16x32_bf16 v[124:127], v[140:143], v[180:183], v[124:127]
	v_mfma_f32_16x16x32_bf16 v[104:107], v[132:135], v[188:191], v[104:107]
	v_mfma_f32_16x16x32_bf16 v[108:111], v[140:143], v[188:191], v[108:111]
	v_mfma_f32_16x16x32_bf16 v[88:91], v[132:135], v[202:205], v[88:91]
	v_mfma_f32_16x16x32_bf16 v[92:95], v[140:143], v[202:205], v[92:95]
	v_mfma_f32_16x16x32_bf16 v[72:75], v[132:135], v[210:213], v[72:75]
	v_mfma_f32_16x16x32_bf16 v[76:79], v[140:143], v[210:213], v[76:79]
	v_mfma_f32_16x16x32_bf16 v[112:115], v[144:147], v[176:179], v[112:115]
	v_mfma_f32_16x16x32_bf16 v[116:119], v[152:155], v[176:179], v[116:119]
	v_mfma_f32_16x16x32_bf16 v[96:99], v[144:147], v[184:187], v[96:99]
	v_mfma_f32_16x16x32_bf16 v[100:103], v[152:155], v[184:187], v[100:103]
	v_mfma_f32_16x16x32_bf16 v[80:83], v[144:147], v[198:201], v[80:83]
	v_mfma_f32_16x16x32_bf16 v[84:87], v[152:155], v[198:201], v[84:87]
	v_mfma_f32_16x16x32_bf16 v[64:67], v[144:147], v[206:209], v[64:67]
	v_mfma_f32_16x16x32_bf16 v[68:71], v[152:155], v[206:209], v[68:71]
	v_mfma_f32_16x16x32_bf16 v[112:115], v[148:151], v[180:183], v[112:115]
	v_mfma_f32_16x16x32_bf16 v[116:119], v[156:159], v[180:183], v[116:119]
	v_mfma_f32_16x16x32_bf16 v[96:99], v[148:151], v[188:191], v[96:99]
	v_mfma_f32_16x16x32_bf16 v[100:103], v[156:159], v[188:191], v[100:103]
	v_mfma_f32_16x16x32_bf16 v[80:83], v[148:151], v[202:205], v[80:83]
	v_mfma_f32_16x16x32_bf16 v[84:87], v[156:159], v[202:205], v[84:87]
	v_mfma_f32_16x16x32_bf16 v[64:67], v[148:151], v[210:213], v[64:67]
	v_mfma_f32_16x16x32_bf16 v[68:71], v[156:159], v[210:213], v[68:71]
	s_barrier
	s_add_u32 s98, s22, s10
	s_addc_u32 s99, s23, s11
	s_add_u32 s100, s24, s10
	s_addc_u32 s101, s25, s11
	s_add_i32 s20, s42, s31
	s_mov_b32 m0, s20
	ds_read_b128 v[176:179], v197 offset:16384
	global_load_lds_dwordx4 v162, s[22:23]
	s_add_i32 m0, s20, 0x2000
	s_add_u32 s20, s22, 0xb0000
	s_addc_u32 s21, s23, 0
	s_add_i32 s51, s43, s31
	global_load_lds_dwordx4 v166, s[22:23]
	s_mov_b32 m0, s51
	ds_read_b128 v[180:183], v197 offset:17408
	global_load_lds_dwordx4 v162, s[20:21]
	s_add_i32 m0, s51, 0x2000
	ds_read_b128 v[184:187], v197 offset:18432
	global_load_lds_dwordx4 v166, s[20:21]
	s_mov_b32 m0, s34
	ds_read_b128 v[188:191], v197 offset:19456
	global_load_lds_dwordx4 v160, s[24:25]
	s_mov_b32 m0, s35
	ds_read_b128 v[198:201], v197 offset:20480
	global_load_lds_dwordx4 v164, s[24:25]
	ds_read_b128 v[202:205], v197 offset:21504
	ds_read_b128 v[206:209], v197 offset:22528
	ds_read_b128 v[210:213], v197 offset:23552
	s_waitcnt vmcnt(8)
	s_waitcnt lgkmcnt(0)
	s_barrier
	v_mfma_f32_16x16x32_bf16 v[56:59], v[128:131], v[176:179], v[56:59]
	v_mfma_f32_16x16x32_bf16 v[60:63], v[136:139], v[176:179], v[60:63]
	v_mfma_f32_16x16x32_bf16 v[40:43], v[128:131], v[184:187], v[40:43]
	v_mfma_f32_16x16x32_bf16 v[44:47], v[136:139], v[184:187], v[44:47]
	v_mfma_f32_16x16x32_bf16 v[24:27], v[128:131], v[198:201], v[24:27]
	v_mfma_f32_16x16x32_bf16 v[28:31], v[136:139], v[198:201], v[28:31]
	v_mfma_f32_16x16x32_bf16 v[8:11], v[128:131], v[206:209], v[8:11]
	v_mfma_f32_16x16x32_bf16 v[12:15], v[136:139], v[206:209], v[12:15]
	v_mfma_f32_16x16x32_bf16 v[56:59], v[132:135], v[180:183], v[56:59]
	v_mfma_f32_16x16x32_bf16 v[60:63], v[140:143], v[180:183], v[60:63]
	v_mfma_f32_16x16x32_bf16 v[40:43], v[132:135], v[188:191], v[40:43]
	v_mfma_f32_16x16x32_bf16 v[44:47], v[140:143], v[188:191], v[44:47]
	v_mfma_f32_16x16x32_bf16 v[24:27], v[132:135], v[202:205], v[24:27]
	v_mfma_f32_16x16x32_bf16 v[28:31], v[140:143], v[202:205], v[28:31]
	v_mfma_f32_16x16x32_bf16 v[8:11], v[132:135], v[210:213], v[8:11]
	v_mfma_f32_16x16x32_bf16 v[12:15], v[140:143], v[210:213], v[12:15]
	v_mfma_f32_16x16x32_bf16 v[48:51], v[144:147], v[176:179], v[48:51]
	v_mfma_f32_16x16x32_bf16 v[52:55], v[152:155], v[176:179], v[52:55]
	v_mfma_f32_16x16x32_bf16 v[32:35], v[144:147], v[184:187], v[32:35]
	v_mfma_f32_16x16x32_bf16 v[36:39], v[152:155], v[184:187], v[36:39]
	v_mfma_f32_16x16x32_bf16 v[16:19], v[144:147], v[198:201], v[16:19]
	v_mfma_f32_16x16x32_bf16 v[20:23], v[152:155], v[198:201], v[20:23]
	v_mfma_f32_16x16x32_bf16 v[4:7], v[144:147], v[206:209], v[4:7]
	v_mfma_f32_16x16x32_bf16 v[0:3], v[152:155], v[206:209], v[0:3]
	v_mfma_f32_16x16x32_bf16 v[48:51], v[148:151], v[180:183], v[48:51]
	v_mfma_f32_16x16x32_bf16 v[52:55], v[156:159], v[180:183], v[52:55]
	v_mfma_f32_16x16x32_bf16 v[32:35], v[148:151], v[188:191], v[32:35]
	v_mfma_f32_16x16x32_bf16 v[36:39], v[156:159], v[188:191], v[36:39]
	v_mfma_f32_16x16x32_bf16 v[16:19], v[148:151], v[202:205], v[16:19]
	v_mfma_f32_16x16x32_bf16 v[20:23], v[156:159], v[202:205], v[20:23]
	v_mfma_f32_16x16x32_bf16 v[4:7], v[148:151], v[210:213], v[4:7]
	v_mfma_f32_16x16x32_bf16 v[0:3], v[156:159], v[210:213], v[0:3]
	s_barrier
; #define PG8_STAGE(bufoff, gbase, voff) do { _Pragma("unroll") for (int _i = 0; _i < 2; ++_i) \
;         __builtin_amdgcn_global_load_lds((const unsigned*)((const char*)(gbase) + (voff)[_i]), (PG8_LAS unsigned*)(lds + (bufoff) + ldsw + _i * 8192), 16, 0, 0); } while (0)
; #define PG8_LDA(dst, b, h) do { _Pragma("unroll") for (int m = 0; m < 4; ++m) _Pragma("unroll") for (int k = 0; k < 2; ++k) dst[m][k] = *(const PG8_LAS bf16x8*)(lds + PG8_SA(b, h) + aoff + m * 2048 + k * 1024); } while (0)
; #define PG8_LDB(dst, b, h) do { _Pragma("unroll") for (int n = 0; n < 2; ++n) _Pragma("unroll") for (int k = 0; k < 2; ++k) dst[n][k] = *(const PG8_LAS bf16x8*)(lds + PG8_SB(b, h) + boff + n * 2048 + k * 1024); } while (0)
; #define PG8_MMA(ai, bj, At, Bt) do { __builtin_amdgcn_s_setprio(1); _Pragma("unroll") for (int m = 0; m < 4; ++m) _Pragma("unroll") for (int n = 0; n < 2; ++n) _Pragma("unroll") for (int k = 0; k < 2; ++k) \
;         acc[ai][bj][m][n] = __builtin_amdgcn_mfma_f32_16x16x32_bf16(Bt[n][k], At[m][k], acc[ai][bj][m][n], 0, 0, 0); __builtin_amdgcn_s_setprio(0); } while (0)
; #define PG8_WAIT_V(n) asm volatile("s_waitcnt vmcnt(" #n ")" ::: "memory")
; #define PG8_WAIT_L(n) asm volatile("s_waitcnt lgkmcnt(" #n ")" ::: "memory")
; #define PG8_BAR __builtin_amdgcn_s_barrier()
; #define PG8_SCHED __builtin_amdgcn_sched_barrier(0)
; template <class Epi, class Sched, bool ALIGN_EPI = false, bool SP2 = false>
; __device__ __forceinline__ void gemm_phase(PG8_LAS unsigned char* lds, const Gemm g, const Sched& S, const Epi& E, int tid_in) {
;     ...
;             PG8_LDB(B0, 1, 0); PG8_LDB(B1, 1, 1); PG8_SCHED; PG8_LDA(At, 1, 0); PG8_STAGE(PG8_SA(0, 1), a2 + hstep, voffA);
;             PG8_WAIT_V(8); PG8_WAIT_L(0); PG8_BAR; PG8_MMA(0, 0, At, B0); PG8_MMA(0, 1, At, B1); PG8_BAR; PG8_SCHED;
;             PG8_LDA(At, 1, 1); PG8_STAGE(PG8_SB(1, 0), b3, voffB); PG8_STAGE(PG8_SB(1, 1), b3 + hstep, voffB); PG8_STAGE(PG8_SA(1, 0), a3, voffA);
;             PG8_WAIT_V(8); PG8_WAIT_L(0); PG8_BAR; PG8_MMA(1, 0, At, B0); PG8_MMA(1, 1, At, B1); PG8_BAR; PG8_SCHED;
	s_add_i32 s51, 0, 0x18000
	s_add_i32 s52, 0, 0x1c000
	s_add_u32 s20, s24, 0xb0000
	s_addc_u32 s21, s25, 0
	s_mov_b32 m0, s36
	s_nop 0
	global_load_lds_dwordx4 v160, s[20:21]
	s_mov_b32 m0, s37
	s_nop 0
	global_load_lds_dwordx4 v164, s[20:21]
	v_add_u32_e32 v140, s51, v193
	v_add_u32_e32 v156, s52, v193
	ds_read_b128 v[128:131], v140
	ds_read_b128 v[132:135], v140 offset:1024
	ds_read_b128 v[136:139], v140 offset:2048
	ds_read_b128 v[140:143], v140 offset:3072
	ds_read_b128 v[144:147], v156
	ds_read_b128 v[148:151], v156 offset:1024
	ds_read_b128 v[152:155], v156 offset:2048
	ds_read_b128 v[156:159], v156 offset:3072
	ds_read_b128 v[176:179], v197 offset:32768
	ds_read_b128 v[180:183], v197 offset:33792
	ds_read_b128 v[184:187], v197 offset:34816
	ds_read_b128 v[188:191], v197 offset:35840
	ds_read_b128 v[198:201], v197 offset:36864
	ds_read_b128 v[202:205], v197 offset:37888
	ds_read_b128 v[206:209], v197 offset:38912
	ds_read_b128 v[210:213], v197 offset:39936
	s_waitcnt vmcnt(8)
	s_waitcnt lgkmcnt(0)
	s_barrier
	v_mfma_f32_16x16x32_bf16 v[120:123], v[128:131], v[176:179], v[120:123]
	v_mfma_f32_16x16x32_bf16 v[124:127], v[136:139], v[176:179], v[124:127]
	v_mfma_f32_16x16x32_bf16 v[104:107], v[128:131], v[184:187], v[104:107]
	v_mfma_f32_16x16x32_bf16 v[108:111], v[136:139], v[184:187], v[108:111]
	v_mfma_f32_16x16x32_bf16 v[88:91], v[128:131], v[198:201], v[88:91]
	v_mfma_f32_16x16x32_bf16 v[92:95], v[136:139], v[198:201], v[92:95]
	v_mfma_f32_16x16x32_bf16 v[72:75], v[128:131], v[206:209], v[72:75]
	v_mfma_f32_16x16x32_bf16 v[76:79], v[136:139], v[206:209], v[76:79]
	v_mfma_f32_16x16x32_bf16 v[120:123], v[132:135], v[180:183], v[120:123]
	v_mfma_f32_16x16x32_bf16 v[124:127], v[140:143], v[180:183], v[124:127]
	v_mfma_f32_16x16x32_bf16 v[104:107], v[132:135], v[188:191], v[104:107]
	v_mfma_f32_16x16x32_bf16 v[108:111], v[140:143], v[188:191], v[108:111]
	v_mfma_f32_16x16x32_bf16 v[88:91], v[132:135], v[202:205], v[88:91]
	v_mfma_f32_16x16x32_bf16 v[92:95], v[140:143], v[202:205], v[92:95]
	v_mfma_f32_16x16x32_bf16 v[72:75], v[132:135], v[210:213], v[72:75]
	v_mfma_f32_16x16x32_bf16 v[76:79], v[140:143], v[210:213], v[76:79]
	v_mfma_f32_16x16x32_bf16 v[112:115], v[144:147], v[176:179], v[112:115]
	v_mfma_f32_16x16x32_bf16 v[116:119], v[152:155], v[176:179], v[116:119]
	v_mfma_f32_16x16x32_bf16 v[96:99], v[144:147], v[184:187], v[96:99]
	v_mfma_f32_16x16x32_bf16 v[100:103], v[152:155], v[184:187], v[100:103]
	v_mfma_f32_16x16x32_bf16 v[80:83], v[144:147], v[198:201], v[80:83]
	v_mfma_f32_16x16x32_bf16 v[84:87], v[152:155], v[198:201], v[84:87]
	v_mfma_f32_16x16x32_bf16 v[64:67], v[144:147], v[206:209], v[64:67]
	v_mfma_f32_16x16x32_bf16 v[68:71], v[152:155], v[206:209], v[68:71]
	v_mfma_f32_16x16x32_bf16 v[112:115], v[148:151], v[180:183], v[112:115]
	v_mfma_f32_16x16x32_bf16 v[116:119], v[156:159], v[180:183], v[116:119]
	v_mfma_f32_16x16x32_bf16 v[96:99], v[148:151], v[188:191], v[96:99]
	v_mfma_f32_16x16x32_bf16 v[100:103], v[156:159], v[188:191], v[100:103]
	v_mfma_f32_16x16x32_bf16 v[80:83], v[148:151], v[202:205], v[80:83]
	v_mfma_f32_16x16x32_bf16 v[84:87], v[156:159], v[202:205], v[84:87]
	v_mfma_f32_16x16x32_bf16 v[64:67], v[148:151], v[210:213], v[64:67]
	v_mfma_f32_16x16x32_bf16 v[68:71], v[156:159], v[210:213], v[68:71]
	s_barrier
	s_add_i32 s20, s51, s31
	s_mov_b32 m0, s20
	ds_read_b128 v[176:179], v197 offset:49152
	global_load_lds_dwordx4 v162, s[98:99]
	s_add_i32 m0, s20, 0x2000
	s_add_u32 s20, s22, 0xb0080
	s_addc_u32 s21, s23, 0
	s_add_i32 s22, s52, s31
	global_load_lds_dwordx4 v166, s[98:99]
	s_mov_b32 m0, s22
	ds_read_b128 v[180:183], v197 offset:50176
	global_load_lds_dwordx4 v162, s[20:21]
	s_add_i32 m0, s22, 0x2000
	ds_read_b128 v[184:187], v197 offset:51200
	global_load_lds_dwordx4 v166, s[20:21]
	s_mov_b32 m0, s39
	ds_read_b128 v[188:191], v197 offset:52224
	global_load_lds_dwordx4 v160, s[100:101]
	s_mov_b32 m0, s40
	ds_read_b128 v[198:201], v197 offset:53248
	global_load_lds_dwordx4 v164, s[100:101]
	ds_read_b128 v[202:205], v197 offset:54272
	ds_read_b128 v[206:209], v197 offset:55296
	ds_read_b128 v[210:213], v197 offset:56320
	s_waitcnt vmcnt(8)
	s_waitcnt lgkmcnt(0)
	s_barrier
	v_mfma_f32_16x16x32_bf16 v[56:59], v[128:131], v[176:179], v[56:59]
	v_mfma_f32_16x16x32_bf16 v[60:63], v[136:139], v[176:179], v[60:63]
	v_mfma_f32_16x16x32_bf16 v[40:43], v[128:131], v[184:187], v[40:43]
	v_mfma_f32_16x16x32_bf16 v[44:47], v[136:139], v[184:187], v[44:47]
	v_mfma_f32_16x16x32_bf16 v[24:27], v[128:131], v[198:201], v[24:27]
	v_mfma_f32_16x16x32_bf16 v[28:31], v[136:139], v[198:201], v[28:31]
	v_mfma_f32_16x16x32_bf16 v[8:11], v[128:131], v[206:209], v[8:11]
	v_mfma_f32_16x16x32_bf16 v[12:15], v[136:139], v[206:209], v[12:15]
	v_mfma_f32_16x16x32_bf16 v[56:59], v[132:135], v[180:183], v[56:59]
	v_mfma_f32_16x16x32_bf16 v[60:63], v[140:143], v[180:183], v[60:63]
	v_mfma_f32_16x16x32_bf16 v[40:43], v[132:135], v[188:191], v[40:43]
	v_mfma_f32_16x16x32_bf16 v[44:47], v[140:143], v[188:191], v[44:47]
	v_mfma_f32_16x16x32_bf16 v[24:27], v[132:135], v[202:205], v[24:27]
	v_mfma_f32_16x16x32_bf16 v[28:31], v[140:143], v[202:205], v[28:31]
	v_mfma_f32_16x16x32_bf16 v[8:11], v[132:135], v[210:213], v[8:11]
	v_mfma_f32_16x16x32_bf16 v[12:15], v[140:143], v[210:213], v[12:15]
	v_mfma_f32_16x16x32_bf16 v[48:51], v[144:147], v[176:179], v[48:51]
	v_mfma_f32_16x16x32_bf16 v[52:55], v[152:155], v[176:179], v[52:55]
	v_mfma_f32_16x16x32_bf16 v[32:35], v[144:147], v[184:187], v[32:35]
	v_mfma_f32_16x16x32_bf16 v[36:39], v[152:155], v[184:187], v[36:39]
	v_mfma_f32_16x16x32_bf16 v[16:19], v[144:147], v[198:201], v[16:19]
	v_mfma_f32_16x16x32_bf16 v[20:23], v[152:155], v[198:201], v[20:23]
	v_mfma_f32_16x16x32_bf16 v[4:7], v[144:147], v[206:209], v[4:7]
	v_mfma_f32_16x16x32_bf16 v[0:3], v[152:155], v[206:209], v[0:3]
	v_mfma_f32_16x16x32_bf16 v[48:51], v[148:151], v[180:183], v[48:51]
	v_mfma_f32_16x16x32_bf16 v[52:55], v[156:159], v[180:183], v[52:55]
	v_mfma_f32_16x16x32_bf16 v[32:35], v[148:151], v[188:191], v[32:35]
	v_mfma_f32_16x16x32_bf16 v[36:39], v[156:159], v[188:191], v[36:39]
	v_mfma_f32_16x16x32_bf16 v[16:19], v[148:151], v[202:205], v[16:19]
	v_mfma_f32_16x16x32_bf16 v[20:23], v[156:159], v[202:205], v[20:23]
	v_mfma_f32_16x16x32_bf16 v[4:7], v[148:151], v[210:213], v[4:7]
	v_mfma_f32_16x16x32_bf16 v[0:3], v[156:159], v[210:213], v[0:3]
	s_barrier
	s_add_i32 s50, s50, 2
	s_add_u32 s48, s48, 0x100
	s_addc_u32 s49, s49, 0
	s_cmp_gt_u32 s50, 41
	s_mov_b64 s[20:21], s[2:3]
	s_cbranch_scc0 .LBB0_1321
	s_setprio 0
	s_and_b64 vcc, exec, s[12:13]
	s_cbranch_vccz .LBB0_1324
	s_barrier
